# w8dpp + bf16 pack via v_cvt_pk in the streamers' in-projection epilogue copy
# baseline (speedup 1.0000x reference)
.LBB0_957:
	v_lshlrev_b32_e32 v130, 3, v143
	s_lshl_b32 s0, s94, 8
	v_lshl_or_b32 v131, s5, 5, v130
	s_lshr_b32 s9, s18, 1
	s_and_b32 s0, s0, 0x100
	v_lshl_add_u32 v130, s4, 8, v1
	v_or_b32_e32 v1, s0, v131
	s_mul_i32 s0, s9, 0x1100000
	s_add_u32 s0, s72, s0
	s_addc_u32 s1, s73, 0
	s_add_u32 s10, s0, 0x3000000
	s_addc_u32 s11, s1, 0
	s_cmp_lt_u32 s18, 2
	s_cselect_b64 s[2:3], -1, 0
	s_cmp_gt_u32 s18, 1
	s_cselect_b64 s[0:1], -1, 0
	s_cmp_lg_u32 s9, 6
	s_cselect_b64 s[6:7], -1, 0
	s_and_b64 s[6:7], s[0:1], s[6:7]
	s_and_b64 vcc, exec, s[6:7]
	s_cbranch_vccnz .LBB0_959
	v_mov_b32_e32 v131, 0x3e38aa3b
	v_cndmask_b32_e64 v132, 1.0, v131, s[2:3]
	v_lshlrev_b32_e32 v134, 1, v1
	v_mov_b32_e32 v135, 0
	v_ashrrev_i32_e32 v131, 31, v130
	v_pk_mul_f32 v[136:137], v[132:133], v[126:127] op_sel_hi:[0,1]
	v_lshl_add_u64 v[140:141], s[10:11], 0, v[134:135]
	v_lshlrev_b64 v[134:135], 10, v[130:131]
	s_movk_i32 s0, 0x7fff
	v_pk_mul_f32 v[138:139], v[132:133], v[128:129] op_sel_hi:[0,1]
	v_pk_mul_f32 v[144:145], v[132:133], v[124:125] op_sel_hi:[0,1]
	v_pk_mul_f32 v[146:147], v[132:133], v[122:123] op_sel_hi:[0,1]
	v_cvt_pk_bf16_f32 v133, v136, v137
	s_mov_b32 s1, 0xffff0000
	v_mov_b32_e32 v136, v133
	v_cvt_pk_bf16_f32 v137, v138, v139
	v_cvt_pk_bf16_f32 v138, v146, v147
	v_lshl_add_u64 v[134:135], v[140:141], 0, v[134:135]
	v_cvt_pk_bf16_f32 v139, v144, v145
	global_store_dwordx4 v[134:135], v[136:139], off
	v_pk_mul_f32 v[144:145], v[132:133], v[116:117] op_sel_hi:[0,1]
	v_pk_mul_f32 v[146:147], v[132:133], v[114:115] op_sel_hi:[0,1]
	v_pk_mul_f32 v[136:137], v[132:133], v[118:119] op_sel_hi:[0,1]
	v_pk_mul_f32 v[138:139], v[132:133], v[120:121] op_sel_hi:[0,1]
	v_cvt_pk_bf16_f32 v133, v136, v137
	v_mov_b32_e32 v136, v133
	v_cvt_pk_bf16_f32 v137, v138, v139
	v_cvt_pk_bf16_f32 v138, v146, v147
	v_cvt_pk_bf16_f32 v139, v144, v145
	global_store_dwordx4 v[134:135], v[136:139], off offset:256
	v_pk_mul_f32 v[146:147], v[132:133], v[108:109] op_sel_hi:[0,1]
	v_pk_mul_f32 v[148:149], v[132:133], v[106:107] op_sel_hi:[0,1]
	v_or_b32_e32 v136, 16, v130
	v_ashrrev_i32_e32 v137, 31, v136
	v_lshlrev_b64 v[136:137], 10, v[136:137]
	v_lshl_add_u64 v[144:145], v[140:141], 0, v[136:137]
	v_pk_mul_f32 v[136:137], v[132:133], v[110:111] op_sel_hi:[0,1]
	v_pk_mul_f32 v[138:139], v[132:133], v[112:113] op_sel_hi:[0,1]
	v_cvt_pk_bf16_f32 v133, v136, v137
	v_mov_b32_e32 v136, v133
	v_cvt_pk_bf16_f32 v137, v138, v139
	v_cvt_pk_bf16_f32 v138, v148, v149
	v_cvt_pk_bf16_f32 v139, v146, v147
	global_store_dwordx4 v[144:145], v[136:139], off
	v_pk_mul_f32 v[146:147], v[132:133], v[100:101] op_sel_hi:[0,1]
	v_pk_mul_f32 v[148:149], v[132:133], v[98:99] op_sel_hi:[0,1]
	v_pk_mul_f32 v[136:137], v[132:133], v[102:103] op_sel_hi:[0,1]
	v_pk_mul_f32 v[138:139], v[132:133], v[104:105] op_sel_hi:[0,1]
	v_cvt_pk_bf16_f32 v133, v136, v137
	v_mov_b32_e32 v136, v133
	v_cvt_pk_bf16_f32 v137, v138, v139
	v_cvt_pk_bf16_f32 v138, v148, v149
	v_cvt_pk_bf16_f32 v139, v146, v147
	global_store_dwordx4 v[144:145], v[136:139], off offset:256
	v_pk_mul_f32 v[146:147], v[132:133], v[92:93] op_sel_hi:[0,1]
	v_pk_mul_f32 v[148:149], v[132:133], v[90:91] op_sel_hi:[0,1]
	v_or_b32_e32 v136, 32, v130
	v_ashrrev_i32_e32 v137, 31, v136
	v_lshlrev_b64 v[136:137], 10, v[136:137]
	v_lshl_add_u64 v[144:145], v[140:141], 0, v[136:137]
	v_pk_mul_f32 v[136:137], v[132:133], v[94:95] op_sel_hi:[0,1]
	v_pk_mul_f32 v[138:139], v[132:133], v[96:97] op_sel_hi:[0,1]
	v_cvt_pk_bf16_f32 v133, v136, v137
	v_mov_b32_e32 v136, v133
	v_cvt_pk_bf16_f32 v137, v138, v139
	v_cvt_pk_bf16_f32 v138, v148, v149
	v_cvt_pk_bf16_f32 v139, v146, v147
	global_store_dwordx4 v[144:145], v[136:139], off
	v_pk_mul_f32 v[146:147], v[132:133], v[84:85] op_sel_hi:[0,1]
	v_pk_mul_f32 v[148:149], v[132:133], v[82:83] op_sel_hi:[0,1]
	v_pk_mul_f32 v[136:137], v[132:133], v[86:87] op_sel_hi:[0,1]
	v_pk_mul_f32 v[138:139], v[132:133], v[88:89] op_sel_hi:[0,1]
	v_cvt_pk_bf16_f32 v133, v136, v137
	v_mov_b32_e32 v136, v133
	v_cvt_pk_bf16_f32 v137, v138, v139
	v_cvt_pk_bf16_f32 v138, v148, v149
	v_cvt_pk_bf16_f32 v139, v146, v147
	global_store_dwordx4 v[144:145], v[136:139], off offset:256
	v_pk_mul_f32 v[144:145], v[132:133], v[76:77] op_sel_hi:[0,1]
	v_pk_mul_f32 v[146:147], v[132:133], v[74:75] op_sel_hi:[0,1]
	v_or_b32_e32 v136, 48, v130
	v_ashrrev_i32_e32 v137, 31, v136
	v_lshlrev_b64 v[136:137], 10, v[136:137]
	v_lshl_add_u64 v[140:141], v[140:141], 0, v[136:137]
	v_pk_mul_f32 v[136:137], v[132:133], v[78:79] op_sel_hi:[0,1]
	v_pk_mul_f32 v[138:139], v[132:133], v[80:81] op_sel_hi:[0,1]
	v_cvt_pk_bf16_f32 v133, v136, v137
	v_mov_b32_e32 v136, v133
	v_cvt_pk_bf16_f32 v137, v138, v139
	v_cvt_pk_bf16_f32 v138, v146, v147
	v_cvt_pk_bf16_f32 v139, v144, v145
	global_store_dwordx4 v[140:141], v[136:139], off
	v_pk_mul_f32 v[144:145], v[132:133], v[68:69] op_sel_hi:[0,1]
	v_pk_mul_f32 v[146:147], v[132:133], v[66:67] op_sel_hi:[0,1]
	v_pk_mul_f32 v[136:137], v[132:133], v[70:71] op_sel_hi:[0,1]
	v_pk_mul_f32 v[138:139], v[132:133], v[72:73] op_sel_hi:[0,1]
	v_cvt_pk_bf16_f32 v133, v136, v137
	v_mov_b32_e32 v136, v133
	v_cvt_pk_bf16_f32 v137, v138, v139
	v_cvt_pk_bf16_f32 v138, v146, v147
	v_cvt_pk_bf16_f32 v139, v144, v145
	global_store_dwordx4 v[140:141], v[136:139], off offset:256
	v_pk_mul_f32 v[144:145], v[132:133], v[60:61] op_sel_hi:[0,1]
	v_pk_mul_f32 v[146:147], v[132:133], v[58:59] op_sel_hi:[0,1]
	v_pk_mul_f32 v[136:137], v[132:133], v[62:63] op_sel_hi:[0,1]
	v_pk_mul_f32 v[138:139], v[132:133], v[64:65] op_sel_hi:[0,1]
	v_cvt_pk_bf16_f32 v133, v136, v137
	v_mov_b32_e32 v136, v133
	v_cvt_pk_bf16_f32 v137, v138, v139
	s_mov_b64 s[12:13], 0x20000
	v_cvt_pk_bf16_f32 v138, v146, v147
	v_bfe_u32 v131, v144, 16, 1
	v_lshl_add_u64 v[140:141], v[134:135], 0, s[12:13]
	v_add3_u32 v131, v144, v131, s0
	v_bfe_u32 v133, v145, 16, 1
	s_mov_b32 s12, 0x20000
	v_lshrrev_b32_e32 v131, 16, v131
	v_add3_u32 v133, v145, v133, s0
	v_add_co_u32_e32 v144, vcc, s12, v134
	v_and_or_b32 v139, v133, s1, v131
	s_nop 0
	v_addc_co_u32_e32 v145, vcc, 0, v135, vcc
	global_store_dwordx4 v[144:145], v[136:139], off
	v_pk_mul_f32 v[144:145], v[132:133], v[52:53] op_sel_hi:[0,1]
	v_pk_mul_f32 v[146:147], v[132:133], v[50:51] op_sel_hi:[0,1]
	v_pk_mul_f32 v[136:137], v[132:133], v[54:55] op_sel_hi:[0,1]
	v_pk_mul_f32 v[138:139], v[132:133], v[56:57] op_sel_hi:[0,1]
	v_cvt_pk_bf16_f32 v133, v136, v137
	v_mov_b32_e32 v136, v133
	v_cvt_pk_bf16_f32 v137, v138, v139
	v_cvt_pk_bf16_f32 v138, v146, v147
	v_cvt_pk_bf16_f32 v139, v144, v145
	global_store_dwordx4 v[140:141], v[136:139], off offset:256
	v_pk_mul_f32 v[144:145], v[132:133], v[44:45] op_sel_hi:[0,1]
	v_pk_mul_f32 v[146:147], v[132:133], v[42:43] op_sel_hi:[0,1]
	v_pk_mul_f32 v[136:137], v[132:133], v[46:47] op_sel_hi:[0,1]
	v_pk_mul_f32 v[138:139], v[132:133], v[48:49] op_sel_hi:[0,1]
	v_cvt_pk_bf16_f32 v133, v136, v137
	v_mov_b32_e32 v136, v133
	v_cvt_pk_bf16_f32 v137, v138, v139
	s_mov_b64 s[12:13], 0x24000
	v_cvt_pk_bf16_f32 v138, v146, v147
	v_bfe_u32 v131, v144, 16, 1
	v_lshl_add_u64 v[140:141], v[134:135], 0, s[12:13]
	v_add3_u32 v131, v144, v131, s0
	v_bfe_u32 v133, v145, 16, 1
	s_mov_b32 s12, 0x24000
	v_lshrrev_b32_e32 v131, 16, v131
	v_add3_u32 v133, v145, v133, s0
	v_add_co_u32_e32 v144, vcc, s12, v134
	v_and_or_b32 v139, v133, s1, v131
	s_nop 0
	v_addc_co_u32_e32 v145, vcc, 0, v135, vcc
	global_store_dwordx4 v[144:145], v[136:139], off
	v_pk_mul_f32 v[144:145], v[132:133], v[36:37] op_sel_hi:[0,1]
	v_pk_mul_f32 v[146:147], v[132:133], v[34:35] op_sel_hi:[0,1]
	v_pk_mul_f32 v[136:137], v[132:133], v[38:39] op_sel_hi:[0,1]
	v_pk_mul_f32 v[138:139], v[132:133], v[40:41] op_sel_hi:[0,1]
	v_cvt_pk_bf16_f32 v133, v136, v137
	v_mov_b32_e32 v136, v133
	v_cvt_pk_bf16_f32 v137, v138, v139
	v_cvt_pk_bf16_f32 v138, v146, v147
	v_cvt_pk_bf16_f32 v139, v144, v145
	global_store_dwordx4 v[140:141], v[136:139], off offset:256
	v_pk_mul_f32 v[144:145], v[132:133], v[28:29] op_sel_hi:[0,1]
	v_pk_mul_f32 v[146:147], v[132:133], v[26:27] op_sel_hi:[0,1]
	v_pk_mul_f32 v[136:137], v[132:133], v[30:31] op_sel_hi:[0,1]
	v_pk_mul_f32 v[138:139], v[132:133], v[32:33] op_sel_hi:[0,1]
	v_cvt_pk_bf16_f32 v133, v136, v137
	v_mov_b32_e32 v136, v133
	v_cvt_pk_bf16_f32 v137, v138, v139
	s_mov_b64 s[12:13], 0x28000
	v_cvt_pk_bf16_f32 v138, v146, v147
	v_bfe_u32 v131, v144, 16, 1
	v_lshl_add_u64 v[140:141], v[134:135], 0, s[12:13]
	v_add3_u32 v131, v144, v131, s0
	v_bfe_u32 v133, v145, 16, 1
	s_mov_b32 s12, 0x28000
	v_lshrrev_b32_e32 v131, 16, v131
	v_add3_u32 v133, v145, v133, s0
	v_add_co_u32_e32 v144, vcc, s12, v134
	v_and_or_b32 v139, v133, s1, v131
	s_nop 0
	v_addc_co_u32_e32 v145, vcc, 0, v135, vcc
	global_store_dwordx4 v[144:145], v[136:139], off
	v_pk_mul_f32 v[144:145], v[132:133], v[20:21] op_sel_hi:[0,1]
	v_pk_mul_f32 v[146:147], v[132:133], v[18:19] op_sel_hi:[0,1]
	v_pk_mul_f32 v[136:137], v[132:133], v[22:23] op_sel_hi:[0,1]
	v_pk_mul_f32 v[138:139], v[132:133], v[24:25] op_sel_hi:[0,1]
	v_cvt_pk_bf16_f32 v133, v136, v137
	v_mov_b32_e32 v136, v133
	v_cvt_pk_bf16_f32 v137, v138, v139
	v_cvt_pk_bf16_f32 v138, v146, v147
	v_cvt_pk_bf16_f32 v139, v144, v145
	global_store_dwordx4 v[140:141], v[136:139], off offset:256
	v_pk_mul_f32 v[144:145], v[132:133], v[12:13] op_sel_hi:[0,1]
	v_pk_mul_f32 v[146:147], v[132:133], v[10:11] op_sel_hi:[0,1]
	v_pk_mul_f32 v[136:137], v[132:133], v[14:15] op_sel_hi:[0,1]
	v_pk_mul_f32 v[138:139], v[132:133], v[16:17] op_sel_hi:[0,1]
	v_cvt_pk_bf16_f32 v133, v136, v137
	v_mov_b32_e32 v136, v133
	v_cvt_pk_bf16_f32 v137, v138, v139
	s_mov_b64 s[12:13], 0x2c000
	v_cvt_pk_bf16_f32 v138, v146, v147
	v_lshl_add_u64 v[140:141], v[134:135], 0, s[12:13]
	s_mov_b32 s12, 0x2c000
	v_add_co_u32_e32 v134, vcc, s12, v134
	v_cvt_pk_bf16_f32 v139, v144, v145
	s_nop 0
	v_addc_co_u32_e32 v135, vcc, 0, v135, vcc
	global_store_dwordx4 v[134:135], v[136:139], off
	v_pk_mul_f32 v[134:135], v[132:133], v[8:9] op_sel_hi:[0,1]
	v_pk_mul_f32 v[144:145], v[132:133], v[2:3] op_sel_hi:[0,1]
	v_pk_mul_f32 v[136:137], v[132:133], v[6:7] op_sel_hi:[0,1]
	v_pk_mul_f32 v[138:139], v[132:133], v[4:5] op_sel_hi:[0,1]
	v_cvt_pk_bf16_f32 v132, v136, v137
	v_cvt_pk_bf16_f32 v133, v134, v135
	v_cvt_pk_bf16_f32 v134, v144, v145
	v_cvt_pk_bf16_f32 v135, v138, v139
	global_store_dwordx4 v[140:141], v[132:135], off offset:256

.LBB0_989:
	s_andn2_b64 vcc, exec, s[6:7]
	s_cbranch_vccnz .LBB0_1062
	s_add_i32 s0, s9, -1
	s_cmp_gt_u32 s0, 1
	s_mov_b64 s[0:1], -1
	s_cbranch_scc0 .LBB0_996
	s_cmp_eq_u32 s9, 5
	s_waitcnt lgkmcnt(0)
	v_mov_b32_e32 v133, 0
	s_cbranch_scc1 .LBB0_993
	v_lshlrev_b32_e32 v132, 1, v1
	v_lshl_add_u64 v[134:135], s[10:11], 0, v[132:133]
	v_mul_f32_e32 v132, 0xbfb8aa3b, v126
	v_exp_f32_e32 v136, v132
	v_mul_f32_e32 v132, 0xbfb8aa3b, v128
	v_exp_f32_e32 v137, v132
	v_ashrrev_i32_e32 v131, 31, v130
	v_lshlrev_b64 v[132:133], 10, v[130:131]
	v_mul_f32_e32 v131, 0xbfb8aa3b, v127
	v_pk_add_f32 v[136:137], v[136:137], 1.0 op_sel_hi:[1,0]
	v_exp_f32_e32 v138, v131
	v_rcp_f32_e32 v141, v137
	v_mul_f32_e32 v131, 0xbfb8aa3b, v129
	v_exp_f32_e32 v139, v131
	v_lshl_add_u64 v[132:133], v[134:135], 0, v[132:133]
	v_rcp_f32_e32 v143, v136
	v_mul_f32_e32 v131, v128, v141
	v_pk_add_f32 v[138:139], v[138:139], 1.0 op_sel_hi:[1,0]
	v_rcp_f32_e32 v142, v138
	v_mul_f32_e32 v141, v126, v143
	v_rcp_f32_e32 v143, v139
	v_mul_f32_e32 v142, v127, v142
	v_mul_f32_e32 v136, 0xbfb8aa3b, v122
	v_mul_f32_e32 v137, 0xbfb8aa3b, v124
	v_exp_f32_e32 v136, v136
	v_exp_f32_e32 v137, v137
	v_mul_f32_e32 v140, v129, v143
	v_mul_f32_e32 v138, 0xbfb8aa3b, v123
	v_pk_add_f32 v[136:137], v[136:137], 1.0 op_sel_hi:[1,0]
	v_mul_f32_e32 v139, 0xbfb8aa3b, v125
	v_rcp_f32_e32 v144, v137
	v_exp_f32_e32 v138, v138
	v_exp_f32_e32 v139, v139
	v_rcp_f32_e32 v147, v136
	v_mul_f32_e32 v137, v124, v144
	v_pk_add_f32 v[138:139], v[138:139], 1.0 op_sel_hi:[1,0]
	v_rcp_f32_e32 v146, v138
	v_mul_f32_e32 v136, v122, v147
	v_rcp_f32_e32 v147, v139
	v_mul_f32_e32 v138, v123, v146
	s_movk_i32 s0, 0x7fff
	v_bfe_u32 v146, v142, 16, 1
	v_mul_f32_e32 v139, v125, v147
	v_add3_u32 v142, v142, v146, s0
	v_cvt_pk_bf16_f32 v138, v136, v138
	v_cvt_pk_bf16_f32 v139, v137, v139
	v_cvt_pk_bf16_f32 v140, v131, v140
	s_mov_b32 s1, 0xffff0000
	v_bfe_u32 v143, v141, 16, 1
	v_mov_b32_e32 v137, v140
	v_mul_f32_e32 v131, 0xbfb8aa3b, v118
	v_add3_u32 v141, v141, v143, s0
	v_exp_f32_e32 v140, v131
	v_mul_f32_e32 v131, 0xbfb8aa3b, v120
	v_lshrrev_b32_e32 v143, 16, v141
	v_exp_f32_e32 v141, v131
	v_and_or_b32 v136, v142, s1, v143
	global_store_dwordx4 v[132:133], v[136:139], off
	v_mul_f32_e32 v131, 0xbfb8aa3b, v119
	s_nop 0
	v_pk_add_f32 v[136:137], v[140:141], 1.0 op_sel_hi:[1,0]
	v_exp_f32_e32 v138, v131
	v_rcp_f32_e32 v141, v137
	v_mul_f32_e32 v131, 0xbfb8aa3b, v121
	v_exp_f32_e32 v139, v131
	v_rcp_f32_e32 v143, v136
	v_mul_f32_e32 v131, v120, v141
	v_pk_add_f32 v[138:139], v[138:139], 1.0 op_sel_hi:[1,0]
	v_rcp_f32_e32 v142, v138
	v_mul_f32_e32 v141, v118, v143
	v_rcp_f32_e32 v143, v139
	v_mul_f32_e32 v142, v119, v142
	v_mul_f32_e32 v136, 0xbfb8aa3b, v114
	v_mul_f32_e32 v137, 0xbfb8aa3b, v116
	v_exp_f32_e32 v136, v136
	v_exp_f32_e32 v137, v137
	v_mul_f32_e32 v140, v121, v143
	v_mul_f32_e32 v138, 0xbfb8aa3b, v115
	v_pk_add_f32 v[136:137], v[136:137], 1.0 op_sel_hi:[1,0]
	v_mul_f32_e32 v139, 0xbfb8aa3b, v117
	v_rcp_f32_e32 v144, v137
	v_exp_f32_e32 v138, v138
	v_exp_f32_e32 v139, v139
	v_rcp_f32_e32 v147, v136
	v_mul_f32_e32 v137, v116, v144
	v_pk_add_f32 v[138:139], v[138:139], 1.0 op_sel_hi:[1,0]
	v_rcp_f32_e32 v146, v138
	v_mul_f32_e32 v136, v114, v147
	v_rcp_f32_e32 v147, v139
	v_mul_f32_e32 v138, v115, v146
	v_mul_f32_e32 v139, v117, v147
	v_cvt_pk_bf16_f32 v142, v141, v142
	v_cvt_pk_bf16_f32 v140, v131, v140
	v_cvt_pk_bf16_f32 v138, v136, v138
	v_cvt_pk_bf16_f32 v139, v137, v139
	v_mov_b32_e32 v137, v140
	v_mov_b32_e32 v136, v142
	v_mul_f32_e32 v131, 0xbfb8aa3b, v110
	global_store_dwordx4 v[132:133], v[136:139], off offset:256
	s_nop 1
	v_exp_f32_e32 v138, v131
	v_mul_f32_e32 v131, 0xbfb8aa3b, v112
	v_exp_f32_e32 v139, v131
	v_mul_f32_e32 v131, 0xbfb8aa3b, v111
	v_exp_f32_e32 v140, v131
	v_mul_f32_e32 v131, 0xbfb8aa3b, v113
	v_pk_add_f32 v[138:139], v[138:139], 1.0 op_sel_hi:[1,0]
	v_exp_f32_e32 v141, v131
	v_rcp_f32_e32 v143, v139
	v_pk_add_f32 v[140:141], v[140:141], 1.0 op_sel_hi:[1,0]
	v_or_b32_e32 v136, 16, v130
	v_ashrrev_i32_e32 v137, 31, v136
	v_rcp_f32_e32 v145, v138
	v_mul_f32_e32 v131, v112, v143
	v_lshlrev_b64 v[136:137], 10, v[136:137]
	v_rcp_f32_e32 v144, v140
	v_mul_f32_e32 v143, v110, v145
	v_lshl_add_u64 v[136:137], v[134:135], 0, v[136:137]
	v_rcp_f32_e32 v145, v141
	v_mul_f32_e32 v144, v111, v144
	v_mul_f32_e32 v138, 0xbfb8aa3b, v106
	v_mul_f32_e32 v139, 0xbfb8aa3b, v108
	v_exp_f32_e32 v138, v138
	v_exp_f32_e32 v139, v139
	v_mul_f32_e32 v142, v113, v145
	v_mul_f32_e32 v140, 0xbfb8aa3b, v107
	v_pk_add_f32 v[138:139], v[138:139], 1.0 op_sel_hi:[1,0]
	v_mul_f32_e32 v141, 0xbfb8aa3b, v109
	v_rcp_f32_e32 v146, v139
	v_exp_f32_e32 v140, v140
	v_exp_f32_e32 v141, v141
	v_rcp_f32_e32 v149, v138
	v_mul_f32_e32 v139, v108, v146
	v_pk_add_f32 v[140:141], v[140:141], 1.0 op_sel_hi:[1,0]
	v_rcp_f32_e32 v148, v140
	v_mul_f32_e32 v138, v106, v149
	v_rcp_f32_e32 v149, v141
	v_mul_f32_e32 v140, v107, v148
	v_bfe_u32 v148, v144, 16, 1
	v_mul_f32_e32 v141, v109, v149
	v_add3_u32 v144, v144, v148, s0
	v_cvt_pk_bf16_f32 v140, v138, v140
	v_cvt_pk_bf16_f32 v141, v139, v141
	v_cvt_pk_bf16_f32 v142, v131, v142
	v_bfe_u32 v145, v143, 16, 1
	v_mov_b32_e32 v139, v142
	v_mul_f32_e32 v131, 0xbfb8aa3b, v102
	v_add3_u32 v143, v143, v145, s0
	v_exp_f32_e32 v142, v131
	v_mul_f32_e32 v131, 0xbfb8aa3b, v104
	v_lshrrev_b32_e32 v145, 16, v143
	v_exp_f32_e32 v143, v131
	v_and_or_b32 v138, v144, s1, v145
	global_store_dwordx4 v[136:137], v[138:141], off
	v_mul_f32_e32 v131, 0xbfb8aa3b, v103
	s_nop 0
	v_pk_add_f32 v[138:139], v[142:143], 1.0 op_sel_hi:[1,0]
	v_exp_f32_e32 v140, v131
	v_rcp_f32_e32 v143, v139
	v_mul_f32_e32 v131, 0xbfb8aa3b, v105
	v_exp_f32_e32 v141, v131
	v_rcp_f32_e32 v145, v138
	v_mul_f32_e32 v131, v104, v143
	v_pk_add_f32 v[140:141], v[140:141], 1.0 op_sel_hi:[1,0]
	v_rcp_f32_e32 v144, v140
	v_mul_f32_e32 v143, v102, v145
	v_rcp_f32_e32 v145, v141
	v_mul_f32_e32 v144, v103, v144
	v_mul_f32_e32 v138, 0xbfb8aa3b, v98
	v_mul_f32_e32 v139, 0xbfb8aa3b, v100
	v_exp_f32_e32 v138, v138
	v_exp_f32_e32 v139, v139
	v_mul_f32_e32 v142, v105, v145
	v_mul_f32_e32 v140, 0xbfb8aa3b, v99
	v_pk_add_f32 v[138:139], v[138:139], 1.0 op_sel_hi:[1,0]
	v_mul_f32_e32 v141, 0xbfb8aa3b, v101
	v_rcp_f32_e32 v146, v139
	v_exp_f32_e32 v140, v140
	v_exp_f32_e32 v141, v141
	v_rcp_f32_e32 v149, v138
	v_mul_f32_e32 v139, v100, v146
	v_pk_add_f32 v[140:141], v[140:141], 1.0 op_sel_hi:[1,0]
	v_rcp_f32_e32 v148, v140
	v_mul_f32_e32 v138, v98, v149
	v_rcp_f32_e32 v149, v141
	v_mul_f32_e32 v140, v99, v148
	v_mul_f32_e32 v141, v101, v149
	v_cvt_pk_bf16_f32 v144, v143, v144
	v_cvt_pk_bf16_f32 v142, v131, v142
	v_cvt_pk_bf16_f32 v140, v138, v140
	v_cvt_pk_bf16_f32 v141, v139, v141
	v_mov_b32_e32 v139, v142
	v_mov_b32_e32 v138, v144
	v_mul_f32_e32 v131, 0xbfb8aa3b, v94
	global_store_dwordx4 v[136:137], v[138:141], off offset:256
	v_or_b32_e32 v136, 32, v130
	v_ashrrev_i32_e32 v137, 31, v136
	v_exp_f32_e32 v138, v131
	v_mul_f32_e32 v131, 0xbfb8aa3b, v96
	v_exp_f32_e32 v139, v131
	v_mul_f32_e32 v131, 0xbfb8aa3b, v95
	v_exp_f32_e32 v140, v131
	v_mul_f32_e32 v131, 0xbfb8aa3b, v97
	v_pk_add_f32 v[138:139], v[138:139], 1.0 op_sel_hi:[1,0]
	v_exp_f32_e32 v141, v131
	v_rcp_f32_e32 v143, v139
	v_pk_add_f32 v[140:141], v[140:141], 1.0 op_sel_hi:[1,0]
	v_lshlrev_b64 v[136:137], 10, v[136:137]
	v_lshl_add_u64 v[136:137], v[134:135], 0, v[136:137]
	v_rcp_f32_e32 v145, v138
	v_mul_f32_e32 v131, v96, v143
	v_rcp_f32_e32 v144, v140
	v_mul_f32_e32 v143, v94, v145
	v_rcp_f32_e32 v145, v141
	v_mul_f32_e32 v144, v95, v144
	v_mul_f32_e32 v138, 0xbfb8aa3b, v90
	v_mul_f32_e32 v139, 0xbfb8aa3b, v92
	v_exp_f32_e32 v138, v138
	v_exp_f32_e32 v139, v139
	v_mul_f32_e32 v142, v97, v145
	v_mul_f32_e32 v140, 0xbfb8aa3b, v91
	v_pk_add_f32 v[138:139], v[138:139], 1.0 op_sel_hi:[1,0]
	v_mul_f32_e32 v141, 0xbfb8aa3b, v93
	v_rcp_f32_e32 v146, v139
	v_exp_f32_e32 v140, v140
	v_exp_f32_e32 v141, v141
	v_rcp_f32_e32 v149, v138
	v_mul_f32_e32 v139, v92, v146
	v_pk_add_f32 v[140:141], v[140:141], 1.0 op_sel_hi:[1,0]
	v_rcp_f32_e32 v148, v140
	v_mul_f32_e32 v138, v90, v149
	v_rcp_f32_e32 v149, v141
	v_mul_f32_e32 v140, v91, v148
	v_bfe_u32 v148, v144, 16, 1
	v_mul_f32_e32 v141, v93, v149
	v_add3_u32 v144, v144, v148, s0
	v_cvt_pk_bf16_f32 v140, v138, v140
	v_cvt_pk_bf16_f32 v141, v139, v141
	v_cvt_pk_bf16_f32 v142, v131, v142
	v_bfe_u32 v145, v143, 16, 1
	v_mov_b32_e32 v139, v142
	v_mul_f32_e32 v131, 0xbfb8aa3b, v86
	v_add3_u32 v143, v143, v145, s0
	v_exp_f32_e32 v142, v131
	v_mul_f32_e32 v131, 0xbfb8aa3b, v88
	v_lshrrev_b32_e32 v145, 16, v143
	v_exp_f32_e32 v143, v131
	v_and_or_b32 v138, v144, s1, v145
	global_store_dwordx4 v[136:137], v[138:141], off
	v_mul_f32_e32 v131, 0xbfb8aa3b, v87
	s_nop 0
	v_pk_add_f32 v[138:139], v[142:143], 1.0 op_sel_hi:[1,0]
	v_exp_f32_e32 v140, v131
	v_rcp_f32_e32 v143, v139
	v_mul_f32_e32 v131, 0xbfb8aa3b, v89
	v_exp_f32_e32 v141, v131
	v_rcp_f32_e32 v145, v138
	v_mul_f32_e32 v131, v88, v143
	v_pk_add_f32 v[140:141], v[140:141], 1.0 op_sel_hi:[1,0]
	v_rcp_f32_e32 v144, v140
	v_mul_f32_e32 v143, v86, v145
	v_rcp_f32_e32 v145, v141
	v_mul_f32_e32 v144, v87, v144
	v_mul_f32_e32 v138, 0xbfb8aa3b, v82
	v_mul_f32_e32 v139, 0xbfb8aa3b, v84
	v_exp_f32_e32 v138, v138
	v_exp_f32_e32 v139, v139
	v_mul_f32_e32 v142, v89, v145
	v_mul_f32_e32 v140, 0xbfb8aa3b, v83
	v_pk_add_f32 v[138:139], v[138:139], 1.0 op_sel_hi:[1,0]
	v_mul_f32_e32 v141, 0xbfb8aa3b, v85
	v_rcp_f32_e32 v146, v139
	v_exp_f32_e32 v140, v140
	v_exp_f32_e32 v141, v141
	v_rcp_f32_e32 v149, v138
	v_mul_f32_e32 v139, v84, v146
	v_pk_add_f32 v[140:141], v[140:141], 1.0 op_sel_hi:[1,0]
	v_rcp_f32_e32 v148, v140
	v_mul_f32_e32 v138, v82, v149
	v_rcp_f32_e32 v149, v141
	v_mul_f32_e32 v140, v83, v148
	v_mul_f32_e32 v141, v85, v149
	v_cvt_pk_bf16_f32 v144, v143, v144
	v_cvt_pk_bf16_f32 v142, v131, v142
	v_cvt_pk_bf16_f32 v140, v138, v140
	v_cvt_pk_bf16_f32 v141, v139, v141
	v_mov_b32_e32 v139, v142
	v_mov_b32_e32 v138, v144
	v_mul_f32_e32 v131, 0xbfb8aa3b, v78
	global_store_dwordx4 v[136:137], v[138:141], off offset:256
	v_or_b32_e32 v136, 48, v130
	v_ashrrev_i32_e32 v137, 31, v136
	v_exp_f32_e32 v138, v131
	v_mul_f32_e32 v131, 0xbfb8aa3b, v80
	v_exp_f32_e32 v139, v131
	v_lshlrev_b64 v[136:137], 10, v[136:137]
	v_lshl_add_u64 v[134:135], v[134:135], 0, v[136:137]
	v_mul_f32_e32 v131, 0xbfb8aa3b, v79
	v_pk_add_f32 v[136:137], v[138:139], 1.0 op_sel_hi:[1,0]
	v_exp_f32_e32 v138, v131
	v_rcp_f32_e32 v141, v137
	v_mul_f32_e32 v131, 0xbfb8aa3b, v81
	v_exp_f32_e32 v139, v131
	v_rcp_f32_e32 v143, v136
	v_mul_f32_e32 v131, v80, v141
	v_pk_add_f32 v[138:139], v[138:139], 1.0 op_sel_hi:[1,0]
	v_rcp_f32_e32 v142, v138
	v_mul_f32_e32 v141, v78, v143
	v_rcp_f32_e32 v143, v139
	v_mul_f32_e32 v142, v79, v142
	v_mul_f32_e32 v136, 0xbfb8aa3b, v74
	v_mul_f32_e32 v137, 0xbfb8aa3b, v76
	v_exp_f32_e32 v136, v136
	v_exp_f32_e32 v137, v137
	v_mul_f32_e32 v140, v81, v143
	v_mul_f32_e32 v138, 0xbfb8aa3b, v75
	v_pk_add_f32 v[136:137], v[136:137], 1.0 op_sel_hi:[1,0]
	v_mul_f32_e32 v139, 0xbfb8aa3b, v77
	v_rcp_f32_e32 v144, v137
	v_exp_f32_e32 v138, v138
	v_exp_f32_e32 v139, v139
	v_rcp_f32_e32 v147, v136
	v_mul_f32_e32 v137, v76, v144
	v_pk_add_f32 v[138:139], v[138:139], 1.0 op_sel_hi:[1,0]
	v_rcp_f32_e32 v146, v138
	v_mul_f32_e32 v136, v74, v147
	v_rcp_f32_e32 v147, v139
	v_mul_f32_e32 v138, v75, v146
	v_bfe_u32 v146, v142, 16, 1
	v_mul_f32_e32 v139, v77, v147
	v_add3_u32 v142, v142, v146, s0
	v_cvt_pk_bf16_f32 v138, v136, v138
	v_cvt_pk_bf16_f32 v139, v137, v139
	v_cvt_pk_bf16_f32 v140, v131, v140
	v_bfe_u32 v143, v141, 16, 1
	v_mov_b32_e32 v137, v140
	v_mul_f32_e32 v131, 0xbfb8aa3b, v70
	v_add3_u32 v141, v141, v143, s0
	v_exp_f32_e32 v140, v131
	v_mul_f32_e32 v131, 0xbfb8aa3b, v72
	v_lshrrev_b32_e32 v143, 16, v141
	v_exp_f32_e32 v141, v131
	v_and_or_b32 v136, v142, s1, v143
	global_store_dwordx4 v[134:135], v[136:139], off
	v_mul_f32_e32 v131, 0xbfb8aa3b, v71
	s_nop 0
	v_pk_add_f32 v[136:137], v[140:141], 1.0 op_sel_hi:[1,0]
	v_exp_f32_e32 v138, v131
	v_rcp_f32_e32 v141, v137
	v_mul_f32_e32 v131, 0xbfb8aa3b, v73
	v_exp_f32_e32 v139, v131
	v_rcp_f32_e32 v143, v136
	v_mul_f32_e32 v131, v72, v141
	v_pk_add_f32 v[138:139], v[138:139], 1.0 op_sel_hi:[1,0]
	v_rcp_f32_e32 v142, v138
	v_mul_f32_e32 v141, v70, v143
	v_rcp_f32_e32 v143, v139
	v_mul_f32_e32 v142, v71, v142
	v_mul_f32_e32 v136, 0xbfb8aa3b, v66
	v_mul_f32_e32 v137, 0xbfb8aa3b, v68
	v_exp_f32_e32 v136, v136
	v_exp_f32_e32 v137, v137
	v_mul_f32_e32 v140, v73, v143
	v_mul_f32_e32 v138, 0xbfb8aa3b, v67
	v_pk_add_f32 v[136:137], v[136:137], 1.0 op_sel_hi:[1,0]
	v_mul_f32_e32 v139, 0xbfb8aa3b, v69
	v_rcp_f32_e32 v144, v137
	v_exp_f32_e32 v138, v138
	v_exp_f32_e32 v139, v139
	v_rcp_f32_e32 v147, v136
	v_mul_f32_e32 v137, v68, v144
	v_pk_add_f32 v[138:139], v[138:139], 1.0 op_sel_hi:[1,0]
	v_rcp_f32_e32 v146, v138
	v_mul_f32_e32 v136, v66, v147
	v_rcp_f32_e32 v147, v139
	v_mul_f32_e32 v138, v67, v146
	s_mov_b64 s[2:3], 0x20000
	v_mul_f32_e32 v139, v69, v147
	v_cvt_pk_bf16_f32 v142, v141, v142
	v_cvt_pk_bf16_f32 v140, v131, v140
	v_cvt_pk_bf16_f32 v138, v136, v138
	v_cvt_pk_bf16_f32 v139, v137, v139
	v_mov_b32_e32 v137, v140
	v_mov_b32_e32 v136, v142
	v_mul_f32_e32 v131, 0xbfb8aa3b, v62
	global_store_dwordx4 v[134:135], v[136:139], off offset:256
	v_lshl_add_u64 v[134:135], v[132:133], 0, s[2:3]
	s_nop 0
	v_exp_f32_e32 v136, v131
	v_mul_f32_e32 v131, 0xbfb8aa3b, v64
	v_exp_f32_e32 v137, v131
	v_mul_f32_e32 v131, 0xbfb8aa3b, v63
	v_exp_f32_e32 v138, v131
	v_mul_f32_e32 v131, 0xbfb8aa3b, v65
	v_pk_add_f32 v[136:137], v[136:137], 1.0 op_sel_hi:[1,0]
	v_exp_f32_e32 v139, v131
	v_rcp_f32_e32 v141, v137
	v_pk_add_f32 v[138:139], v[138:139], 1.0 op_sel_hi:[1,0]
	v_rcp_f32_e32 v143, v136
	v_mul_f32_e32 v131, v64, v141
	v_rcp_f32_e32 v142, v138
	v_mul_f32_e32 v141, v62, v143
	v_rcp_f32_e32 v143, v139
	v_mul_f32_e32 v142, v63, v142
	v_mul_f32_e32 v136, 0xbfb8aa3b, v58
	v_mul_f32_e32 v137, 0xbfb8aa3b, v60
	v_exp_f32_e32 v136, v136
	v_exp_f32_e32 v137, v137
	v_mul_f32_e32 v140, v65, v143
	v_mul_f32_e32 v138, 0xbfb8aa3b, v59
	v_pk_add_f32 v[136:137], v[136:137], 1.0 op_sel_hi:[1,0]
	v_mul_f32_e32 v139, 0xbfb8aa3b, v61
	v_rcp_f32_e32 v144, v137
	v_exp_f32_e32 v138, v138
	v_exp_f32_e32 v139, v139
	v_rcp_f32_e32 v147, v136
	v_mul_f32_e32 v137, v60, v144
	v_pk_add_f32 v[138:139], v[138:139], 1.0 op_sel_hi:[1,0]
	v_rcp_f32_e32 v146, v138
	v_mul_f32_e32 v136, v58, v147
	v_rcp_f32_e32 v147, v139
	v_mul_f32_e32 v138, v59, v146
	s_mov_b32 s2, 0x20000
	v_mul_f32_e32 v139, v61, v147
	v_cvt_pk_bf16_f32 v142, v141, v142
	v_cvt_pk_bf16_f32 v138, v136, v138
	v_cvt_pk_bf16_f32 v139, v137, v139
	v_cvt_pk_bf16_f32 v140, v131, v140
	v_mov_b32_e32 v137, v140
	v_mul_f32_e32 v131, 0xbfb8aa3b, v54
	v_exp_f32_e32 v140, v131
	v_mul_f32_e32 v131, 0xbfb8aa3b, v56
	v_mov_b32_e32 v136, v142
	v_exp_f32_e32 v141, v131
	v_add_co_u32_e32 v142, vcc, s2, v132
	v_mul_f32_e32 v131, 0xbfb8aa3b, v55
	s_nop 0
	v_addc_co_u32_e32 v143, vcc, 0, v133, vcc
	global_store_dwordx4 v[142:143], v[136:139], off
	s_nop 1
	v_pk_add_f32 v[136:137], v[140:141], 1.0 op_sel_hi:[1,0]
	v_exp_f32_e32 v138, v131
	v_rcp_f32_e32 v141, v137
	v_mul_f32_e32 v131, 0xbfb8aa3b, v57
	v_exp_f32_e32 v139, v131
	v_rcp_f32_e32 v143, v136
	v_mul_f32_e32 v131, v56, v141
	v_pk_add_f32 v[138:139], v[138:139], 1.0 op_sel_hi:[1,0]
	v_rcp_f32_e32 v142, v138
	v_mul_f32_e32 v141, v54, v143
	v_rcp_f32_e32 v143, v139
	v_mul_f32_e32 v142, v55, v142
	v_mul_f32_e32 v136, 0xbfb8aa3b, v50
	v_mul_f32_e32 v137, 0xbfb8aa3b, v52
	v_exp_f32_e32 v136, v136
	v_exp_f32_e32 v137, v137
	v_mul_f32_e32 v140, v57, v143
	v_mul_f32_e32 v138, 0xbfb8aa3b, v51
	v_pk_add_f32 v[136:137], v[136:137], 1.0 op_sel_hi:[1,0]
	v_mul_f32_e32 v139, 0xbfb8aa3b, v53
	v_rcp_f32_e32 v144, v137
	v_exp_f32_e32 v138, v138
	v_exp_f32_e32 v139, v139
	v_rcp_f32_e32 v147, v136
	v_mul_f32_e32 v137, v52, v144
	v_pk_add_f32 v[138:139], v[138:139], 1.0 op_sel_hi:[1,0]
	v_rcp_f32_e32 v146, v138
	v_mul_f32_e32 v136, v50, v147
	v_rcp_f32_e32 v147, v139
	v_mul_f32_e32 v138, v51, v146
	s_mov_b64 s[2:3], 0x24000
	v_mul_f32_e32 v139, v53, v147
	v_cvt_pk_bf16_f32 v142, v141, v142
	v_cvt_pk_bf16_f32 v140, v131, v140
	v_cvt_pk_bf16_f32 v138, v136, v138
	v_cvt_pk_bf16_f32 v139, v137, v139
	v_mov_b32_e32 v137, v140
	v_mov_b32_e32 v136, v142
	v_mul_f32_e32 v131, 0xbfb8aa3b, v46
	global_store_dwordx4 v[134:135], v[136:139], off offset:256
	v_lshl_add_u64 v[134:135], v[132:133], 0, s[2:3]
	s_nop 0
	v_exp_f32_e32 v136, v131
	v_mul_f32_e32 v131, 0xbfb8aa3b, v48
	v_exp_f32_e32 v137, v131
	v_mul_f32_e32 v131, 0xbfb8aa3b, v47
	v_exp_f32_e32 v138, v131
	v_mul_f32_e32 v131, 0xbfb8aa3b, v49
	v_pk_add_f32 v[136:137], v[136:137], 1.0 op_sel_hi:[1,0]
	v_exp_f32_e32 v139, v131
	v_rcp_f32_e32 v141, v137
	v_pk_add_f32 v[138:139], v[138:139], 1.0 op_sel_hi:[1,0]
	v_rcp_f32_e32 v143, v136
	v_mul_f32_e32 v131, v48, v141
	v_rcp_f32_e32 v142, v138
	v_mul_f32_e32 v141, v46, v143
	v_rcp_f32_e32 v143, v139
	v_mul_f32_e32 v142, v47, v142
	v_mul_f32_e32 v136, 0xbfb8aa3b, v42
	v_mul_f32_e32 v137, 0xbfb8aa3b, v44
	v_exp_f32_e32 v136, v136
	v_exp_f32_e32 v137, v137
	v_mul_f32_e32 v140, v49, v143
	v_mul_f32_e32 v138, 0xbfb8aa3b, v43
	v_pk_add_f32 v[136:137], v[136:137], 1.0 op_sel_hi:[1,0]
	v_mul_f32_e32 v139, 0xbfb8aa3b, v45
	v_rcp_f32_e32 v144, v137
	v_exp_f32_e32 v138, v138
	v_exp_f32_e32 v139, v139
	v_rcp_f32_e32 v147, v136
	v_mul_f32_e32 v137, v44, v144
	v_pk_add_f32 v[138:139], v[138:139], 1.0 op_sel_hi:[1,0]
	v_rcp_f32_e32 v146, v138
	v_mul_f32_e32 v136, v42, v147
	v_rcp_f32_e32 v147, v139
	v_mul_f32_e32 v138, v43, v146
	s_mov_b32 s2, 0x24000
	v_mul_f32_e32 v139, v45, v147
	v_cvt_pk_bf16_f32 v142, v141, v142
	v_cvt_pk_bf16_f32 v138, v136, v138
	v_cvt_pk_bf16_f32 v139, v137, v139
	v_cvt_pk_bf16_f32 v140, v131, v140
	v_mov_b32_e32 v137, v140
	v_mul_f32_e32 v131, 0xbfb8aa3b, v38
	v_exp_f32_e32 v140, v131
	v_mul_f32_e32 v131, 0xbfb8aa3b, v40
	v_mov_b32_e32 v136, v142
	v_exp_f32_e32 v141, v131
	v_add_co_u32_e32 v142, vcc, s2, v132
	v_mul_f32_e32 v131, 0xbfb8aa3b, v39
	s_nop 0
	v_addc_co_u32_e32 v143, vcc, 0, v133, vcc
	global_store_dwordx4 v[142:143], v[136:139], off
	s_nop 1
	v_pk_add_f32 v[136:137], v[140:141], 1.0 op_sel_hi:[1,0]
	v_exp_f32_e32 v138, v131
	v_rcp_f32_e32 v141, v137
	v_mul_f32_e32 v131, 0xbfb8aa3b, v41
	v_exp_f32_e32 v139, v131
	v_rcp_f32_e32 v143, v136
	v_mul_f32_e32 v131, v40, v141
	v_pk_add_f32 v[138:139], v[138:139], 1.0 op_sel_hi:[1,0]
	v_rcp_f32_e32 v142, v138
	v_mul_f32_e32 v141, v38, v143
	v_rcp_f32_e32 v143, v139
	v_mul_f32_e32 v142, v39, v142
	v_mul_f32_e32 v136, 0xbfb8aa3b, v34
	v_mul_f32_e32 v137, 0xbfb8aa3b, v36
	v_exp_f32_e32 v136, v136
	v_exp_f32_e32 v137, v137
	v_mul_f32_e32 v140, v41, v143
	v_mul_f32_e32 v138, 0xbfb8aa3b, v35
	v_pk_add_f32 v[136:137], v[136:137], 1.0 op_sel_hi:[1,0]
	v_mul_f32_e32 v139, 0xbfb8aa3b, v37
	v_rcp_f32_e32 v144, v137
	v_exp_f32_e32 v138, v138
	v_exp_f32_e32 v139, v139
	v_rcp_f32_e32 v147, v136
	v_mul_f32_e32 v137, v36, v144
	v_pk_add_f32 v[138:139], v[138:139], 1.0 op_sel_hi:[1,0]
	v_rcp_f32_e32 v146, v138
	v_mul_f32_e32 v136, v34, v147
	v_rcp_f32_e32 v147, v139
	v_mul_f32_e32 v138, v35, v146
	s_mov_b64 s[2:3], 0x28000
	v_mul_f32_e32 v139, v37, v147
	v_cvt_pk_bf16_f32 v142, v141, v142
	v_cvt_pk_bf16_f32 v140, v131, v140
	v_cvt_pk_bf16_f32 v138, v136, v138
	v_cvt_pk_bf16_f32 v139, v137, v139
	v_mov_b32_e32 v137, v140
	v_mov_b32_e32 v136, v142
	v_mul_f32_e32 v131, 0xbfb8aa3b, v30
	global_store_dwordx4 v[134:135], v[136:139], off offset:256
	v_lshl_add_u64 v[134:135], v[132:133], 0, s[2:3]
	s_nop 0
	v_exp_f32_e32 v136, v131
	v_mul_f32_e32 v131, 0xbfb8aa3b, v32
	v_exp_f32_e32 v137, v131
	v_mul_f32_e32 v131, 0xbfb8aa3b, v31
	v_exp_f32_e32 v138, v131
	v_mul_f32_e32 v131, 0xbfb8aa3b, v33
	v_pk_add_f32 v[136:137], v[136:137], 1.0 op_sel_hi:[1,0]
	v_exp_f32_e32 v139, v131
	v_rcp_f32_e32 v141, v137
	v_pk_add_f32 v[138:139], v[138:139], 1.0 op_sel_hi:[1,0]
	v_rcp_f32_e32 v143, v136
	v_mul_f32_e32 v131, v32, v141
	v_rcp_f32_e32 v142, v138
	v_mul_f32_e32 v141, v30, v143
	v_rcp_f32_e32 v143, v139
	v_mul_f32_e32 v142, v31, v142
	v_mul_f32_e32 v136, 0xbfb8aa3b, v26
	v_mul_f32_e32 v137, 0xbfb8aa3b, v28
	v_exp_f32_e32 v136, v136
	v_exp_f32_e32 v137, v137
	v_mul_f32_e32 v140, v33, v143
	v_mul_f32_e32 v138, 0xbfb8aa3b, v27
	v_pk_add_f32 v[136:137], v[136:137], 1.0 op_sel_hi:[1,0]
	v_mul_f32_e32 v139, 0xbfb8aa3b, v29
	v_rcp_f32_e32 v144, v137
	v_exp_f32_e32 v138, v138
	v_exp_f32_e32 v139, v139
	v_rcp_f32_e32 v147, v136
	v_mul_f32_e32 v137, v28, v144
	v_pk_add_f32 v[138:139], v[138:139], 1.0 op_sel_hi:[1,0]
	v_rcp_f32_e32 v146, v138
	v_mul_f32_e32 v136, v26, v147
	v_rcp_f32_e32 v147, v139
	v_mul_f32_e32 v138, v27, v146
	s_mov_b32 s2, 0x28000
	v_mul_f32_e32 v139, v29, v147
	v_cvt_pk_bf16_f32 v142, v141, v142
	v_cvt_pk_bf16_f32 v138, v136, v138
	v_cvt_pk_bf16_f32 v139, v137, v139
	v_cvt_pk_bf16_f32 v140, v131, v140
	v_mov_b32_e32 v137, v140
	v_mul_f32_e32 v131, 0xbfb8aa3b, v22
	v_exp_f32_e32 v140, v131
	v_mul_f32_e32 v131, 0xbfb8aa3b, v24
	v_mov_b32_e32 v136, v142
	v_exp_f32_e32 v141, v131
	v_add_co_u32_e32 v142, vcc, s2, v132
	v_mul_f32_e32 v131, 0xbfb8aa3b, v23
	s_nop 0
	v_addc_co_u32_e32 v143, vcc, 0, v133, vcc
	global_store_dwordx4 v[142:143], v[136:139], off
	s_nop 1
	v_pk_add_f32 v[136:137], v[140:141], 1.0 op_sel_hi:[1,0]
	v_exp_f32_e32 v138, v131
	v_rcp_f32_e32 v141, v137
	v_mul_f32_e32 v131, 0xbfb8aa3b, v25
	v_exp_f32_e32 v139, v131
	v_rcp_f32_e32 v143, v136
	v_mul_f32_e32 v131, v24, v141
	v_pk_add_f32 v[138:139], v[138:139], 1.0 op_sel_hi:[1,0]
	v_rcp_f32_e32 v142, v138
	v_mul_f32_e32 v141, v22, v143
	v_rcp_f32_e32 v143, v139
	v_mul_f32_e32 v142, v23, v142
	v_mul_f32_e32 v136, 0xbfb8aa3b, v18
	v_mul_f32_e32 v137, 0xbfb8aa3b, v20
	v_exp_f32_e32 v136, v136
	v_exp_f32_e32 v137, v137
	v_mul_f32_e32 v140, v25, v143
	v_mul_f32_e32 v138, 0xbfb8aa3b, v19
	v_pk_add_f32 v[136:137], v[136:137], 1.0 op_sel_hi:[1,0]
	v_mul_f32_e32 v139, 0xbfb8aa3b, v21
	v_rcp_f32_e32 v144, v137
	v_exp_f32_e32 v138, v138
	v_exp_f32_e32 v139, v139
	v_rcp_f32_e32 v147, v136
	v_mul_f32_e32 v137, v20, v144
	v_pk_add_f32 v[138:139], v[138:139], 1.0 op_sel_hi:[1,0]
	v_rcp_f32_e32 v146, v138
	v_mul_f32_e32 v136, v18, v147
	v_rcp_f32_e32 v147, v139
	v_mul_f32_e32 v138, v19, v146
	s_mov_b64 s[2:3], 0x2c000
	v_mul_f32_e32 v139, v21, v147
	v_cvt_pk_bf16_f32 v142, v141, v142
	v_cvt_pk_bf16_f32 v140, v131, v140
	v_cvt_pk_bf16_f32 v138, v136, v138
	v_cvt_pk_bf16_f32 v139, v137, v139
	v_mov_b32_e32 v137, v140
	v_mov_b32_e32 v136, v142
	v_mul_f32_e32 v131, 0xbfb8aa3b, v14
	global_store_dwordx4 v[134:135], v[136:139], off offset:256
	v_lshl_add_u64 v[134:135], v[132:133], 0, s[2:3]
	s_nop 0
	v_exp_f32_e32 v136, v131
	v_mul_f32_e32 v131, 0xbfb8aa3b, v16
	v_exp_f32_e32 v137, v131
	v_mul_f32_e32 v131, 0xbfb8aa3b, v15
	v_exp_f32_e32 v138, v131
	v_mul_f32_e32 v131, 0xbfb8aa3b, v17
	v_pk_add_f32 v[136:137], v[136:137], 1.0 op_sel_hi:[1,0]
	v_exp_f32_e32 v139, v131
	v_rcp_f32_e32 v141, v137
	v_pk_add_f32 v[138:139], v[138:139], 1.0 op_sel_hi:[1,0]
	v_rcp_f32_e32 v143, v136
	v_mul_f32_e32 v131, v16, v141
	v_rcp_f32_e32 v142, v138
	v_mul_f32_e32 v141, v14, v143
	v_rcp_f32_e32 v143, v139
	v_mul_f32_e32 v142, v15, v142
	v_mul_f32_e32 v136, 0xbfb8aa3b, v10
	v_mul_f32_e32 v137, 0xbfb8aa3b, v12
	v_exp_f32_e32 v136, v136
	v_exp_f32_e32 v137, v137
	v_mul_f32_e32 v140, v17, v143
	v_mul_f32_e32 v138, 0xbfb8aa3b, v11
	v_pk_add_f32 v[136:137], v[136:137], 1.0 op_sel_hi:[1,0]
	v_mul_f32_e32 v139, 0xbfb8aa3b, v13
	v_rcp_f32_e32 v144, v137
	v_exp_f32_e32 v138, v138
	v_exp_f32_e32 v139, v139
	v_rcp_f32_e32 v147, v136
	v_mul_f32_e32 v137, v12, v144
	v_pk_add_f32 v[138:139], v[138:139], 1.0 op_sel_hi:[1,0]
	v_rcp_f32_e32 v146, v138
	v_mul_f32_e32 v136, v10, v147
	v_rcp_f32_e32 v147, v139
	v_mul_f32_e32 v138, v11, v146
	s_mov_b32 s2, 0x2c000
	v_mul_f32_e32 v139, v13, v147
	v_cvt_pk_bf16_f32 v142, v141, v142
	v_cvt_pk_bf16_f32 v138, v136, v138
	v_cvt_pk_bf16_f32 v139, v137, v139
	v_cvt_pk_bf16_f32 v140, v131, v140
	v_mov_b32_e32 v137, v140
	v_mul_f32_e32 v131, 0xbfb8aa3b, v6
	v_exp_f32_e32 v140, v131
	v_mul_f32_e32 v131, 0xbfb8aa3b, v8
	v_mov_b32_e32 v136, v142
	v_exp_f32_e32 v141, v131
	v_add_co_u32_e32 v132, vcc, s2, v132
	v_mul_f32_e32 v131, 0xbfb8aa3b, v7
	s_nop 0
	v_addc_co_u32_e32 v133, vcc, 0, v133, vcc
	global_store_dwordx4 v[132:133], v[136:139], off
	v_pk_add_f32 v[132:133], v[140:141], 1.0 op_sel_hi:[1,0]
	s_nop 0
	v_rcp_f32_e32 v139, v133
	v_exp_f32_e32 v136, v131
	v_mul_f32_e32 v131, 0xbfb8aa3b, v9
	v_exp_f32_e32 v137, v131
	v_rcp_f32_e32 v141, v132
	v_mul_f32_e32 v131, v8, v139
	v_pk_add_f32 v[136:137], v[136:137], 1.0 op_sel_hi:[1,0]
	v_rcp_f32_e32 v140, v136
	v_mul_f32_e32 v139, v6, v141
	v_rcp_f32_e32 v141, v137
	v_mul_f32_e32 v140, v7, v140
	v_mul_f32_e32 v132, 0xbfb8aa3b, v2
	v_mul_f32_e32 v133, 0xbfb8aa3b, v4
	v_exp_f32_e32 v132, v132
	v_exp_f32_e32 v133, v133
	v_mul_f32_e32 v138, v9, v141
	v_mul_f32_e32 v136, 0xbfb8aa3b, v3
	v_pk_add_f32 v[132:133], v[132:133], 1.0 op_sel_hi:[1,0]
	v_mul_f32_e32 v137, 0xbfb8aa3b, v5
	v_rcp_f32_e32 v142, v133
	v_exp_f32_e32 v136, v136
	v_exp_f32_e32 v137, v137
	v_rcp_f32_e32 v145, v132
	v_mul_f32_e32 v133, v4, v142
	v_pk_add_f32 v[136:137], v[136:137], 1.0 op_sel_hi:[1,0]
	v_rcp_f32_e32 v144, v136
	v_mul_f32_e32 v132, v2, v145
	v_rcp_f32_e32 v145, v137
	v_mul_f32_e32 v136, v3, v144
	v_mul_f32_e32 v137, v5, v145
	v_bfe_u32 v143, v138, 16, 1
	v_bfe_u32 v144, v140, 16, 1
	v_add3_u32 v140, v140, v144, s0
	v_add3_u32 v143, v138, v143, s0
	v_cvt_pk_bf16_f32 v136, v132, v136
	v_cvt_pk_bf16_f32 v137, v133, v137
	v_bfe_u32 v138, v139, 16, 1
	v_bfe_u32 v141, v131, 16, 1
	v_add3_u32 v131, v131, v141, s0
	v_add3_u32 v138, v139, v138, s0
	v_lshrrev_b32_e32 v141, 16, v138
	v_lshrrev_b32_e32 v131, 16, v131
	v_mov_b32_e32 v139, v137
	v_mov_b32_e32 v138, v136
	v_and_or_b32 v137, v143, s1, v131
	v_and_or_b32 v136, v140, s1, v141
	s_mov_b64 s[0:1], 0
	global_store_dwordx4 v[134:135], v[136:139], off offset:256
.LBB0_993:
	s_andn2_b64 vcc, exec, s[0:1]
	s_cbranch_vccnz .LBB0_995
	v_readlane_b32 s16, v254, 4
	v_readlane_b32 s17, v254, 5
	v_readlane_b32 s18, v254, 6
	v_readlane_b32 s19, v254, 7
	v_readlane_b32 s20, v254, 8
	v_readlane_b32 s21, v254, 9
	v_lshlrev_b32_e32 v131, 2, v1
	v_readlane_b32 s22, v254, 10
	v_readlane_b32 s23, v254, 11
	s_mov_b64 s[16:17], s[20:21]
	global_load_dwordx4 v[140:143], v131, s[16:17] offset:2048
	global_load_dwordx4 v[144:147], v131, s[16:17]
	global_load_dwordx4 v[148:151], v131, s[16:17] offset:16
	global_load_dwordx4 v[156:159], v131, s[16:17] offset:2064
	global_load_dwordx4 v[160:163], v131, s[16:17] offset:2560
	global_load_dwordx4 v[164:167], v131, s[16:17] offset:512
	global_load_dwordx4 v[168:171], v131, s[16:17] offset:528
	global_load_dwordx4 v[172:175], v131, s[16:17] offset:2576
	s_mov_b64 s[18:19], s[22:23]
	s_movk_i32 s20, 0x2080
	v_mov_b32_e32 v154, 0xffffdf80
	v_cmp_gt_i32_e32 vcc, s20, v130
	v_lshlrev_b32_e32 v134, 1, v1
	v_mov_b32_e32 v135, 0
	v_ashrrev_i32_e32 v131, 31, v130
	v_cndmask_b32_e64 v153, v154, 0, vcc
	s_mov_b64 s[2:3], 0xb800000
	s_movk_i32 s18, 0x70
	v_lshl_add_u64 v[132:133], s[10:11], 0, v[134:135]
	v_lshl_add_u64 v[134:135], s[72:73], 0, v[134:135]
	v_lshlrev_b64 v[136:137], 10, v[130:131]
	v_add_u32_e32 v131, v153, v130
	v_lshl_add_u64 v[134:135], v[134:135], 0, s[2:3]
	v_cmp_gt_i32_e64 s[2:3], s18, v131
	v_mul_f32_e32 v152, 0x3fb8aa3b, v128
	v_mul_f32_e32 v155, 0x3fb8aa3b, v129
	v_exp_f32_e32 v177, v152
	v_exp_f32_e32 v179, v155
	v_mul_f32_e32 v138, 0x3fb8aa3b, v126
	v_exp_f32_e32 v176, v138
	v_mul_f32_e32 v139, 0x3fb8aa3b, v127
	s_mov_b32 s14, 0x800000
	v_exp_f32_e32 v178, v139
	s_mov_b32 s9, 0x3f317217
	s_mov_b32 s15, 0x7f800000
	s_movk_i32 s19, 0x4100
	v_cmp_gt_i32_e64 s[0:1], s19, v130
	s_movk_i32 s16, 0x7fff
	s_mov_b32 s17, 0xffff0000
	v_lshl_add_u64 v[138:139], v[132:133], 0, v[136:137]
	v_lshl_add_u64 v[136:137], v[134:135], 0, v[136:137]
	v_readlane_b32 s24, v254, 12
	v_readlane_b32 s25, v254, 13
	v_readlane_b32 s26, v254, 14
	v_readlane_b32 s27, v254, 15
	v_readlane_b32 s28, v254, 16
	v_readlane_b32 s29, v254, 17
	v_readlane_b32 s30, v254, 18
	v_readlane_b32 s31, v254, 19
	s_waitcnt vmcnt(0)
	v_sub_f32_e32 v131, v144, v140
	v_sub_f32_e32 v140, v145, v141
	v_sub_f32_e32 v141, v146, v142
	v_sub_f32_e32 v142, v147, v143
	v_sub_f32_e32 v143, v148, v156
	v_mul_f32_e32 v131, 0x3fb8aa3b, v131
	v_sub_f32_e32 v156, v171, v175
	v_mul_f32_e32 v141, 0x3fb8aa3b, v141
	v_sub_f32_e32 v144, v149, v157
	v_sub_f32_e32 v147, v164, v160
	v_mul_f32_e32 v164, 0x3fb8aa3b, v156
	v_exp_f32_e32 v156, v131
	v_exp_f32_e32 v157, v141
	v_sub_f32_e32 v152, v169, v173
	v_sub_f32_e32 v145, v150, v158
	v_sub_f32_e32 v149, v166, v162
	v_pk_add_f32 v[156:157], v[156:157], 1.0 op_sel_hi:[1,0]
	v_sub_f32_e32 v150, v167, v163
	v_mul_f32_e32 v140, 0x3fb8aa3b, v140
	v_mul_f32_e32 v162, 0x3fb8aa3b, v152
	v_sub_f32_e32 v148, v165, v161
	v_mul_f32_e32 v145, 0x3fb8aa3b, v145
	v_mul_f32_e32 v150, 0x3fb8aa3b, v150
	v_exp_f32_e32 v158, v140
	v_exp_f32_e32 v140, v162
	v_mul_f32_e32 v131, 0x3fb8aa3b, v122
	v_rcp_f32_e32 v162, v156
	v_sub_f32_e32 v146, v151, v159
	v_sub_f32_e32 v151, v168, v172
	v_mul_f32_e32 v144, 0x3fb8aa3b, v144
	v_mul_f32_e32 v148, 0x3fb8aa3b, v148
	v_exp_f32_e32 v161, v145
	v_exp_f32_e32 v145, v150
	v_exp_f32_e32 v150, v131
	v_mul_f32_e32 v131, 0x3fb8aa3b, v123
	v_mul_f32_e32 v142, 0x3fb8aa3b, v142
	v_mul_f32_e32 v151, 0x3fb8aa3b, v151
	v_exp_f32_e32 v152, v144
	v_exp_f32_e32 v144, v148
	v_exp_f32_e32 v148, v131
	v_mul_f32_e32 v131, 0x3fb8aa3b, v124
	v_sub_f32_e32 v153, v170, v174
	v_mul_f32_e32 v146, 0x3fb8aa3b, v146
	v_mul_f32_e32 v147, 0x3fb8aa3b, v147
	v_mul_f32_e32 v149, 0x3fb8aa3b, v149
	v_exp_f32_e32 v159, v142
	v_exp_f32_e32 v142, v151
	v_exp_f32_e32 v151, v131
	v_mul_f32_e32 v131, 0x3fb8aa3b, v125
	v_mul_f32_e32 v163, 0x3fb8aa3b, v153
	v_exp_f32_e32 v153, v146
	v_exp_f32_e32 v146, v147
	v_exp_f32_e32 v147, v149
	v_exp_f32_e32 v149, v131
	v_mul_f32_e32 v143, 0x3fb8aa3b, v143
	v_exp_f32_e32 v160, v143
	v_exp_f32_e32 v143, v163
	v_exp_f32_e32 v141, v164
	v_rcp_f32_e32 v164, v157
	v_mov_b32_e32 v156, v162
	v_pk_add_f32 v[158:159], v[158:159], 1.0 op_sel_hi:[1,0]
	v_rcp_f32_e32 v163, v158
	v_mov_b32_e32 v157, v164
	v_pk_add_f32 v[160:161], v[160:161], 1.0 op_sel_hi:[1,0]
	v_div_scale_f32 v164, s[4:5], v159, v159, 1.0
	v_rcp_f32_e32 v165, v164
	v_mov_b32_e32 v155, v163
	v_fma_f32 v131, -v164, v165, 1.0
	v_fmac_f32_e32 v165, v131, v165
	v_div_scale_f32 v131, vcc, 1.0, v159, 1.0
	v_mul_f32_e32 v158, v131, v165
	v_fma_f32 v162, -v164, v158, v131
	v_fmac_f32_e32 v158, v162, v165
	v_pk_add_f32 v[162:163], v[176:177], 1.0 op_sel_hi:[1,0]
	v_fma_f32 v131, -v164, v158, v131
	v_div_scale_f32 v166, s[4:5], v163, v163, v157
	v_rcp_f32_e32 v167, v166
	v_div_fmas_f32 v131, v131, v165, v158
	v_pk_add_f32 v[150:151], v[150:151], 1.0 op_sel_hi:[1,0]
	v_pk_add_f32 v[148:149], v[148:149], 1.0 op_sel_hi:[1,0]
	v_fma_f32 v158, -v166, v167, 1.0
	v_fmac_f32_e32 v167, v158, v167
	v_div_scale_f32 v158, vcc, v157, v163, v157
	v_mul_f32_e32 v164, v158, v167
	v_fma_f32 v165, -v166, v164, v158
	v_fmac_f32_e32 v164, v165, v167
	v_rcp_f32_e32 v168, v162
	v_fma_f32 v158, -v166, v164, v158
	v_div_fmas_f32 v164, v158, v167, v164
	v_pk_add_f32 v[146:147], v[146:147], 1.0 op_sel_hi:[1,0]
	v_mul_f32_e32 v165, v156, v168
	v_sub_f32_e32 v158, 1.0, v165
	v_cmp_gt_f32_e64 s[4:5], s14, v158
	v_pk_add_f32 v[142:143], v[142:143], 1.0 op_sel_hi:[1,0]
	s_nop 0
	v_cndmask_b32_e64 v162, 0, 32, s[4:5]
	v_ldexp_f32 v158, v158, v162
	v_log_f32_e32 v166, v158
	v_div_fixup_f32 v158, v131, v159, 1.0
	v_div_fixup_f32 v159, v164, v163, v157
	v_pk_add_f32 v[162:163], v[178:179], 1.0 op_sel_hi:[1,0]
	v_mul_f32_e32 v131, 0x3f317217, v166
	v_div_scale_f32 v164, s[6:7], v163, v163, v158
	v_rcp_f32_e32 v167, v164
	v_fma_f32 v131, v166, s9, -v131
	v_fmac_f32_e32 v131, 0x3377d1cf, v166
	v_fmac_f32_e32 v131, 0x3f317217, v166
	v_cmp_lt_f32_e64 vcc, |v166|, s15
	v_fma_f32 v168, -v164, v167, 1.0
	v_fmac_f32_e32 v167, v168, v167
	v_cndmask_b32_e32 v166, v166, v131, vcc
	v_div_scale_f32 v168, vcc, v158, v163, v158
	v_mul_f32_e32 v169, v168, v167
	v_fma_f32 v170, -v164, v169, v168
	v_fmac_f32_e32 v169, v170, v167
	v_rcp_f32_e32 v171, v162
	v_fma_f32 v164, -v164, v169, v168
	v_div_fmas_f32 v164, v164, v167, v169
	v_mov_b32_e32 v131, 0x41b17218
	v_mul_f32_e32 v162, v155, v171
	v_sub_f32_e32 v167, 1.0, v162
	v_cmp_gt_f32_e32 vcc, s14, v167
	v_div_fixup_f32 v163, v164, v163, v158
	s_nop 0
	v_cndmask_b32_e64 v168, 0, 32, vcc
	v_ldexp_f32 v167, v167, v168
	v_log_f32_e32 v167, v167
	v_cndmask_b32_e64 v168, 0, v131, s[4:5]
	v_sub_f32_e32 v166, v166, v168
	v_sub_f32_e32 v168, 1.0, v159
	v_cmp_gt_f32_e64 s[4:5], s14, v168
	v_mul_f32_e32 v164, 0x3f317217, v167
	v_fma_f32 v164, v167, s9, -v164
	v_cndmask_b32_e64 v169, 0, 32, s[4:5]
	v_ldexp_f32 v168, v168, v169
	v_fmac_f32_e32 v164, 0x3377d1cf, v167
	v_log_f32_e32 v168, v168
	v_fmac_f32_e32 v164, 0x3f317217, v167
	v_cmp_lt_f32_e64 s[6:7], |v167|, s15
	v_sub_f32_e32 v169, 1.0, v163
	s_nop 0
	v_cndmask_b32_e64 v164, v167, v164, s[6:7]
	v_cndmask_b32_e32 v167, 0, v131, vcc
	v_cmp_gt_f32_e32 vcc, s14, v169
	v_sub_f32_e32 v164, v164, v167
	v_mul_f32_e32 v167, 0x3f317217, v168
	v_cndmask_b32_e64 v170, 0, 32, vcc
	v_ldexp_f32 v169, v169, v170
	v_fma_f32 v167, v168, s9, -v167
	v_log_f32_e32 v169, v169
	v_fmac_f32_e32 v167, 0x3377d1cf, v168
	v_fmac_f32_e32 v167, 0x3f317217, v168
	v_cmp_lt_f32_e64 s[6:7], |v168|, s15
	s_nop 1
	v_cndmask_b32_e64 v167, v168, v167, s[6:7]
	v_cndmask_b32_e64 v168, 0, v131, s[4:5]
	v_sub_f32_e32 v167, v167, v168
	v_mul_f32_e32 v168, 0x3f317217, v169
	v_fma_f32 v168, v169, s9, -v168
	v_fmac_f32_e32 v168, 0x3377d1cf, v169
	v_fmac_f32_e32 v168, 0x3f317217, v169
	v_cmp_lt_f32_e64 s[4:5], |v169|, s15
	s_nop 1
	v_cndmask_b32_e64 v168, v169, v168, s[4:5]
	v_cndmask_b32_e32 v169, 0, v131, vcc
	s_and_b64 s[4:5], s[0:1], s[2:3]
	v_sub_f32_e32 v168, v168, v169
	v_cndmask_b32_e64 v169, v159, 0, s[4:5]
	v_rcp_f32_e32 v170, v160
	v_cndmask_b32_e64 v171, v162, 0, s[4:5]
	v_cndmask_b32_e64 v172, v163, 0, s[4:5]
	v_cndmask_b32_e64 v165, v165, 0, s[4:5]
	v_rcp_f32_e32 v173, v161
	v_mov_b32_e32 v159, v170
	v_pk_add_f32 v[162:163], v[152:153], 1.0 op_sel_hi:[1,0]
	v_div_scale_f32 v153, s[0:1], v162, v162, 1.0
	v_rcp_f32_e32 v174, v153
	v_mov_b32_e32 v152, v173
	v_fma_f32 v160, -v153, v174, 1.0
	v_fmac_f32_e32 v174, v160, v174
	v_div_scale_f32 v160, vcc, 1.0, v162, 1.0
	v_mul_f32_e32 v161, v160, v174
	v_fma_f32 v170, -v153, v161, v160
	v_fmac_f32_e32 v161, v170, v174
	v_div_scale_f32 v170, s[0:1], v163, v163, 1.0
	v_rcp_f32_e32 v173, v170
	v_fma_f32 v153, -v153, v161, v160
	v_div_fmas_f32 v153, v153, v174, v161
	v_fma_f32 v160, -v170, v173, 1.0
	v_fmac_f32_e32 v173, v160, v173
	v_div_scale_f32 v160, vcc, 1.0, v163, 1.0
	v_mul_f32_e32 v161, v160, v173
	v_fma_f32 v174, -v170, v161, v160
	v_fmac_f32_e32 v161, v174, v173
	v_rcp_f32_e32 v175, v151
	v_fma_f32 v160, -v170, v161, v160
	v_div_fmas_f32 v161, v160, v173, v161
	v_rcp_f32_e32 v176, v150
	v_mul_f32_e32 v151, v152, v175
	v_mul_f32_e32 v150, v159, v176
	v_sub_f32_e32 v160, 1.0, v150
	v_cmp_gt_f32_e64 s[0:1], s14, v160
	v_cndmask_b32_e64 v150, v150, 0, s[4:5]
	s_nop 0
	v_cndmask_b32_e64 v173, 0, 32, s[0:1]
	v_ldexp_f32 v160, v160, v173
	v_log_f32_e32 v173, v160
	v_div_fixup_f32 v160, v153, v162, 1.0
	v_div_fixup_f32 v153, v161, v163, 1.0
	v_rcp_f32_e32 v163, v149
	v_mul_f32_e32 v161, 0x3f317217, v173
	v_fma_f32 v161, v173, s9, -v161
	v_fmac_f32_e32 v161, 0x3377d1cf, v173
	v_fmac_f32_e32 v161, 0x3f317217, v173
	v_cmp_lt_f32_e64 vcc, |v173|, s15
	s_nop 1
	v_cndmask_b32_e32 v161, v173, v161, vcc
	v_rcp_f32_e32 v175, v148
	v_mul_f32_e32 v149, v153, v163
	v_mul_f32_e32 v148, v160, v175
	v_sub_f32_e32 v163, 1.0, v148
	v_cmp_gt_f32_e32 vcc, s14, v163
	v_cndmask_b32_e64 v148, v148, 0, s[4:5]
	s_nop 0
	v_cndmask_b32_e64 v170, 0, 32, vcc
	v_ldexp_f32 v163, v163, v170
	v_log_f32_e32 v163, v163
	v_cndmask_b32_e64 v170, 0, v131, s[0:1]
	v_sub_f32_e32 v161, v161, v170
	v_sub_f32_e32 v170, 1.0, v151
	v_cmp_gt_f32_e64 s[0:1], s14, v170
	v_mul_f32_e32 v162, 0x3f317217, v163
	v_fma_f32 v162, v163, s9, -v162
	v_cndmask_b32_e64 v173, 0, 32, s[0:1]
	v_ldexp_f32 v170, v170, v173
	v_fmac_f32_e32 v162, 0x3377d1cf, v163
	v_log_f32_e32 v170, v170
	v_fmac_f32_e32 v162, 0x3f317217, v163
	v_cmp_lt_f32_e64 s[2:3], |v163|, s15
	v_sub_f32_e32 v173, 1.0, v149
	v_cndmask_b32_e64 v149, v149, 0, s[4:5]
	v_cndmask_b32_e64 v162, v163, v162, s[2:3]
	v_cndmask_b32_e32 v163, 0, v131, vcc
	v_cmp_gt_f32_e32 vcc, s14, v173
	v_sub_f32_e32 v162, v162, v163
	v_mul_f32_e32 v163, 0x3f317217, v170
	v_cndmask_b32_e64 v174, 0, 32, vcc
	v_ldexp_f32 v173, v173, v174
	v_fma_f32 v163, v170, s9, -v163
	v_log_f32_e32 v173, v173
	v_fmac_f32_e32 v163, 0x3377d1cf, v170
	v_fmac_f32_e32 v163, 0x3f317217, v170
	v_cmp_lt_f32_e64 s[2:3], |v170|, s15
	v_cndmask_b32_e64 v151, v151, 0, s[4:5]
	s_nop 0
	v_cndmask_b32_e64 v163, v170, v163, s[2:3]
	v_cndmask_b32_e64 v170, 0, v131, s[0:1]
	v_sub_f32_e32 v163, v163, v170
	v_mul_f32_e32 v170, 0x3f317217, v173
	v_fma_f32 v170, v173, s9, -v170
	v_fmac_f32_e32 v170, 0x3377d1cf, v173
	v_fmac_f32_e32 v170, 0x3f317217, v173
	v_cmp_lt_f32_e64 s[0:1], |v173|, s15
	v_cvt_pk_bf16_f32 v171, v165, v171
	v_cvt_pk_bf16_f32 v172, v169, v172
	v_cndmask_b32_e64 v170, v173, v170, s[0:1]
	v_cndmask_b32_e32 v173, 0, v131, vcc
	v_sub_f32_e32 v170, v170, v173
	v_cvt_pk_bf16_f32 v148, v150, v148
	v_cvt_pk_bf16_f32 v149, v151, v149
	v_mov_b32_e32 v151, v149
	v_mov_b32_e32 v150, v148
	v_mov_b32_e32 v149, v172
	v_mov_b32_e32 v148, v171
	global_store_dwordx4 v[138:139], v[148:151], off
	s_nop 1
	v_cndmask_b32_e64 v148, v166, 0, s[4:5]
	v_bfe_u32 v149, v148, 16, 1
	v_add3_u32 v148, v148, v149, s16
	v_cndmask_b32_e64 v149, v164, 0, s[4:5]
	v_bfe_u32 v150, v149, 16, 1
	v_lshrrev_b32_e32 v148, 16, v148
	v_add3_u32 v149, v149, v150, s16
	v_and_or_b32 v148, v149, s17, v148
	v_cndmask_b32_e64 v149, v167, 0, s[4:5]
	v_bfe_u32 v150, v149, 16, 1
	v_add3_u32 v149, v149, v150, s16
	v_cndmask_b32_e64 v150, v168, 0, s[4:5]
	v_bfe_u32 v151, v150, 16, 1
	v_lshrrev_b32_e32 v149, 16, v149
	v_add3_u32 v150, v150, v151, s16
	v_and_or_b32 v149, v150, s17, v149
	v_cndmask_b32_e64 v150, v161, 0, s[4:5]
	v_bfe_u32 v151, v150, 16, 1
	v_add3_u32 v150, v150, v151, s16
	v_cndmask_b32_e64 v151, v162, 0, s[4:5]
	v_bfe_u32 v161, v151, 16, 1
	v_lshrrev_b32_e32 v150, 16, v150
	v_add3_u32 v151, v151, v161, s16
	v_and_or_b32 v150, v151, s17, v150
	v_cndmask_b32_e64 v151, v163, 0, s[4:5]
	v_bfe_u32 v161, v151, 16, 1
	v_add3_u32 v151, v151, v161, s16
	v_cndmask_b32_e64 v161, v170, 0, s[4:5]
	v_bfe_u32 v162, v161, 16, 1
	v_lshrrev_b32_e32 v151, 16, v151
	v_add3_u32 v161, v161, v162, s16
	v_and_or_b32 v151, v161, s17, v151
	v_rcp_f32_e32 v166, v146
	global_store_dwordx4 v[136:137], v[148:151], off
	v_rcp_f32_e32 v169, v147
	v_mov_b32_e32 v146, v166
	v_mul_f32_e32 v148, 0x3fb8aa3b, v118
	v_pk_add_f32 v[166:167], v[144:145], 1.0 op_sel_hi:[1,0]
	v_div_scale_f32 v145, s[0:1], v166, v166, 1.0
	v_rcp_f32_e32 v170, v145
	v_mov_b32_e32 v144, v169
	v_exp_f32_e32 v162, v148
	v_mul_f32_e32 v148, 0x3fb8aa3b, v119
	v_fma_f32 v147, -v145, v170, 1.0
	v_fmac_f32_e32 v170, v147, v170
	v_div_scale_f32 v147, vcc, 1.0, v166, 1.0
	v_mul_f32_e32 v161, v147, v170
	v_fma_f32 v168, -v145, v161, v147
	v_fmac_f32_e32 v161, v168, v170
	v_div_scale_f32 v168, s[0:1], v167, v167, 1.0
	v_rcp_f32_e32 v169, v168
	v_exp_f32_e32 v164, v148
	v_mul_f32_e32 v148, 0x3fb8aa3b, v120
	v_exp_f32_e32 v163, v148
	v_fma_f32 v145, -v145, v161, v147
	v_fma_f32 v147, -v168, v169, 1.0
	v_div_fmas_f32 v145, v145, v170, v161
	v_fmac_f32_e32 v169, v147, v169
	v_div_scale_f32 v147, vcc, 1.0, v167, 1.0
	v_mul_f32_e32 v161, v147, v169
	v_fma_f32 v170, -v168, v161, v147
	v_pk_add_f32 v[162:163], v[162:163], 1.0 op_sel_hi:[1,0]
	v_fmac_f32_e32 v161, v170, v169
	v_div_scale_f32 v170, s[0:1], v163, v163, v144
	v_rcp_f32_e32 v171, v170
	v_fma_f32 v147, -v168, v161, v147
	v_div_fmas_f32 v161, v147, v169, v161
	v_mul_f32_e32 v148, 0x3fb8aa3b, v121
	v_fma_f32 v147, -v170, v171, 1.0
	v_fmac_f32_e32 v171, v147, v171
	v_div_scale_f32 v147, vcc, v144, v163, v144
	v_mul_f32_e32 v168, v147, v171
	v_fma_f32 v169, -v170, v168, v147
	v_fmac_f32_e32 v168, v169, v171
	v_rcp_f32_e32 v172, v162
	v_fma_f32 v147, -v170, v168, v147
	v_div_fmas_f32 v168, v147, v171, v168
	v_exp_f32_e32 v165, v148
	v_mul_f32_e32 v169, v146, v172
	v_sub_f32_e32 v147, 1.0, v169
	v_cmp_gt_f32_e64 s[0:1], s14, v147
	v_mul_f32_e32 v148, 0x3fb8aa3b, v114
	v_mul_f32_e32 v149, 0x3fb8aa3b, v116
	v_cndmask_b32_e64 v162, 0, 32, s[0:1]
	v_ldexp_f32 v147, v147, v162
	v_log_f32_e32 v170, v147
	v_div_fixup_f32 v147, v145, v166, 1.0
	v_div_fixup_f32 v145, v161, v167, 1.0
	v_div_fixup_f32 v161, v168, v163, v144
	v_mul_f32_e32 v162, 0x3f317217, v170
	v_fma_f32 v166, v170, s9, -v162
	v_pk_add_f32 v[162:163], v[164:165], 1.0 op_sel_hi:[1,0]
	v_fmac_f32_e32 v166, 0x3377d1cf, v170
	v_rcp_f32_e32 v165, v163
	v_fmac_f32_e32 v166, 0x3f317217, v170
	v_cmp_lt_f32_e64 vcc, |v170|, s15
	v_exp_f32_e32 v150, v148
	s_nop 0
	v_cndmask_b32_e32 v166, v170, v166, vcc
	v_rcp_f32_e32 v171, v162
	v_mul_f32_e32 v163, v145, v165
	v_mul_f32_e32 v162, v147, v171
	v_sub_f32_e32 v165, 1.0, v162
	v_cmp_gt_f32_e32 vcc, s14, v165
	v_cndmask_b32_e64 v171, v162, 0, s[4:5]
	v_cndmask_b32_e64 v172, v163, 0, s[4:5]
	v_cndmask_b32_e64 v167, 0, 32, vcc
	v_ldexp_f32 v165, v165, v167
	v_log_f32_e32 v165, v165
	v_cndmask_b32_e64 v167, 0, v131, s[0:1]
	v_sub_f32_e32 v166, v166, v167
	v_sub_f32_e32 v167, 1.0, v161
	v_cmp_gt_f32_e64 s[0:1], s14, v167
	v_mul_f32_e32 v164, 0x3f317217, v165
	v_fma_f32 v164, v165, s9, -v164
	v_cndmask_b32_e64 v168, 0, 32, s[0:1]
	v_ldexp_f32 v167, v167, v168
	v_fmac_f32_e32 v164, 0x3377d1cf, v165
	v_log_f32_e32 v167, v167
	v_fmac_f32_e32 v164, 0x3f317217, v165
	v_cmp_lt_f32_e64 s[2:3], |v165|, s15
	v_sub_f32_e32 v168, 1.0, v163
	v_exp_f32_e32 v151, v149
	v_cndmask_b32_e64 v164, v165, v164, s[2:3]
	v_cndmask_b32_e32 v165, 0, v131, vcc
	v_cmp_gt_f32_e32 vcc, s14, v168
	v_sub_f32_e32 v164, v164, v165
	v_mul_f32_e32 v165, 0x3f317217, v167
	v_cndmask_b32_e64 v170, 0, 32, vcc
	v_ldexp_f32 v168, v168, v170
	v_fma_f32 v165, v167, s9, -v165
	v_log_f32_e32 v168, v168
	v_fmac_f32_e32 v165, 0x3377d1cf, v167
	v_fmac_f32_e32 v165, 0x3f317217, v167
	v_cmp_lt_f32_e64 s[2:3], |v167|, s15
	v_pk_add_f32 v[150:151], v[150:151], 1.0 op_sel_hi:[1,0]
	v_mul_f32_e32 v148, 0x3fb8aa3b, v115
	v_cndmask_b32_e64 v165, v167, v165, s[2:3]
	v_cndmask_b32_e64 v167, 0, v131, s[0:1]
	v_sub_f32_e32 v165, v165, v167
	v_mul_f32_e32 v167, 0x3f317217, v168
	v_fma_f32 v167, v168, s9, -v167
	v_fmac_f32_e32 v167, 0x3377d1cf, v168
	v_fmac_f32_e32 v167, 0x3f317217, v168
	v_cmp_lt_f32_e64 s[0:1], |v168|, s15
	v_mul_f32_e32 v149, 0x3fb8aa3b, v117
	v_exp_f32_e32 v148, v148
	v_cndmask_b32_e64 v167, v168, v167, s[0:1]
	v_cndmask_b32_e32 v168, 0, v131, vcc
	v_sub_f32_e32 v167, v167, v168
	v_rcp_f32_e32 v170, v142
	v_exp_f32_e32 v149, v149
	v_cndmask_b32_e64 v161, v161, 0, s[4:5]
	v_cndmask_b32_e64 v169, v169, 0, s[4:5]
	v_rcp_f32_e32 v173, v143
	v_mov_b32_e32 v142, v170
	v_pk_add_f32 v[148:149], v[148:149], 1.0 op_sel_hi:[1,0]
	v_pk_add_f32 v[162:163], v[140:141], 1.0 op_sel_hi:[1,0]
	v_div_scale_f32 v141, s[0:1], v162, v162, 1.0
	v_rcp_f32_e32 v174, v141
	v_mov_b32_e32 v140, v173
	v_fma_f32 v143, -v141, v174, 1.0
	v_fmac_f32_e32 v174, v143, v174
	v_div_scale_f32 v143, vcc, 1.0, v162, 1.0
	v_mul_f32_e32 v168, v143, v174
	v_fma_f32 v170, -v141, v168, v143
	v_fmac_f32_e32 v168, v170, v174
	v_div_scale_f32 v170, s[0:1], v163, v163, 1.0
	v_rcp_f32_e32 v173, v170
	v_fma_f32 v141, -v141, v168, v143
	v_div_fmas_f32 v141, v141, v174, v168
	v_fma_f32 v143, -v170, v173, 1.0
	v_fmac_f32_e32 v173, v143, v173
	v_div_scale_f32 v143, vcc, 1.0, v163, 1.0
	v_mul_f32_e32 v168, v143, v173
	v_fma_f32 v174, -v170, v168, v143
	v_fmac_f32_e32 v168, v174, v173
	v_rcp_f32_e32 v175, v151
	v_fma_f32 v143, -v170, v168, v143
	v_div_fmas_f32 v168, v143, v173, v168
	v_rcp_f32_e32 v176, v150
	v_mul_f32_e32 v151, v140, v175
	v_mul_f32_e32 v150, v142, v176
	v_sub_f32_e32 v143, 1.0, v150
	v_cmp_gt_f32_e64 s[0:1], s14, v143
	v_cndmask_b32_e64 v150, v150, 0, s[4:5]
	s_nop 0
	v_cndmask_b32_e64 v173, 0, 32, s[0:1]
	v_ldexp_f32 v143, v143, v173
	v_log_f32_e32 v173, v143
	v_div_fixup_f32 v143, v141, v162, 1.0
	v_div_fixup_f32 v141, v168, v163, 1.0
	v_rcp_f32_e32 v168, v149
	v_mul_f32_e32 v162, 0x3f317217, v173
	v_fma_f32 v162, v173, s9, -v162
	v_fmac_f32_e32 v162, 0x3377d1cf, v173
	v_fmac_f32_e32 v162, 0x3f317217, v173
	v_cmp_lt_f32_e64 vcc, |v173|, s15
	s_nop 1
	v_cndmask_b32_e32 v162, v173, v162, vcc
	v_rcp_f32_e32 v175, v148
	v_mul_f32_e32 v149, v141, v168
	v_mul_f32_e32 v148, v143, v175
	v_sub_f32_e32 v168, 1.0, v148
	v_cmp_gt_f32_e32 vcc, s14, v168
	v_cndmask_b32_e64 v148, v148, 0, s[4:5]
	s_nop 0
	v_cndmask_b32_e64 v170, 0, 32, vcc
	v_ldexp_f32 v168, v168, v170
	v_log_f32_e32 v168, v168
	v_cndmask_b32_e64 v170, 0, v131, s[0:1]
	v_sub_f32_e32 v162, v162, v170
	v_sub_f32_e32 v170, 1.0, v151
	v_cmp_gt_f32_e64 s[0:1], s14, v170
	v_mul_f32_e32 v163, 0x3f317217, v168
	v_fma_f32 v163, v168, s9, -v163
	v_cndmask_b32_e64 v173, 0, 32, s[0:1]
	v_ldexp_f32 v170, v170, v173
	v_fmac_f32_e32 v163, 0x3377d1cf, v168
	v_log_f32_e32 v170, v170
	v_fmac_f32_e32 v163, 0x3f317217, v168
	v_cmp_lt_f32_e64 s[2:3], |v168|, s15
	v_sub_f32_e32 v173, 1.0, v149
	v_cndmask_b32_e64 v149, v149, 0, s[4:5]
	v_cndmask_b32_e64 v163, v168, v163, s[2:3]
	v_cndmask_b32_e32 v168, 0, v131, vcc
	v_cmp_gt_f32_e32 vcc, s14, v173
	v_sub_f32_e32 v163, v163, v168
	v_mul_f32_e32 v168, 0x3f317217, v170
	v_cndmask_b32_e64 v174, 0, 32, vcc
	v_ldexp_f32 v173, v173, v174
	v_fma_f32 v168, v170, s9, -v168
	v_log_f32_e32 v173, v173
	v_fmac_f32_e32 v168, 0x3377d1cf, v170
	v_fmac_f32_e32 v168, 0x3f317217, v170
	v_cmp_lt_f32_e64 s[2:3], |v170|, s15
	v_cndmask_b32_e64 v151, v151, 0, s[4:5]
	s_nop 0
	v_cndmask_b32_e64 v168, v170, v168, s[2:3]
	v_cndmask_b32_e64 v170, 0, v131, s[0:1]
	v_sub_f32_e32 v168, v168, v170
	v_mul_f32_e32 v170, 0x3f317217, v173
	v_fma_f32 v170, v173, s9, -v170
	v_fmac_f32_e32 v170, 0x3377d1cf, v173
	v_fmac_f32_e32 v170, 0x3f317217, v173
	v_cmp_lt_f32_e64 s[0:1], |v173|, s15
	v_cvt_pk_bf16_f32 v171, v169, v171
	v_cvt_pk_bf16_f32 v172, v161, v172
	v_cndmask_b32_e64 v170, v173, v170, s[0:1]
	v_cndmask_b32_e32 v173, 0, v131, vcc
	v_sub_f32_e32 v170, v170, v173
	v_cvt_pk_bf16_f32 v148, v150, v148
	v_cvt_pk_bf16_f32 v149, v151, v149
	v_mov_b32_e32 v151, v149
	v_mov_b32_e32 v150, v148
	v_mov_b32_e32 v149, v172
	v_mov_b32_e32 v148, v171
	global_store_dwordx4 v[138:139], v[148:151], off offset:256
	v_cndmask_b32_e64 v138, v166, 0, s[4:5]
	v_bfe_u32 v139, v138, 16, 1
	v_add3_u32 v138, v138, v139, s16
	v_cndmask_b32_e64 v139, v164, 0, s[4:5]
	v_bfe_u32 v148, v139, 16, 1
	v_lshrrev_b32_e32 v138, 16, v138
	v_add3_u32 v139, v139, v148, s16
	v_and_or_b32 v148, v139, s17, v138
	v_cndmask_b32_e64 v138, v165, 0, s[4:5]
	v_bfe_u32 v139, v138, 16, 1
	v_add3_u32 v138, v138, v139, s16
	v_cndmask_b32_e64 v139, v167, 0, s[4:5]
	v_bfe_u32 v149, v139, 16, 1
	v_lshrrev_b32_e32 v138, 16, v138
	v_add3_u32 v139, v139, v149, s16
	v_and_or_b32 v149, v139, s17, v138
	v_cndmask_b32_e64 v138, v162, 0, s[4:5]
	v_bfe_u32 v139, v138, 16, 1
	v_add3_u32 v138, v138, v139, s16
	v_cndmask_b32_e64 v139, v163, 0, s[4:5]
	v_bfe_u32 v150, v139, 16, 1
	v_lshrrev_b32_e32 v138, 16, v138
	v_add3_u32 v139, v139, v150, s16
	v_and_or_b32 v150, v139, s17, v138
	v_cndmask_b32_e64 v138, v168, 0, s[4:5]
	v_bfe_u32 v139, v138, 16, 1
	v_add3_u32 v138, v138, v139, s16
	v_cndmask_b32_e64 v139, v170, 0, s[4:5]
	v_bfe_u32 v151, v139, 16, 1
	v_lshrrev_b32_e32 v138, 16, v138
	v_add3_u32 v139, v139, v151, s16
	v_and_or_b32 v151, v139, s17, v138
	global_store_dwordx4 v[136:137], v[148:151], off offset:256
	v_mul_f32_e32 v161, 0x3fb8aa3b, v106
	v_exp_f32_e32 v162, v161
	v_mul_f32_e32 v149, 0x3fb8aa3b, v111
	v_mul_f32_e32 v148, 0x3fb8aa3b, v110
	v_exp_f32_e32 v150, v149
	v_mul_f32_e32 v149, 0x3fb8aa3b, v112
	v_exp_f32_e32 v148, v148
	v_exp_f32_e32 v149, v149
	v_mul_f32_e32 v161, 0x3fb8aa3b, v107
	v_or_b32_e32 v136, 16, v130
	v_exp_f32_e32 v164, v161
	v_pk_add_f32 v[148:149], v[148:149], 1.0 op_sel_hi:[1,0]
	v_mul_f32_e32 v161, 0x3fb8aa3b, v108
	v_div_scale_f32 v165, s[4:5], v149, v149, v157
	v_rcp_f32_e32 v166, v165
	v_cmp_gt_i32_e32 vcc, s20, v136
	v_exp_f32_e32 v163, v161
	v_mul_f32_e32 v151, 0x3fb8aa3b, v113
	v_fma_f32 v161, -v165, v166, 1.0
	v_cndmask_b32_e64 v137, v154, 0, vcc
	v_fmac_f32_e32 v166, v161, v166
	v_div_scale_f32 v161, vcc, v157, v149, v157
	v_mul_f32_e32 v167, v161, v166
	v_fma_f32 v168, -v165, v167, v161
	v_fmac_f32_e32 v167, v168, v166
	v_rcp_f32_e32 v169, v148
	v_fma_f32 v161, -v165, v167, v161
	v_div_fmas_f32 v161, v161, v166, v167
	v_exp_f32_e32 v151, v151
	v_mul_f32_e32 v166, v156, v169
	v_sub_f32_e32 v148, 1.0, v166
	v_cmp_gt_f32_e64 s[4:5], s14, v148
	v_div_fixup_f32 v161, v161, v149, v157
	v_add_u32_e32 v137, v137, v136
	v_cndmask_b32_e64 v165, 0, 32, s[4:5]
	v_ldexp_f32 v148, v148, v165
	v_log_f32_e32 v167, v148
	v_mul_f32_e32 v148, 0x3fb8aa3b, v109
	v_exp_f32_e32 v165, v148
	v_cmp_gt_i32_e64 s[0:1], s19, v136
	v_mul_f32_e32 v148, 0x3f317217, v167
	v_fma_f32 v168, v167, s9, -v148
	v_pk_add_f32 v[148:149], v[150:151], 1.0 op_sel_hi:[1,0]
	v_fmac_f32_e32 v168, 0x3377d1cf, v167
	v_rcp_f32_e32 v151, v149
	v_fmac_f32_e32 v168, 0x3f317217, v167
	v_cmp_lt_f32_e64 vcc, |v167|, s15
	v_cmp_gt_i32_e64 s[2:3], s18, v137
	v_ashrrev_i32_e32 v137, 31, v136
	v_cndmask_b32_e32 v167, v167, v168, vcc
	v_rcp_f32_e32 v171, v148
	v_mul_f32_e32 v150, v158, v151
	v_mul_f32_e32 v151, v155, v171
	v_sub_f32_e32 v148, 1.0, v151
	v_cmp_gt_f32_e32 vcc, s14, v148
	v_lshlrev_b64 v[136:137], 10, v[136:137]
	v_lshl_add_u64 v[138:139], v[132:133], 0, v[136:137]
	v_cndmask_b32_e64 v168, 0, 32, vcc
	v_ldexp_f32 v148, v148, v168
	v_log_f32_e32 v148, v148
	v_cndmask_b32_e64 v168, 0, v131, s[4:5]
	v_sub_f32_e32 v167, v167, v168
	v_sub_f32_e32 v168, 1.0, v161
	v_mul_f32_e32 v149, 0x3f317217, v148
	v_fma_f32 v149, v148, s9, -v149
	v_cmp_gt_f32_e64 s[4:5], s14, v168
	v_fmac_f32_e32 v149, 0x3377d1cf, v148
	v_fmac_f32_e32 v149, 0x3f317217, v148
	v_cndmask_b32_e64 v169, 0, 32, s[4:5]
	v_ldexp_f32 v168, v168, v169
	v_cmp_lt_f32_e64 s[6:7], |v148|, s15
	v_log_f32_e32 v168, v168
	v_lshl_add_u64 v[136:137], v[134:135], 0, v[136:137]
	v_cndmask_b32_e64 v148, v148, v149, s[6:7]
	v_cndmask_b32_e32 v149, 0, v131, vcc
	v_sub_f32_e32 v169, v148, v149
	v_sub_f32_e32 v149, 1.0, v150
	v_cmp_gt_f32_e32 vcc, s14, v149
	v_mul_f32_e32 v148, 0x3f317217, v168
	v_fma_f32 v148, v168, s9, -v148
	v_cndmask_b32_e64 v170, 0, 32, vcc
	v_ldexp_f32 v149, v149, v170
	v_log_f32_e32 v149, v149
	v_fmac_f32_e32 v148, 0x3377d1cf, v168
	v_fmac_f32_e32 v148, 0x3f317217, v168
	v_cmp_lt_f32_e64 s[6:7], |v168|, s15
	s_nop 1
	v_cndmask_b32_e64 v148, v168, v148, s[6:7]
	v_cndmask_b32_e64 v168, 0, v131, s[4:5]
	v_sub_f32_e32 v168, v148, v168
	v_mul_f32_e32 v148, 0x3f317217, v149
	v_fma_f32 v148, v149, s9, -v148
	v_fmac_f32_e32 v148, 0x3377d1cf, v149
	v_fmac_f32_e32 v148, 0x3f317217, v149
	v_cmp_lt_f32_e64 s[4:5], |v149|, s15
	s_nop 1
	v_cndmask_b32_e64 v148, v149, v148, s[4:5]
	v_cndmask_b32_e32 v149, 0, v131, vcc
	v_sub_f32_e32 v170, v148, v149
	v_pk_add_f32 v[148:149], v[162:163], 1.0 op_sel_hi:[1,0]
	s_nop 0
	v_rcp_f32_e32 v163, v149
	s_and_b64 s[4:5], s[0:1], s[2:3]
	v_cndmask_b32_e64 v151, v151, 0, s[4:5]
	v_cndmask_b32_e64 v150, v150, 0, s[4:5]
	v_rcp_f32_e32 v174, v148
	v_mul_f32_e32 v162, v152, v163
	v_mul_f32_e32 v163, v159, v174
	v_sub_f32_e32 v148, 1.0, v163
	v_cmp_gt_f32_e64 s[0:1], s14, v148
	v_cndmask_b32_e64 v161, v161, 0, s[4:5]
	v_cndmask_b32_e64 v166, v166, 0, s[4:5]
	v_cndmask_b32_e64 v171, 0, 32, s[0:1]
	v_ldexp_f32 v148, v148, v171
	v_log_f32_e32 v171, v148
	v_cndmask_b32_e64 v163, v163, 0, s[4:5]
	v_bfe_u32 v176, v151, 16, 1
	v_add3_u32 v176, v151, v176, s16
	v_mul_f32_e32 v148, 0x3f317217, v171
	v_fma_f32 v172, v171, s9, -v148
	v_pk_add_f32 v[148:149], v[164:165], 1.0 op_sel_hi:[1,0]
	v_fmac_f32_e32 v172, 0x3377d1cf, v171
	v_rcp_f32_e32 v165, v149
	v_fmac_f32_e32 v172, 0x3f317217, v171
	v_cmp_lt_f32_e64 vcc, |v171|, s15
	v_bfe_u32 v151, v161, 16, 1
	v_add3_u32 v151, v161, v151, s16
	v_cndmask_b32_e32 v171, v171, v172, vcc
	v_rcp_f32_e32 v175, v148
	v_mul_f32_e32 v149, v153, v165
	v_mul_f32_e32 v148, v160, v175
	v_sub_f32_e32 v165, 1.0, v148
	v_cmp_gt_f32_e32 vcc, s14, v165
	v_cndmask_b32_e64 v148, v148, 0, s[4:5]
	v_bfe_u32 v175, v150, 16, 1
	v_cndmask_b32_e64 v172, 0, 32, vcc
	v_ldexp_f32 v165, v165, v172
	v_log_f32_e32 v165, v165
	v_cndmask_b32_e64 v172, 0, v131, s[0:1]
	v_sub_f32_e32 v171, v171, v172
	v_sub_f32_e32 v172, 1.0, v162
	v_cmp_gt_f32_e64 s[0:1], s14, v172
	v_mul_f32_e32 v164, 0x3f317217, v165
	v_fma_f32 v164, v165, s9, -v164
	v_cndmask_b32_e64 v173, 0, 32, s[0:1]
	v_ldexp_f32 v172, v172, v173
	v_fmac_f32_e32 v164, 0x3377d1cf, v165
	v_log_f32_e32 v172, v172
	v_fmac_f32_e32 v164, 0x3f317217, v165
	v_cmp_lt_f32_e64 s[2:3], |v165|, s15
	v_sub_f32_e32 v173, 1.0, v149
	v_cndmask_b32_e64 v149, v149, 0, s[4:5]
	v_cndmask_b32_e64 v164, v165, v164, s[2:3]
	v_cndmask_b32_e32 v165, 0, v131, vcc
	v_cmp_gt_f32_e32 vcc, s14, v173
	v_sub_f32_e32 v164, v164, v165
	v_mul_f32_e32 v165, 0x3f317217, v172
	v_cndmask_b32_e64 v174, 0, 32, vcc
	v_ldexp_f32 v173, v173, v174
	v_fma_f32 v165, v172, s9, -v165
	v_log_f32_e32 v173, v173
	v_fmac_f32_e32 v165, 0x3377d1cf, v172
	v_fmac_f32_e32 v165, 0x3f317217, v172
	v_cmp_lt_f32_e64 s[2:3], |v172|, s15
	v_cndmask_b32_e64 v162, v162, 0, s[4:5]
	s_nop 0
	v_cndmask_b32_e64 v165, v172, v165, s[2:3]
	v_cndmask_b32_e64 v172, 0, v131, s[0:1]
	v_sub_f32_e32 v165, v165, v172
	v_mul_f32_e32 v172, 0x3f317217, v173
	v_fma_f32 v172, v173, s9, -v172
	v_fmac_f32_e32 v172, 0x3377d1cf, v173
	v_fmac_f32_e32 v172, 0x3f317217, v173
	v_cmp_lt_f32_e64 s[0:1], |v173|, s15
	v_add3_u32 v175, v150, v175, s16
	v_cvt_pk_bf16_f32 v148, v163, v148
	v_cndmask_b32_e64 v172, v173, v172, s[0:1]
	v_cndmask_b32_e32 v173, 0, v131, vcc
	v_sub_f32_e32 v172, v172, v173
	v_cvt_pk_bf16_f32 v149, v162, v149
	v_bfe_u32 v150, v166, 16, 1
	v_add3_u32 v150, v166, v150, s16
	v_lshrrev_b32_e32 v161, 16, v150
	v_lshrrev_b32_e32 v166, 16, v151
	v_mov_b32_e32 v151, v149
	v_mov_b32_e32 v150, v148
	v_and_or_b32 v149, v175, s17, v166
	v_and_or_b32 v148, v176, s17, v161
	global_store_dwordx4 v[138:139], v[148:151], off
	s_nop 1
	v_cndmask_b32_e64 v148, v167, 0, s[4:5]
	v_bfe_u32 v149, v148, 16, 1
	v_add3_u32 v148, v148, v149, s16
	v_cndmask_b32_e64 v149, v169, 0, s[4:5]
	v_bfe_u32 v150, v149, 16, 1
	v_lshrrev_b32_e32 v148, 16, v148
	v_add3_u32 v149, v149, v150, s16
	v_and_or_b32 v148, v149, s17, v148
	v_cndmask_b32_e64 v149, v168, 0, s[4:5]
	v_bfe_u32 v150, v149, 16, 1
	v_add3_u32 v149, v149, v150, s16
	v_cndmask_b32_e64 v150, v170, 0, s[4:5]
	v_bfe_u32 v151, v150, 16, 1
	v_lshrrev_b32_e32 v149, 16, v149
	v_add3_u32 v150, v150, v151, s16
	v_and_or_b32 v149, v150, s17, v149
	v_cndmask_b32_e64 v150, v171, 0, s[4:5]
	v_bfe_u32 v151, v150, 16, 1
	v_add3_u32 v150, v150, v151, s16
	v_cndmask_b32_e64 v151, v164, 0, s[4:5]
	v_bfe_u32 v161, v151, 16, 1
	v_lshrrev_b32_e32 v150, 16, v150
	v_add3_u32 v151, v151, v161, s16
	v_and_or_b32 v150, v151, s17, v150
	v_cndmask_b32_e64 v151, v165, 0, s[4:5]
	v_bfe_u32 v161, v151, 16, 1
	v_add3_u32 v151, v151, v161, s16
	v_cndmask_b32_e64 v161, v172, 0, s[4:5]
	v_bfe_u32 v162, v161, 16, 1
	v_lshrrev_b32_e32 v151, 16, v151
	v_add3_u32 v161, v161, v162, s16
	v_and_or_b32 v151, v161, s17, v151
	global_store_dwordx4 v[136:137], v[148:151], off
	v_mul_f32_e32 v161, 0x3fb8aa3b, v98
	v_exp_f32_e32 v162, v161
	v_mul_f32_e32 v149, 0x3fb8aa3b, v103
	v_mul_f32_e32 v148, 0x3fb8aa3b, v102
	v_exp_f32_e32 v150, v149
	v_mul_f32_e32 v149, 0x3fb8aa3b, v104
	v_exp_f32_e32 v148, v148
	v_exp_f32_e32 v149, v149
	v_mul_f32_e32 v161, 0x3fb8aa3b, v99
	v_exp_f32_e32 v164, v161
	v_mul_f32_e32 v161, 0x3fb8aa3b, v100
	v_pk_add_f32 v[148:149], v[148:149], 1.0 op_sel_hi:[1,0]
	v_exp_f32_e32 v163, v161
	v_rcp_f32_e32 v166, v149
	v_mul_f32_e32 v151, 0x3fb8aa3b, v105
	v_exp_f32_e32 v151, v151
	v_rcp_f32_e32 v169, v148
	v_mul_f32_e32 v161, v144, v166
	v_mul_f32_e32 v166, v146, v169
	v_sub_f32_e32 v148, 1.0, v166
	v_cmp_gt_f32_e64 s[0:1], s14, v148
	v_cndmask_b32_e64 v166, v166, 0, s[4:5]
	s_nop 0
	v_cndmask_b32_e64 v165, 0, 32, s[0:1]
	v_ldexp_f32 v148, v148, v165
	v_log_f32_e32 v167, v148
	v_mul_f32_e32 v148, 0x3fb8aa3b, v101
	v_exp_f32_e32 v165, v148
	v_mul_f32_e32 v148, 0x3f317217, v167
	v_fma_f32 v168, v167, s9, -v148
	v_pk_add_f32 v[148:149], v[150:151], 1.0 op_sel_hi:[1,0]
	v_fmac_f32_e32 v168, 0x3377d1cf, v167
	v_rcp_f32_e32 v151, v149
	v_fmac_f32_e32 v168, 0x3f317217, v167
	v_cmp_lt_f32_e64 vcc, |v167|, s15
	s_nop 1
	v_cndmask_b32_e32 v167, v167, v168, vcc
	v_rcp_f32_e32 v171, v148
	v_mul_f32_e32 v150, v145, v151
	v_mul_f32_e32 v151, v147, v171
	v_sub_f32_e32 v148, 1.0, v151
	v_cmp_gt_f32_e32 vcc, s14, v148
	v_cndmask_b32_e64 v151, v151, 0, s[4:5]
	v_bfe_u32 v176, v151, 16, 1
	v_cndmask_b32_e64 v168, 0, 32, vcc
	v_ldexp_f32 v148, v148, v168
	v_log_f32_e32 v148, v148
	v_cndmask_b32_e64 v168, 0, v131, s[0:1]
	v_sub_f32_e32 v167, v167, v168
	v_sub_f32_e32 v168, 1.0, v161
	v_mul_f32_e32 v149, 0x3f317217, v148
	v_fma_f32 v149, v148, s9, -v149
	v_cmp_gt_f32_e64 s[0:1], s14, v168
	v_fmac_f32_e32 v149, 0x3377d1cf, v148
	v_fmac_f32_e32 v149, 0x3f317217, v148
	v_cndmask_b32_e64 v169, 0, 32, s[0:1]
	v_ldexp_f32 v168, v168, v169
	v_cmp_lt_f32_e64 s[2:3], |v148|, s15
	v_log_f32_e32 v168, v168
	v_cndmask_b32_e64 v161, v161, 0, s[4:5]
	v_cndmask_b32_e64 v148, v148, v149, s[2:3]
	v_cndmask_b32_e32 v149, 0, v131, vcc
	v_sub_f32_e32 v169, v148, v149
	v_sub_f32_e32 v149, 1.0, v150
	v_cmp_gt_f32_e32 vcc, s14, v149
	v_mul_f32_e32 v148, 0x3f317217, v168
	v_fma_f32 v148, v168, s9, -v148
	v_cndmask_b32_e64 v170, 0, 32, vcc
	v_ldexp_f32 v149, v149, v170
	v_log_f32_e32 v149, v149
	v_fmac_f32_e32 v148, 0x3377d1cf, v168
	v_fmac_f32_e32 v148, 0x3f317217, v168
	v_cmp_lt_f32_e64 s[2:3], |v168|, s15
	v_cndmask_b32_e32 v171, 0, v131, vcc
	v_cndmask_b32_e64 v150, v150, 0, s[4:5]
	v_cndmask_b32_e64 v148, v168, v148, s[2:3]
	v_cndmask_b32_e64 v168, 0, v131, s[0:1]
	v_sub_f32_e32 v168, v148, v168
	v_mul_f32_e32 v148, 0x3f317217, v149
	v_fma_f32 v148, v149, s9, -v148
	v_fmac_f32_e32 v148, 0x3377d1cf, v149
	v_fmac_f32_e32 v148, 0x3f317217, v149
	v_cmp_lt_f32_e64 s[0:1], |v149|, s15
	v_add3_u32 v176, v151, v176, s16
	v_bfe_u32 v151, v161, 16, 1
	v_cndmask_b32_e64 v170, v149, v148, s[0:1]
	v_pk_add_f32 v[148:149], v[162:163], 1.0 op_sel_hi:[1,0]
	v_sub_f32_e32 v170, v170, v171
	v_rcp_f32_e32 v163, v149
	v_add3_u32 v151, v161, v151, s16
	v_rcp_f32_e32 v174, v148
	v_mul_f32_e32 v162, v140, v163
	v_mul_f32_e32 v163, v142, v174
	v_sub_f32_e32 v148, 1.0, v163
	v_cmp_gt_f32_e64 s[0:1], s14, v148
	v_cndmask_b32_e64 v163, v163, 0, s[4:5]
	s_nop 0
	v_cndmask_b32_e64 v171, 0, 32, s[0:1]
	v_ldexp_f32 v148, v148, v171
	v_log_f32_e32 v171, v148
	s_nop 0
	v_mul_f32_e32 v148, 0x3f317217, v171
	v_fma_f32 v172, v171, s9, -v148
	v_pk_add_f32 v[148:149], v[164:165], 1.0 op_sel_hi:[1,0]
	v_fmac_f32_e32 v172, 0x3377d1cf, v171
	v_rcp_f32_e32 v165, v149
	v_fmac_f32_e32 v172, 0x3f317217, v171
	v_cmp_lt_f32_e64 vcc, |v171|, s15
	s_nop 1
	v_cndmask_b32_e32 v171, v171, v172, vcc
	v_rcp_f32_e32 v175, v148
	v_mul_f32_e32 v149, v141, v165
	v_mul_f32_e32 v148, v143, v175
	v_sub_f32_e32 v165, 1.0, v148
	v_cmp_gt_f32_e32 vcc, s14, v165
	v_cndmask_b32_e64 v148, v148, 0, s[4:5]
	v_bfe_u32 v175, v150, 16, 1
	v_cndmask_b32_e64 v172, 0, 32, vcc
	v_ldexp_f32 v165, v165, v172
	v_log_f32_e32 v165, v165
	v_cndmask_b32_e64 v172, 0, v131, s[0:1]
	v_sub_f32_e32 v171, v171, v172
	v_sub_f32_e32 v172, 1.0, v162
	v_cmp_gt_f32_e64 s[0:1], s14, v172
	v_mul_f32_e32 v164, 0x3f317217, v165
	v_fma_f32 v164, v165, s9, -v164
	v_cndmask_b32_e64 v173, 0, 32, s[0:1]
	v_ldexp_f32 v172, v172, v173
	v_fmac_f32_e32 v164, 0x3377d1cf, v165
	v_log_f32_e32 v172, v172
	v_fmac_f32_e32 v164, 0x3f317217, v165
	v_cmp_lt_f32_e64 s[2:3], |v165|, s15
	v_sub_f32_e32 v173, 1.0, v149
	v_cndmask_b32_e64 v149, v149, 0, s[4:5]
	v_cndmask_b32_e64 v164, v165, v164, s[2:3]
	v_cndmask_b32_e32 v165, 0, v131, vcc
	v_cmp_gt_f32_e32 vcc, s14, v173
	v_sub_f32_e32 v164, v164, v165
	v_mul_f32_e32 v165, 0x3f317217, v172
	v_cndmask_b32_e64 v174, 0, 32, vcc
	v_ldexp_f32 v173, v173, v174
	v_fma_f32 v165, v172, s9, -v165
	v_log_f32_e32 v173, v173
	v_fmac_f32_e32 v165, 0x3377d1cf, v172
	v_fmac_f32_e32 v165, 0x3f317217, v172
	v_cmp_lt_f32_e64 s[2:3], |v172|, s15
	v_cndmask_b32_e64 v162, v162, 0, s[4:5]
	s_nop 0
	v_cndmask_b32_e64 v165, v172, v165, s[2:3]
	v_cndmask_b32_e64 v172, 0, v131, s[0:1]
	v_sub_f32_e32 v165, v165, v172
	v_mul_f32_e32 v172, 0x3f317217, v173
	v_fma_f32 v172, v173, s9, -v172
	v_fmac_f32_e32 v172, 0x3377d1cf, v173
	v_fmac_f32_e32 v172, 0x3f317217, v173
	v_cmp_lt_f32_e64 s[0:1], |v173|, s15
	v_add3_u32 v175, v150, v175, s16
	v_cvt_pk_bf16_f32 v148, v163, v148
	v_cndmask_b32_e64 v172, v173, v172, s[0:1]
	v_cndmask_b32_e32 v173, 0, v131, vcc
	v_sub_f32_e32 v172, v172, v173
	v_cvt_pk_bf16_f32 v149, v162, v149
	v_bfe_u32 v150, v166, 16, 1
	v_add3_u32 v150, v166, v150, s16
	v_lshrrev_b32_e32 v161, 16, v150
	v_lshrrev_b32_e32 v166, 16, v151
	v_mov_b32_e32 v151, v149
	v_mov_b32_e32 v150, v148
	v_and_or_b32 v149, v175, s17, v166
	v_and_or_b32 v148, v176, s17, v161
	global_store_dwordx4 v[138:139], v[148:151], off offset:256
	v_cndmask_b32_e64 v138, v167, 0, s[4:5]
	v_bfe_u32 v139, v138, 16, 1
	v_add3_u32 v138, v138, v139, s16
	v_cndmask_b32_e64 v139, v169, 0, s[4:5]
	v_bfe_u32 v148, v139, 16, 1
	v_lshrrev_b32_e32 v138, 16, v138
	v_add3_u32 v139, v139, v148, s16
	v_and_or_b32 v148, v139, s17, v138
	v_cndmask_b32_e64 v138, v168, 0, s[4:5]
	v_bfe_u32 v139, v138, 16, 1
	v_add3_u32 v138, v138, v139, s16
	v_cndmask_b32_e64 v139, v170, 0, s[4:5]
	v_bfe_u32 v149, v139, 16, 1
	v_lshrrev_b32_e32 v138, 16, v138
	v_add3_u32 v139, v139, v149, s16
	v_and_or_b32 v149, v139, s17, v138
	v_cndmask_b32_e64 v138, v171, 0, s[4:5]
	v_bfe_u32 v139, v138, 16, 1
	v_add3_u32 v138, v138, v139, s16
	v_cndmask_b32_e64 v139, v164, 0, s[4:5]
	v_bfe_u32 v150, v139, 16, 1
	v_lshrrev_b32_e32 v138, 16, v138
	v_add3_u32 v139, v139, v150, s16
	v_and_or_b32 v150, v139, s17, v138
	v_cndmask_b32_e64 v138, v165, 0, s[4:5]
	v_bfe_u32 v139, v138, 16, 1
	v_add3_u32 v138, v138, v139, s16
	v_cndmask_b32_e64 v139, v172, 0, s[4:5]
	v_bfe_u32 v151, v139, 16, 1
	v_lshrrev_b32_e32 v138, 16, v138
	v_add3_u32 v139, v139, v151, s16
	v_and_or_b32 v151, v139, s17, v138
	global_store_dwordx4 v[136:137], v[148:151], off offset:256
	v_mul_f32_e32 v161, 0x3fb8aa3b, v90
	v_exp_f32_e32 v162, v161
	v_mul_f32_e32 v149, 0x3fb8aa3b, v95
	v_mul_f32_e32 v148, 0x3fb8aa3b, v94
	v_exp_f32_e32 v150, v149
	v_mul_f32_e32 v149, 0x3fb8aa3b, v96
	v_exp_f32_e32 v148, v148
	v_exp_f32_e32 v149, v149
	v_mul_f32_e32 v161, 0x3fb8aa3b, v91
	v_or_b32_e32 v136, 32, v130
	v_exp_f32_e32 v164, v161
	v_pk_add_f32 v[148:149], v[148:149], 1.0 op_sel_hi:[1,0]
	v_mul_f32_e32 v161, 0x3fb8aa3b, v92
	v_div_scale_f32 v165, s[4:5], v149, v149, v157
	v_rcp_f32_e32 v166, v165
	v_cmp_gt_i32_e32 vcc, s20, v136
	v_exp_f32_e32 v163, v161
	v_mul_f32_e32 v151, 0x3fb8aa3b, v97
	v_fma_f32 v161, -v165, v166, 1.0
	v_cndmask_b32_e64 v137, v154, 0, vcc
	v_fmac_f32_e32 v166, v161, v166
	v_div_scale_f32 v161, vcc, v157, v149, v157
	v_mul_f32_e32 v167, v161, v166
	v_fma_f32 v168, -v165, v167, v161
	v_fmac_f32_e32 v167, v168, v166
	v_rcp_f32_e32 v169, v148
	v_fma_f32 v161, -v165, v167, v161
	v_div_fmas_f32 v161, v161, v166, v167
	v_exp_f32_e32 v151, v151
	v_mul_f32_e32 v166, v156, v169
	v_sub_f32_e32 v148, 1.0, v166
	v_cmp_gt_f32_e64 s[4:5], s14, v148
	v_div_fixup_f32 v161, v161, v149, v157
	v_add_u32_e32 v137, v137, v136
	v_cndmask_b32_e64 v165, 0, 32, s[4:5]
	v_ldexp_f32 v148, v148, v165
	v_log_f32_e32 v167, v148
	v_mul_f32_e32 v148, 0x3fb8aa3b, v93
	v_exp_f32_e32 v165, v148
	v_cmp_gt_i32_e64 s[0:1], s19, v136
	v_mul_f32_e32 v148, 0x3f317217, v167
	v_fma_f32 v168, v167, s9, -v148
	v_pk_add_f32 v[148:149], v[150:151], 1.0 op_sel_hi:[1,0]
	v_fmac_f32_e32 v168, 0x3377d1cf, v167
	v_rcp_f32_e32 v151, v149
	v_fmac_f32_e32 v168, 0x3f317217, v167
	v_cmp_lt_f32_e64 vcc, |v167|, s15
	v_cmp_gt_i32_e64 s[2:3], s18, v137
	v_ashrrev_i32_e32 v137, 31, v136
	v_cndmask_b32_e32 v167, v167, v168, vcc
	v_rcp_f32_e32 v171, v148
	v_mul_f32_e32 v150, v158, v151
	v_mul_f32_e32 v151, v155, v171
	v_sub_f32_e32 v148, 1.0, v151
	v_cmp_gt_f32_e32 vcc, s14, v148
	v_lshlrev_b64 v[136:137], 10, v[136:137]
	v_lshl_add_u64 v[138:139], v[132:133], 0, v[136:137]
	v_cndmask_b32_e64 v168, 0, 32, vcc
	v_ldexp_f32 v148, v148, v168
	v_log_f32_e32 v148, v148
	v_cndmask_b32_e64 v168, 0, v131, s[4:5]
	v_sub_f32_e32 v167, v167, v168
	v_sub_f32_e32 v168, 1.0, v161
	v_mul_f32_e32 v149, 0x3f317217, v148
	v_fma_f32 v149, v148, s9, -v149
	v_cmp_gt_f32_e64 s[4:5], s14, v168
	v_fmac_f32_e32 v149, 0x3377d1cf, v148
	v_fmac_f32_e32 v149, 0x3f317217, v148
	v_cndmask_b32_e64 v169, 0, 32, s[4:5]
	v_ldexp_f32 v168, v168, v169
	v_cmp_lt_f32_e64 s[6:7], |v148|, s15
	v_log_f32_e32 v168, v168
	v_lshl_add_u64 v[136:137], v[134:135], 0, v[136:137]
	v_cndmask_b32_e64 v148, v148, v149, s[6:7]
	v_cndmask_b32_e32 v149, 0, v131, vcc
	v_sub_f32_e32 v169, v148, v149
	v_sub_f32_e32 v149, 1.0, v150
	v_cmp_gt_f32_e32 vcc, s14, v149
	v_mul_f32_e32 v148, 0x3f317217, v168
	v_fma_f32 v148, v168, s9, -v148
	v_cndmask_b32_e64 v170, 0, 32, vcc
	v_ldexp_f32 v149, v149, v170
	v_log_f32_e32 v149, v149
	v_fmac_f32_e32 v148, 0x3377d1cf, v168
	v_fmac_f32_e32 v148, 0x3f317217, v168
	v_cmp_lt_f32_e64 s[6:7], |v168|, s15
	s_nop 1
	v_cndmask_b32_e64 v148, v168, v148, s[6:7]
	v_cndmask_b32_e64 v168, 0, v131, s[4:5]
	v_sub_f32_e32 v168, v148, v168
	v_mul_f32_e32 v148, 0x3f317217, v149
	v_fma_f32 v148, v149, s9, -v148
	v_fmac_f32_e32 v148, 0x3377d1cf, v149
	v_fmac_f32_e32 v148, 0x3f317217, v149
	v_cmp_lt_f32_e64 s[4:5], |v149|, s15
	s_nop 1
	v_cndmask_b32_e64 v148, v149, v148, s[4:5]
	v_cndmask_b32_e32 v149, 0, v131, vcc
	v_sub_f32_e32 v170, v148, v149
	v_pk_add_f32 v[148:149], v[162:163], 1.0 op_sel_hi:[1,0]
	s_nop 0
	v_rcp_f32_e32 v163, v149
	s_and_b64 s[4:5], s[0:1], s[2:3]
	v_cndmask_b32_e64 v151, v151, 0, s[4:5]
	v_cndmask_b32_e64 v150, v150, 0, s[4:5]
	v_rcp_f32_e32 v174, v148
	v_mul_f32_e32 v162, v152, v163
	v_mul_f32_e32 v163, v159, v174
	v_sub_f32_e32 v148, 1.0, v163
	v_cmp_gt_f32_e64 s[0:1], s14, v148
	v_cndmask_b32_e64 v161, v161, 0, s[4:5]
	v_cndmask_b32_e64 v166, v166, 0, s[4:5]
	v_cndmask_b32_e64 v171, 0, 32, s[0:1]
	v_ldexp_f32 v148, v148, v171
	v_log_f32_e32 v171, v148
	v_cndmask_b32_e64 v163, v163, 0, s[4:5]
	v_bfe_u32 v176, v151, 16, 1
	v_add3_u32 v176, v151, v176, s16
	v_mul_f32_e32 v148, 0x3f317217, v171
	v_fma_f32 v172, v171, s9, -v148
	v_pk_add_f32 v[148:149], v[164:165], 1.0 op_sel_hi:[1,0]
	v_fmac_f32_e32 v172, 0x3377d1cf, v171
	v_rcp_f32_e32 v165, v149
	v_fmac_f32_e32 v172, 0x3f317217, v171
	v_cmp_lt_f32_e64 vcc, |v171|, s15
	v_bfe_u32 v151, v161, 16, 1
	v_add3_u32 v151, v161, v151, s16
	v_cndmask_b32_e32 v171, v171, v172, vcc
	v_rcp_f32_e32 v175, v148
	v_mul_f32_e32 v149, v153, v165
	v_mul_f32_e32 v148, v160, v175
	v_sub_f32_e32 v165, 1.0, v148
	v_cmp_gt_f32_e32 vcc, s14, v165
	v_cndmask_b32_e64 v148, v148, 0, s[4:5]
	v_bfe_u32 v175, v150, 16, 1
	v_cndmask_b32_e64 v172, 0, 32, vcc
	v_ldexp_f32 v165, v165, v172
	v_log_f32_e32 v165, v165
	v_cndmask_b32_e64 v172, 0, v131, s[0:1]
	v_sub_f32_e32 v171, v171, v172
	v_sub_f32_e32 v172, 1.0, v162
	v_cmp_gt_f32_e64 s[0:1], s14, v172
	v_mul_f32_e32 v164, 0x3f317217, v165
	v_fma_f32 v164, v165, s9, -v164
	v_cndmask_b32_e64 v173, 0, 32, s[0:1]
	v_ldexp_f32 v172, v172, v173
	v_fmac_f32_e32 v164, 0x3377d1cf, v165
	v_log_f32_e32 v172, v172
	v_fmac_f32_e32 v164, 0x3f317217, v165
	v_cmp_lt_f32_e64 s[2:3], |v165|, s15
	v_sub_f32_e32 v173, 1.0, v149
	v_cndmask_b32_e64 v149, v149, 0, s[4:5]
	v_cndmask_b32_e64 v164, v165, v164, s[2:3]
	v_cndmask_b32_e32 v165, 0, v131, vcc
	v_cmp_gt_f32_e32 vcc, s14, v173
	v_sub_f32_e32 v164, v164, v165
	v_mul_f32_e32 v165, 0x3f317217, v172
	v_cndmask_b32_e64 v174, 0, 32, vcc
	v_ldexp_f32 v173, v173, v174
	v_fma_f32 v165, v172, s9, -v165
	v_log_f32_e32 v173, v173
	v_fmac_f32_e32 v165, 0x3377d1cf, v172
	v_fmac_f32_e32 v165, 0x3f317217, v172
	v_cmp_lt_f32_e64 s[2:3], |v172|, s15
	v_cndmask_b32_e64 v162, v162, 0, s[4:5]
	s_nop 0
	v_cndmask_b32_e64 v165, v172, v165, s[2:3]
	v_cndmask_b32_e64 v172, 0, v131, s[0:1]
	v_sub_f32_e32 v165, v165, v172
	v_mul_f32_e32 v172, 0x3f317217, v173
	v_fma_f32 v172, v173, s9, -v172
	v_fmac_f32_e32 v172, 0x3377d1cf, v173
	v_fmac_f32_e32 v172, 0x3f317217, v173
	v_cmp_lt_f32_e64 s[0:1], |v173|, s15
	v_add3_u32 v175, v150, v175, s16
	v_cvt_pk_bf16_f32 v148, v163, v148
	v_cndmask_b32_e64 v172, v173, v172, s[0:1]
	v_cndmask_b32_e32 v173, 0, v131, vcc
	v_sub_f32_e32 v172, v172, v173
	v_cvt_pk_bf16_f32 v149, v162, v149
	v_bfe_u32 v150, v166, 16, 1
	v_add3_u32 v150, v166, v150, s16
	v_lshrrev_b32_e32 v161, 16, v150
	v_lshrrev_b32_e32 v166, 16, v151
	v_mov_b32_e32 v151, v149
	v_mov_b32_e32 v150, v148
	v_and_or_b32 v149, v175, s17, v166
	v_and_or_b32 v148, v176, s17, v161
	global_store_dwordx4 v[138:139], v[148:151], off
	s_nop 1
	v_cndmask_b32_e64 v148, v167, 0, s[4:5]
	v_bfe_u32 v149, v148, 16, 1
	v_add3_u32 v148, v148, v149, s16
	v_cndmask_b32_e64 v149, v169, 0, s[4:5]
	v_bfe_u32 v150, v149, 16, 1
	v_lshrrev_b32_e32 v148, 16, v148
	v_add3_u32 v149, v149, v150, s16
	v_and_or_b32 v148, v149, s17, v148
	v_cndmask_b32_e64 v149, v168, 0, s[4:5]
	v_bfe_u32 v150, v149, 16, 1
	v_add3_u32 v149, v149, v150, s16
	v_cndmask_b32_e64 v150, v170, 0, s[4:5]
	v_bfe_u32 v151, v150, 16, 1
	v_lshrrev_b32_e32 v149, 16, v149
	v_add3_u32 v150, v150, v151, s16
	v_and_or_b32 v149, v150, s17, v149
	v_cndmask_b32_e64 v150, v171, 0, s[4:5]
	v_bfe_u32 v151, v150, 16, 1
	v_add3_u32 v150, v150, v151, s16
	v_cndmask_b32_e64 v151, v164, 0, s[4:5]
	v_bfe_u32 v161, v151, 16, 1
	v_lshrrev_b32_e32 v150, 16, v150
	v_add3_u32 v151, v151, v161, s16
	v_and_or_b32 v150, v151, s17, v150
	v_cndmask_b32_e64 v151, v165, 0, s[4:5]
	v_bfe_u32 v161, v151, 16, 1
	v_add3_u32 v151, v151, v161, s16
	v_cndmask_b32_e64 v161, v172, 0, s[4:5]
	v_bfe_u32 v162, v161, 16, 1
	v_lshrrev_b32_e32 v151, 16, v151
	v_add3_u32 v161, v161, v162, s16
	v_and_or_b32 v151, v161, s17, v151
	global_store_dwordx4 v[136:137], v[148:151], off
	v_mul_f32_e32 v161, 0x3fb8aa3b, v82
	v_exp_f32_e32 v162, v161
	v_mul_f32_e32 v149, 0x3fb8aa3b, v87
	v_mul_f32_e32 v148, 0x3fb8aa3b, v86
	v_exp_f32_e32 v150, v149
	v_mul_f32_e32 v149, 0x3fb8aa3b, v88
	v_exp_f32_e32 v148, v148
	v_exp_f32_e32 v149, v149
	v_mul_f32_e32 v161, 0x3fb8aa3b, v83
	v_exp_f32_e32 v164, v161
	v_mul_f32_e32 v161, 0x3fb8aa3b, v84
	v_pk_add_f32 v[148:149], v[148:149], 1.0 op_sel_hi:[1,0]
	v_exp_f32_e32 v163, v161
	v_rcp_f32_e32 v166, v149
	v_mul_f32_e32 v151, 0x3fb8aa3b, v89
	v_exp_f32_e32 v151, v151
	v_rcp_f32_e32 v169, v148
	v_mul_f32_e32 v161, v144, v166
	v_mul_f32_e32 v166, v146, v169
	v_sub_f32_e32 v148, 1.0, v166
	v_cmp_gt_f32_e64 s[0:1], s14, v148
	v_cndmask_b32_e64 v166, v166, 0, s[4:5]
	s_nop 0
	v_cndmask_b32_e64 v165, 0, 32, s[0:1]
	v_ldexp_f32 v148, v148, v165
	v_log_f32_e32 v167, v148
	v_mul_f32_e32 v148, 0x3fb8aa3b, v85
	v_exp_f32_e32 v165, v148
	v_mul_f32_e32 v148, 0x3f317217, v167
	v_fma_f32 v168, v167, s9, -v148
	v_pk_add_f32 v[148:149], v[150:151], 1.0 op_sel_hi:[1,0]
	v_fmac_f32_e32 v168, 0x3377d1cf, v167
	v_rcp_f32_e32 v151, v149
	v_fmac_f32_e32 v168, 0x3f317217, v167
	v_cmp_lt_f32_e64 vcc, |v167|, s15
	s_nop 1
	v_cndmask_b32_e32 v167, v167, v168, vcc
	v_rcp_f32_e32 v171, v148
	v_mul_f32_e32 v150, v145, v151
	v_mul_f32_e32 v151, v147, v171
	v_sub_f32_e32 v148, 1.0, v151
	v_cmp_gt_f32_e32 vcc, s14, v148
	v_cndmask_b32_e64 v151, v151, 0, s[4:5]
	v_bfe_u32 v176, v151, 16, 1
	v_cndmask_b32_e64 v168, 0, 32, vcc
	v_ldexp_f32 v148, v148, v168
	v_log_f32_e32 v148, v148
	v_cndmask_b32_e64 v168, 0, v131, s[0:1]
	v_sub_f32_e32 v167, v167, v168
	v_sub_f32_e32 v168, 1.0, v161
	v_mul_f32_e32 v149, 0x3f317217, v148
	v_fma_f32 v149, v148, s9, -v149
	v_cmp_gt_f32_e64 s[0:1], s14, v168
	v_fmac_f32_e32 v149, 0x3377d1cf, v148
	v_fmac_f32_e32 v149, 0x3f317217, v148
	v_cndmask_b32_e64 v169, 0, 32, s[0:1]
	v_ldexp_f32 v168, v168, v169
	v_cmp_lt_f32_e64 s[2:3], |v148|, s15
	v_log_f32_e32 v168, v168
	v_cndmask_b32_e64 v161, v161, 0, s[4:5]
	v_cndmask_b32_e64 v148, v148, v149, s[2:3]
	v_cndmask_b32_e32 v149, 0, v131, vcc
	v_sub_f32_e32 v169, v148, v149
	v_sub_f32_e32 v149, 1.0, v150
	v_cmp_gt_f32_e32 vcc, s14, v149
	v_mul_f32_e32 v148, 0x3f317217, v168
	v_fma_f32 v148, v168, s9, -v148
	v_cndmask_b32_e64 v170, 0, 32, vcc
	v_ldexp_f32 v149, v149, v170
	v_log_f32_e32 v149, v149
	v_fmac_f32_e32 v148, 0x3377d1cf, v168
	v_fmac_f32_e32 v148, 0x3f317217, v168
	v_cmp_lt_f32_e64 s[2:3], |v168|, s15
	v_cndmask_b32_e32 v171, 0, v131, vcc
	v_cndmask_b32_e64 v150, v150, 0, s[4:5]
	v_cndmask_b32_e64 v148, v168, v148, s[2:3]
	v_cndmask_b32_e64 v168, 0, v131, s[0:1]
	v_sub_f32_e32 v168, v148, v168
	v_mul_f32_e32 v148, 0x3f317217, v149
	v_fma_f32 v148, v149, s9, -v148
	v_fmac_f32_e32 v148, 0x3377d1cf, v149
	v_fmac_f32_e32 v148, 0x3f317217, v149
	v_cmp_lt_f32_e64 s[0:1], |v149|, s15
	v_add3_u32 v176, v151, v176, s16
	v_bfe_u32 v151, v161, 16, 1
	v_cndmask_b32_e64 v170, v149, v148, s[0:1]
	v_pk_add_f32 v[148:149], v[162:163], 1.0 op_sel_hi:[1,0]
	v_sub_f32_e32 v170, v170, v171
	v_rcp_f32_e32 v163, v149
	v_add3_u32 v151, v161, v151, s16
	v_rcp_f32_e32 v174, v148
	v_mul_f32_e32 v162, v140, v163
	v_mul_f32_e32 v163, v142, v174
	v_sub_f32_e32 v148, 1.0, v163
	v_cmp_gt_f32_e64 s[0:1], s14, v148
	v_cndmask_b32_e64 v163, v163, 0, s[4:5]
	s_nop 0
	v_cndmask_b32_e64 v171, 0, 32, s[0:1]
	v_ldexp_f32 v148, v148, v171
	v_log_f32_e32 v171, v148
	s_nop 0
	v_mul_f32_e32 v148, 0x3f317217, v171
	v_fma_f32 v172, v171, s9, -v148
	v_pk_add_f32 v[148:149], v[164:165], 1.0 op_sel_hi:[1,0]
	v_fmac_f32_e32 v172, 0x3377d1cf, v171
	v_rcp_f32_e32 v165, v149
	v_fmac_f32_e32 v172, 0x3f317217, v171
	v_cmp_lt_f32_e64 vcc, |v171|, s15
	s_nop 1
	v_cndmask_b32_e32 v171, v171, v172, vcc
	v_rcp_f32_e32 v175, v148
	v_mul_f32_e32 v149, v141, v165
	v_mul_f32_e32 v148, v143, v175
	v_sub_f32_e32 v165, 1.0, v148
	v_cmp_gt_f32_e32 vcc, s14, v165
	v_cndmask_b32_e64 v148, v148, 0, s[4:5]
	v_bfe_u32 v175, v150, 16, 1
	v_cndmask_b32_e64 v172, 0, 32, vcc
	v_ldexp_f32 v165, v165, v172
	v_log_f32_e32 v165, v165
	v_cndmask_b32_e64 v172, 0, v131, s[0:1]
	v_sub_f32_e32 v171, v171, v172
	v_sub_f32_e32 v172, 1.0, v162
	v_cmp_gt_f32_e64 s[0:1], s14, v172
	v_mul_f32_e32 v164, 0x3f317217, v165
	v_fma_f32 v164, v165, s9, -v164
	v_cndmask_b32_e64 v173, 0, 32, s[0:1]
	v_ldexp_f32 v172, v172, v173
	v_fmac_f32_e32 v164, 0x3377d1cf, v165
	v_log_f32_e32 v172, v172
	v_fmac_f32_e32 v164, 0x3f317217, v165
	v_cmp_lt_f32_e64 s[2:3], |v165|, s15
	v_sub_f32_e32 v173, 1.0, v149
	v_cndmask_b32_e64 v149, v149, 0, s[4:5]
	v_cndmask_b32_e64 v164, v165, v164, s[2:3]
	v_cndmask_b32_e32 v165, 0, v131, vcc
	v_cmp_gt_f32_e32 vcc, s14, v173
	v_sub_f32_e32 v164, v164, v165
	v_mul_f32_e32 v165, 0x3f317217, v172
	v_cndmask_b32_e64 v174, 0, 32, vcc
	v_ldexp_f32 v173, v173, v174
	v_fma_f32 v165, v172, s9, -v165
	v_log_f32_e32 v173, v173
	v_fmac_f32_e32 v165, 0x3377d1cf, v172
	v_fmac_f32_e32 v165, 0x3f317217, v172
	v_cmp_lt_f32_e64 s[2:3], |v172|, s15
	v_cndmask_b32_e64 v162, v162, 0, s[4:5]
	s_nop 0
	v_cndmask_b32_e64 v165, v172, v165, s[2:3]
	v_cndmask_b32_e64 v172, 0, v131, s[0:1]
	v_sub_f32_e32 v165, v165, v172
	v_mul_f32_e32 v172, 0x3f317217, v173
	v_fma_f32 v172, v173, s9, -v172
	v_fmac_f32_e32 v172, 0x3377d1cf, v173
	v_fmac_f32_e32 v172, 0x3f317217, v173
	v_cmp_lt_f32_e64 s[0:1], |v173|, s15
	v_add3_u32 v175, v150, v175, s16
	v_cvt_pk_bf16_f32 v148, v163, v148
	v_cndmask_b32_e64 v172, v173, v172, s[0:1]
	v_cndmask_b32_e32 v173, 0, v131, vcc
	v_sub_f32_e32 v172, v172, v173
	v_cvt_pk_bf16_f32 v149, v162, v149
	v_bfe_u32 v150, v166, 16, 1
	v_add3_u32 v150, v166, v150, s16
	v_lshrrev_b32_e32 v161, 16, v150
	v_lshrrev_b32_e32 v166, 16, v151
	v_mov_b32_e32 v151, v149
	v_mov_b32_e32 v150, v148
	v_and_or_b32 v149, v175, s17, v166
	v_and_or_b32 v148, v176, s17, v161
	global_store_dwordx4 v[138:139], v[148:151], off offset:256
	v_cndmask_b32_e64 v138, v167, 0, s[4:5]
	v_bfe_u32 v139, v138, 16, 1
	v_add3_u32 v138, v138, v139, s16
	v_cndmask_b32_e64 v139, v169, 0, s[4:5]
	v_bfe_u32 v148, v139, 16, 1
	v_lshrrev_b32_e32 v138, 16, v138
	v_add3_u32 v139, v139, v148, s16
	v_and_or_b32 v148, v139, s17, v138
	v_cndmask_b32_e64 v138, v168, 0, s[4:5]
	v_bfe_u32 v139, v138, 16, 1
	v_add3_u32 v138, v138, v139, s16
	v_cndmask_b32_e64 v139, v170, 0, s[4:5]
	v_bfe_u32 v149, v139, 16, 1
	v_lshrrev_b32_e32 v138, 16, v138
	v_add3_u32 v139, v139, v149, s16
	v_and_or_b32 v149, v139, s17, v138
	v_cndmask_b32_e64 v138, v171, 0, s[4:5]
	v_bfe_u32 v139, v138, 16, 1
	v_add3_u32 v138, v138, v139, s16
	v_cndmask_b32_e64 v139, v164, 0, s[4:5]
	v_bfe_u32 v150, v139, 16, 1
	v_lshrrev_b32_e32 v138, 16, v138
	v_add3_u32 v139, v139, v150, s16
	v_and_or_b32 v150, v139, s17, v138
	v_cndmask_b32_e64 v138, v165, 0, s[4:5]
	v_bfe_u32 v139, v138, 16, 1
	v_add3_u32 v138, v138, v139, s16
	v_cndmask_b32_e64 v139, v172, 0, s[4:5]
	v_bfe_u32 v151, v139, 16, 1
	v_lshrrev_b32_e32 v138, 16, v138
	v_add3_u32 v139, v139, v151, s16
	v_and_or_b32 v151, v139, s17, v138
	global_store_dwordx4 v[136:137], v[148:151], off offset:256
	v_mul_f32_e32 v161, 0x3fb8aa3b, v74
	v_exp_f32_e32 v162, v161
	v_mul_f32_e32 v149, 0x3fb8aa3b, v79
	v_mul_f32_e32 v148, 0x3fb8aa3b, v78
	v_exp_f32_e32 v150, v149
	v_mul_f32_e32 v149, 0x3fb8aa3b, v80
	v_exp_f32_e32 v148, v148
	v_exp_f32_e32 v149, v149
	v_mul_f32_e32 v161, 0x3fb8aa3b, v75
	v_or_b32_e32 v136, 48, v130
	v_exp_f32_e32 v164, v161
	v_pk_add_f32 v[148:149], v[148:149], 1.0 op_sel_hi:[1,0]
	v_mul_f32_e32 v161, 0x3fb8aa3b, v76
	v_div_scale_f32 v165, s[4:5], v149, v149, v157
	v_rcp_f32_e32 v166, v165
	v_cmp_gt_i32_e32 vcc, s20, v136
	v_exp_f32_e32 v163, v161
	v_mul_f32_e32 v151, 0x3fb8aa3b, v81
	v_fma_f32 v161, -v165, v166, 1.0
	v_cndmask_b32_e64 v137, v154, 0, vcc
	v_fmac_f32_e32 v166, v161, v166
	v_div_scale_f32 v161, vcc, v157, v149, v157
	v_mul_f32_e32 v167, v161, v166
	v_fma_f32 v168, -v165, v167, v161
	v_fmac_f32_e32 v167, v168, v166
	v_rcp_f32_e32 v169, v148
	v_fma_f32 v161, -v165, v167, v161
	v_div_fmas_f32 v161, v161, v166, v167
	v_exp_f32_e32 v151, v151
	v_mul_f32_e32 v166, v156, v169
	v_sub_f32_e32 v148, 1.0, v166
	v_cmp_gt_f32_e64 s[4:5], s14, v148
	v_div_fixup_f32 v161, v161, v149, v157
	v_add_u32_e32 v137, v137, v136
	v_cndmask_b32_e64 v165, 0, 32, s[4:5]
	v_ldexp_f32 v148, v148, v165
	v_log_f32_e32 v167, v148
	v_mul_f32_e32 v148, 0x3fb8aa3b, v77
	v_exp_f32_e32 v165, v148
	v_cmp_gt_i32_e64 s[0:1], s19, v136
	v_mul_f32_e32 v148, 0x3f317217, v167
	v_fma_f32 v168, v167, s9, -v148
	v_pk_add_f32 v[148:149], v[150:151], 1.0 op_sel_hi:[1,0]
	v_fmac_f32_e32 v168, 0x3377d1cf, v167
	v_rcp_f32_e32 v151, v149
	v_fmac_f32_e32 v168, 0x3f317217, v167
	v_cmp_lt_f32_e64 vcc, |v167|, s15
	v_cmp_gt_i32_e64 s[2:3], s18, v137
	v_ashrrev_i32_e32 v137, 31, v136
	v_cndmask_b32_e32 v167, v167, v168, vcc
	v_rcp_f32_e32 v171, v148
	v_mul_f32_e32 v150, v158, v151
	v_mul_f32_e32 v151, v155, v171
	v_sub_f32_e32 v148, 1.0, v151
	v_cmp_gt_f32_e32 vcc, s14, v148
	v_lshlrev_b64 v[136:137], 10, v[136:137]
	v_lshl_add_u64 v[138:139], v[132:133], 0, v[136:137]
	v_cndmask_b32_e64 v168, 0, 32, vcc
	v_ldexp_f32 v148, v148, v168
	v_log_f32_e32 v148, v148
	v_cndmask_b32_e64 v168, 0, v131, s[4:5]
	v_sub_f32_e32 v167, v167, v168
	v_sub_f32_e32 v168, 1.0, v161
	v_mul_f32_e32 v149, 0x3f317217, v148
	v_fma_f32 v149, v148, s9, -v149
	v_cmp_gt_f32_e64 s[4:5], s14, v168
	v_fmac_f32_e32 v149, 0x3377d1cf, v148
	v_fmac_f32_e32 v149, 0x3f317217, v148
	v_cndmask_b32_e64 v169, 0, 32, s[4:5]
	v_ldexp_f32 v168, v168, v169
	v_cmp_lt_f32_e64 s[6:7], |v148|, s15
	v_log_f32_e32 v168, v168
	v_lshl_add_u64 v[136:137], v[134:135], 0, v[136:137]
	v_cndmask_b32_e64 v148, v148, v149, s[6:7]
	v_cndmask_b32_e32 v149, 0, v131, vcc
	v_sub_f32_e32 v169, v148, v149
	v_sub_f32_e32 v149, 1.0, v150
	v_cmp_gt_f32_e32 vcc, s14, v149
	v_mul_f32_e32 v148, 0x3f317217, v168
	v_fma_f32 v148, v168, s9, -v148
	v_cndmask_b32_e64 v170, 0, 32, vcc
	v_ldexp_f32 v149, v149, v170
	v_log_f32_e32 v149, v149
	v_fmac_f32_e32 v148, 0x3377d1cf, v168
	v_fmac_f32_e32 v148, 0x3f317217, v168
	v_cmp_lt_f32_e64 s[6:7], |v168|, s15
	s_nop 1
	v_cndmask_b32_e64 v148, v168, v148, s[6:7]
	v_cndmask_b32_e64 v168, 0, v131, s[4:5]
	v_sub_f32_e32 v168, v148, v168
	v_mul_f32_e32 v148, 0x3f317217, v149
	v_fma_f32 v148, v149, s9, -v148
	v_fmac_f32_e32 v148, 0x3377d1cf, v149
	v_fmac_f32_e32 v148, 0x3f317217, v149
	v_cmp_lt_f32_e64 s[4:5], |v149|, s15
	s_nop 1
	v_cndmask_b32_e64 v148, v149, v148, s[4:5]
	v_cndmask_b32_e32 v149, 0, v131, vcc
	v_sub_f32_e32 v170, v148, v149
	v_pk_add_f32 v[148:149], v[162:163], 1.0 op_sel_hi:[1,0]
	s_nop 0
	v_rcp_f32_e32 v163, v149
	s_and_b64 s[4:5], s[0:1], s[2:3]
	v_cndmask_b32_e64 v151, v151, 0, s[4:5]
	v_cndmask_b32_e64 v150, v150, 0, s[4:5]
	v_rcp_f32_e32 v174, v148
	v_mul_f32_e32 v162, v152, v163
	v_mul_f32_e32 v163, v159, v174
	v_sub_f32_e32 v148, 1.0, v163
	v_cmp_gt_f32_e64 s[0:1], s14, v148
	v_cndmask_b32_e64 v161, v161, 0, s[4:5]
	v_cndmask_b32_e64 v166, v166, 0, s[4:5]
	v_cndmask_b32_e64 v171, 0, 32, s[0:1]
	v_ldexp_f32 v148, v148, v171
	v_log_f32_e32 v171, v148
	v_cndmask_b32_e64 v163, v163, 0, s[4:5]
	v_bfe_u32 v176, v151, 16, 1
	v_add3_u32 v176, v151, v176, s16
	v_mul_f32_e32 v148, 0x3f317217, v171
	v_fma_f32 v172, v171, s9, -v148
	v_pk_add_f32 v[148:149], v[164:165], 1.0 op_sel_hi:[1,0]
	v_fmac_f32_e32 v172, 0x3377d1cf, v171
	v_rcp_f32_e32 v165, v149
	v_fmac_f32_e32 v172, 0x3f317217, v171
	v_cmp_lt_f32_e64 vcc, |v171|, s15
	v_bfe_u32 v151, v161, 16, 1
	v_add3_u32 v151, v161, v151, s16
	v_cndmask_b32_e32 v171, v171, v172, vcc
	v_rcp_f32_e32 v175, v148
	v_mul_f32_e32 v149, v153, v165
	v_mul_f32_e32 v148, v160, v175
	v_sub_f32_e32 v165, 1.0, v148
	v_cmp_gt_f32_e32 vcc, s14, v165
	v_cndmask_b32_e64 v148, v148, 0, s[4:5]
	v_bfe_u32 v175, v150, 16, 1
	v_cndmask_b32_e64 v172, 0, 32, vcc
	v_ldexp_f32 v165, v165, v172
	v_log_f32_e32 v165, v165
	v_cndmask_b32_e64 v172, 0, v131, s[0:1]
	v_sub_f32_e32 v171, v171, v172
	v_sub_f32_e32 v172, 1.0, v162
	v_cmp_gt_f32_e64 s[0:1], s14, v172
	v_mul_f32_e32 v164, 0x3f317217, v165
	v_fma_f32 v164, v165, s9, -v164
	v_cndmask_b32_e64 v173, 0, 32, s[0:1]
	v_ldexp_f32 v172, v172, v173
	v_fmac_f32_e32 v164, 0x3377d1cf, v165
	v_log_f32_e32 v172, v172
	v_fmac_f32_e32 v164, 0x3f317217, v165
	v_cmp_lt_f32_e64 s[2:3], |v165|, s15
	v_sub_f32_e32 v173, 1.0, v149
	v_cndmask_b32_e64 v149, v149, 0, s[4:5]
	v_cndmask_b32_e64 v164, v165, v164, s[2:3]
	v_cndmask_b32_e32 v165, 0, v131, vcc
	v_cmp_gt_f32_e32 vcc, s14, v173
	v_sub_f32_e32 v164, v164, v165
	v_mul_f32_e32 v165, 0x3f317217, v172
	v_cndmask_b32_e64 v174, 0, 32, vcc
	v_ldexp_f32 v173, v173, v174
	v_fma_f32 v165, v172, s9, -v165
	v_log_f32_e32 v173, v173
	v_fmac_f32_e32 v165, 0x3377d1cf, v172
	v_fmac_f32_e32 v165, 0x3f317217, v172
	v_cmp_lt_f32_e64 s[2:3], |v172|, s15
	v_cndmask_b32_e64 v162, v162, 0, s[4:5]
	s_nop 0
	v_cndmask_b32_e64 v165, v172, v165, s[2:3]
	v_cndmask_b32_e64 v172, 0, v131, s[0:1]
	v_sub_f32_e32 v165, v165, v172
	v_mul_f32_e32 v172, 0x3f317217, v173
	v_fma_f32 v172, v173, s9, -v172
	v_fmac_f32_e32 v172, 0x3377d1cf, v173
	v_fmac_f32_e32 v172, 0x3f317217, v173
	v_cmp_lt_f32_e64 s[0:1], |v173|, s15
	v_add3_u32 v175, v150, v175, s16
	v_cvt_pk_bf16_f32 v148, v163, v148
	v_cndmask_b32_e64 v172, v173, v172, s[0:1]
	v_cndmask_b32_e32 v173, 0, v131, vcc
	v_sub_f32_e32 v172, v172, v173
	v_cvt_pk_bf16_f32 v149, v162, v149
	v_bfe_u32 v150, v166, 16, 1
	v_add3_u32 v150, v166, v150, s16
	v_lshrrev_b32_e32 v161, 16, v150
	v_lshrrev_b32_e32 v166, 16, v151
	v_mov_b32_e32 v151, v149
	v_mov_b32_e32 v150, v148
	v_and_or_b32 v149, v175, s17, v166
	v_and_or_b32 v148, v176, s17, v161
	global_store_dwordx4 v[138:139], v[148:151], off
	s_nop 1
	v_cndmask_b32_e64 v148, v167, 0, s[4:5]
	v_bfe_u32 v149, v148, 16, 1
	v_add3_u32 v148, v148, v149, s16
	v_cndmask_b32_e64 v149, v169, 0, s[4:5]
	v_bfe_u32 v150, v149, 16, 1
	v_lshrrev_b32_e32 v148, 16, v148
	v_add3_u32 v149, v149, v150, s16
	v_and_or_b32 v148, v149, s17, v148
	v_cndmask_b32_e64 v149, v168, 0, s[4:5]
	v_bfe_u32 v150, v149, 16, 1
	v_add3_u32 v149, v149, v150, s16
	v_cndmask_b32_e64 v150, v170, 0, s[4:5]
	v_bfe_u32 v151, v150, 16, 1
	v_lshrrev_b32_e32 v149, 16, v149
	v_add3_u32 v150, v150, v151, s16
	v_and_or_b32 v149, v150, s17, v149
	v_cndmask_b32_e64 v150, v171, 0, s[4:5]
	v_bfe_u32 v151, v150, 16, 1
	v_add3_u32 v150, v150, v151, s16
	v_cndmask_b32_e64 v151, v164, 0, s[4:5]
	v_bfe_u32 v161, v151, 16, 1
	v_lshrrev_b32_e32 v150, 16, v150
	v_add3_u32 v151, v151, v161, s16
	v_and_or_b32 v150, v151, s17, v150
	v_cndmask_b32_e64 v151, v165, 0, s[4:5]
	v_bfe_u32 v161, v151, 16, 1
	v_add3_u32 v151, v151, v161, s16
	v_cndmask_b32_e64 v161, v172, 0, s[4:5]
	v_bfe_u32 v162, v161, 16, 1
	v_lshrrev_b32_e32 v151, 16, v151
	v_add3_u32 v161, v161, v162, s16
	v_and_or_b32 v151, v161, s17, v151
	global_store_dwordx4 v[136:137], v[148:151], off
	v_mul_f32_e32 v161, 0x3fb8aa3b, v66
	v_exp_f32_e32 v162, v161
	v_mul_f32_e32 v149, 0x3fb8aa3b, v71
	v_mul_f32_e32 v148, 0x3fb8aa3b, v70
	v_exp_f32_e32 v150, v149
	v_mul_f32_e32 v149, 0x3fb8aa3b, v72
	v_exp_f32_e32 v148, v148
	v_exp_f32_e32 v149, v149
	v_mul_f32_e32 v161, 0x3fb8aa3b, v67
	v_exp_f32_e32 v164, v161
	v_mul_f32_e32 v161, 0x3fb8aa3b, v68
	v_pk_add_f32 v[148:149], v[148:149], 1.0 op_sel_hi:[1,0]
	v_exp_f32_e32 v163, v161
	v_rcp_f32_e32 v166, v149
	v_mul_f32_e32 v151, 0x3fb8aa3b, v73
	v_exp_f32_e32 v151, v151
	v_rcp_f32_e32 v169, v148
	v_mul_f32_e32 v161, v144, v166
	v_mul_f32_e32 v166, v146, v169
	v_sub_f32_e32 v148, 1.0, v166
	v_cmp_gt_f32_e64 s[0:1], s14, v148
	v_cndmask_b32_e64 v166, v166, 0, s[4:5]
	s_nop 0
	v_cndmask_b32_e64 v165, 0, 32, s[0:1]
	v_ldexp_f32 v148, v148, v165
	v_log_f32_e32 v167, v148
	v_mul_f32_e32 v148, 0x3fb8aa3b, v69
	v_exp_f32_e32 v165, v148
	v_mul_f32_e32 v148, 0x3f317217, v167
	v_fma_f32 v168, v167, s9, -v148
	v_pk_add_f32 v[148:149], v[150:151], 1.0 op_sel_hi:[1,0]
	v_fmac_f32_e32 v168, 0x3377d1cf, v167
	v_rcp_f32_e32 v151, v149
	v_fmac_f32_e32 v168, 0x3f317217, v167
	v_cmp_lt_f32_e64 vcc, |v167|, s15
	s_nop 1
	v_cndmask_b32_e32 v167, v167, v168, vcc
	v_rcp_f32_e32 v171, v148
	v_mul_f32_e32 v150, v145, v151
	v_mul_f32_e32 v151, v147, v171
	v_sub_f32_e32 v148, 1.0, v151
	v_cmp_gt_f32_e32 vcc, s14, v148
	v_cndmask_b32_e64 v151, v151, 0, s[4:5]
	v_bfe_u32 v176, v151, 16, 1
	v_cndmask_b32_e64 v168, 0, 32, vcc
	v_ldexp_f32 v148, v148, v168
	v_log_f32_e32 v148, v148
	v_cndmask_b32_e64 v168, 0, v131, s[0:1]
	v_sub_f32_e32 v167, v167, v168
	v_sub_f32_e32 v168, 1.0, v161
	v_mul_f32_e32 v149, 0x3f317217, v148
	v_fma_f32 v149, v148, s9, -v149
	v_cmp_gt_f32_e64 s[0:1], s14, v168
	v_fmac_f32_e32 v149, 0x3377d1cf, v148
	v_fmac_f32_e32 v149, 0x3f317217, v148
	v_cndmask_b32_e64 v169, 0, 32, s[0:1]
	v_ldexp_f32 v168, v168, v169
	v_cmp_lt_f32_e64 s[2:3], |v148|, s15
	v_log_f32_e32 v168, v168
	v_cndmask_b32_e64 v161, v161, 0, s[4:5]
	v_cndmask_b32_e64 v148, v148, v149, s[2:3]
	v_cndmask_b32_e32 v149, 0, v131, vcc
	v_sub_f32_e32 v169, v148, v149
	v_sub_f32_e32 v149, 1.0, v150
	v_cmp_gt_f32_e32 vcc, s14, v149
	v_mul_f32_e32 v148, 0x3f317217, v168
	v_fma_f32 v148, v168, s9, -v148
	v_cndmask_b32_e64 v170, 0, 32, vcc
	v_ldexp_f32 v149, v149, v170
	v_log_f32_e32 v149, v149
	v_fmac_f32_e32 v148, 0x3377d1cf, v168
	v_fmac_f32_e32 v148, 0x3f317217, v168
	v_cmp_lt_f32_e64 s[2:3], |v168|, s15
	v_cndmask_b32_e32 v171, 0, v131, vcc
	v_cndmask_b32_e64 v150, v150, 0, s[4:5]
	v_cndmask_b32_e64 v148, v168, v148, s[2:3]
	v_cndmask_b32_e64 v168, 0, v131, s[0:1]
	v_sub_f32_e32 v168, v148, v168
	v_mul_f32_e32 v148, 0x3f317217, v149
	v_fma_f32 v148, v149, s9, -v148
	v_fmac_f32_e32 v148, 0x3377d1cf, v149
	v_fmac_f32_e32 v148, 0x3f317217, v149
	v_cmp_lt_f32_e64 s[0:1], |v149|, s15
	v_add3_u32 v176, v151, v176, s16
	v_bfe_u32 v151, v161, 16, 1
	v_cndmask_b32_e64 v170, v149, v148, s[0:1]
	v_pk_add_f32 v[148:149], v[162:163], 1.0 op_sel_hi:[1,0]
	v_sub_f32_e32 v170, v170, v171
	v_rcp_f32_e32 v163, v149
	v_add3_u32 v151, v161, v151, s16
	v_rcp_f32_e32 v174, v148
	v_mul_f32_e32 v162, v140, v163
	v_mul_f32_e32 v163, v142, v174
	v_sub_f32_e32 v148, 1.0, v163
	v_cmp_gt_f32_e64 s[0:1], s14, v148
	v_cndmask_b32_e64 v163, v163, 0, s[4:5]
	s_nop 0
	v_cndmask_b32_e64 v171, 0, 32, s[0:1]
	v_ldexp_f32 v148, v148, v171
	v_log_f32_e32 v171, v148
	s_nop 0
	v_mul_f32_e32 v148, 0x3f317217, v171
	v_fma_f32 v172, v171, s9, -v148
	v_pk_add_f32 v[148:149], v[164:165], 1.0 op_sel_hi:[1,0]
	v_fmac_f32_e32 v172, 0x3377d1cf, v171
	v_rcp_f32_e32 v165, v149
	v_fmac_f32_e32 v172, 0x3f317217, v171
	v_cmp_lt_f32_e64 vcc, |v171|, s15
	s_nop 1
	v_cndmask_b32_e32 v171, v171, v172, vcc
	v_rcp_f32_e32 v175, v148
	v_mul_f32_e32 v149, v141, v165
	v_mul_f32_e32 v148, v143, v175
	v_sub_f32_e32 v165, 1.0, v148
	v_cmp_gt_f32_e32 vcc, s14, v165
	v_cndmask_b32_e64 v148, v148, 0, s[4:5]
	v_bfe_u32 v175, v150, 16, 1
	v_cndmask_b32_e64 v172, 0, 32, vcc
	v_ldexp_f32 v165, v165, v172
	v_log_f32_e32 v165, v165
	v_cndmask_b32_e64 v172, 0, v131, s[0:1]
	v_sub_f32_e32 v171, v171, v172
	v_sub_f32_e32 v172, 1.0, v162
	v_cmp_gt_f32_e64 s[0:1], s14, v172
	v_mul_f32_e32 v164, 0x3f317217, v165
	v_fma_f32 v164, v165, s9, -v164
	v_cndmask_b32_e64 v173, 0, 32, s[0:1]
	v_ldexp_f32 v172, v172, v173
	v_fmac_f32_e32 v164, 0x3377d1cf, v165
	v_log_f32_e32 v172, v172
	v_fmac_f32_e32 v164, 0x3f317217, v165
	v_cmp_lt_f32_e64 s[2:3], |v165|, s15
	v_sub_f32_e32 v173, 1.0, v149
	v_cndmask_b32_e64 v149, v149, 0, s[4:5]
	v_cndmask_b32_e64 v164, v165, v164, s[2:3]
	v_cndmask_b32_e32 v165, 0, v131, vcc
	v_cmp_gt_f32_e32 vcc, s14, v173
	v_sub_f32_e32 v164, v164, v165
	v_mul_f32_e32 v165, 0x3f317217, v172
	v_cndmask_b32_e64 v174, 0, 32, vcc
	v_ldexp_f32 v173, v173, v174
	v_fma_f32 v165, v172, s9, -v165
	v_log_f32_e32 v173, v173
	v_fmac_f32_e32 v165, 0x3377d1cf, v172
	v_fmac_f32_e32 v165, 0x3f317217, v172
	v_cmp_lt_f32_e64 s[2:3], |v172|, s15
	v_cndmask_b32_e64 v162, v162, 0, s[4:5]
	s_nop 0
	v_cndmask_b32_e64 v165, v172, v165, s[2:3]
	v_cndmask_b32_e64 v172, 0, v131, s[0:1]
	v_sub_f32_e32 v165, v165, v172
	v_mul_f32_e32 v172, 0x3f317217, v173
	v_fma_f32 v172, v173, s9, -v172
	v_fmac_f32_e32 v172, 0x3377d1cf, v173
	v_fmac_f32_e32 v172, 0x3f317217, v173
	v_cmp_lt_f32_e64 s[0:1], |v173|, s15
	v_add3_u32 v175, v150, v175, s16
	v_cvt_pk_bf16_f32 v148, v163, v148
	v_cndmask_b32_e64 v172, v173, v172, s[0:1]
	v_cndmask_b32_e32 v173, 0, v131, vcc
	v_sub_f32_e32 v172, v172, v173
	v_cvt_pk_bf16_f32 v149, v162, v149
	v_bfe_u32 v150, v166, 16, 1
	v_add3_u32 v150, v166, v150, s16
	v_lshrrev_b32_e32 v161, 16, v150
	v_lshrrev_b32_e32 v166, 16, v151
	v_mov_b32_e32 v151, v149
	v_mov_b32_e32 v150, v148
	v_and_or_b32 v149, v175, s17, v166
	v_and_or_b32 v148, v176, s17, v161
	global_store_dwordx4 v[138:139], v[148:151], off offset:256
	v_cndmask_b32_e64 v138, v167, 0, s[4:5]
	v_bfe_u32 v139, v138, 16, 1
	v_add3_u32 v138, v138, v139, s16
	v_cndmask_b32_e64 v139, v169, 0, s[4:5]
	v_bfe_u32 v148, v139, 16, 1
	v_lshrrev_b32_e32 v138, 16, v138
	v_add3_u32 v139, v139, v148, s16
	v_and_or_b32 v148, v139, s17, v138
	v_cndmask_b32_e64 v138, v168, 0, s[4:5]
	v_bfe_u32 v139, v138, 16, 1
	v_add3_u32 v138, v138, v139, s16
	v_cndmask_b32_e64 v139, v170, 0, s[4:5]
	v_bfe_u32 v149, v139, 16, 1
	v_lshrrev_b32_e32 v138, 16, v138
	v_add3_u32 v139, v139, v149, s16
	v_and_or_b32 v149, v139, s17, v138
	v_cndmask_b32_e64 v138, v171, 0, s[4:5]
	v_bfe_u32 v139, v138, 16, 1
	v_add3_u32 v138, v138, v139, s16
	v_cndmask_b32_e64 v139, v164, 0, s[4:5]
	v_bfe_u32 v150, v139, 16, 1
	v_lshrrev_b32_e32 v138, 16, v138
	v_add3_u32 v139, v139, v150, s16
	v_and_or_b32 v150, v139, s17, v138
	v_cndmask_b32_e64 v138, v165, 0, s[4:5]
	v_bfe_u32 v139, v138, 16, 1
	v_add3_u32 v138, v138, v139, s16
	v_cndmask_b32_e64 v139, v172, 0, s[4:5]
	v_bfe_u32 v151, v139, 16, 1
	v_lshrrev_b32_e32 v138, 16, v138
	v_add3_u32 v139, v139, v151, s16
	v_and_or_b32 v151, v139, s17, v138
	global_store_dwordx4 v[136:137], v[148:151], off offset:256
	v_mul_f32_e32 v161, 0x3fb8aa3b, v58
	v_exp_f32_e32 v162, v161
	v_mul_f32_e32 v149, 0x3fb8aa3b, v63
	v_mul_f32_e32 v148, 0x3fb8aa3b, v62
	v_exp_f32_e32 v150, v149
	v_mul_f32_e32 v149, 0x3fb8aa3b, v64
	v_exp_f32_e32 v148, v148
	v_exp_f32_e32 v149, v149
	v_mul_f32_e32 v161, 0x3fb8aa3b, v59
	s_movk_i32 s2, 0x2000
	v_exp_f32_e32 v164, v161
	v_pk_add_f32 v[148:149], v[148:149], 1.0 op_sel_hi:[1,0]
	v_mul_f32_e32 v161, 0x3fb8aa3b, v60
	v_div_scale_f32 v165, s[4:5], v149, v149, v157
	v_rcp_f32_e32 v166, v165
	v_cmp_gt_i32_e32 vcc, s2, v130
	v_exp_f32_e32 v163, v161
	v_mul_f32_e32 v151, 0x3fb8aa3b, v65
	v_fma_f32 v161, -v165, v166, 1.0
	v_cndmask_b32_e64 v137, v154, 0, vcc
	v_fmac_f32_e32 v166, v161, v166
	v_div_scale_f32 v161, vcc, v157, v149, v157
	v_mul_f32_e32 v167, v161, v166
	v_fma_f32 v168, -v165, v167, v161
	v_fmac_f32_e32 v167, v168, v166
	v_rcp_f32_e32 v169, v148
	v_fma_f32 v161, -v165, v167, v161
	v_div_fmas_f32 v161, v161, v166, v167
	v_exp_f32_e32 v151, v151
	v_mul_f32_e32 v166, v156, v169
	v_sub_f32_e32 v148, 1.0, v166
	v_cmp_gt_f32_e64 s[4:5], s14, v148
	v_div_fixup_f32 v161, v161, v149, v157
	v_add_u32_e32 v136, 0x80, v130
	v_cndmask_b32_e64 v165, 0, 32, s[4:5]
	v_ldexp_f32 v148, v148, v165
	v_log_f32_e32 v167, v148
	v_mul_f32_e32 v148, 0x3fb8aa3b, v61
	v_exp_f32_e32 v165, v148
	s_movk_i32 s0, 0x4080
	v_mul_f32_e32 v148, 0x3f317217, v167
	v_fma_f32 v168, v167, s9, -v148
	v_pk_add_f32 v[148:149], v[150:151], 1.0 op_sel_hi:[1,0]
	v_fmac_f32_e32 v168, 0x3377d1cf, v167
	v_rcp_f32_e32 v151, v149
	v_fmac_f32_e32 v168, 0x3f317217, v167
	v_cmp_lt_f32_e64 vcc, |v167|, s15
	v_add_u32_e32 v137, v137, v136
	v_cmp_gt_i32_e64 s[0:1], s0, v130
	v_cndmask_b32_e32 v167, v167, v168, vcc
	v_rcp_f32_e32 v171, v148
	v_mul_f32_e32 v150, v158, v151
	v_mul_f32_e32 v151, v155, v171
	v_sub_f32_e32 v148, 1.0, v151
	v_cmp_gt_f32_e32 vcc, s14, v148
	v_cmp_gt_i32_e64 s[2:3], s18, v137
	v_ashrrev_i32_e32 v137, 31, v136
	v_cndmask_b32_e64 v168, 0, 32, vcc
	v_ldexp_f32 v148, v148, v168
	v_log_f32_e32 v148, v148
	v_cndmask_b32_e64 v168, 0, v131, s[4:5]
	v_sub_f32_e32 v167, v167, v168
	v_sub_f32_e32 v168, 1.0, v161
	v_mul_f32_e32 v149, 0x3f317217, v148
	v_fma_f32 v149, v148, s9, -v149
	v_cmp_gt_f32_e64 s[4:5], s14, v168
	v_fmac_f32_e32 v149, 0x3377d1cf, v148
	v_fmac_f32_e32 v149, 0x3f317217, v148
	v_cndmask_b32_e64 v169, 0, 32, s[4:5]
	v_ldexp_f32 v168, v168, v169
	v_cmp_lt_f32_e64 s[6:7], |v148|, s15
	v_log_f32_e32 v168, v168
	v_lshlrev_b64 v[136:137], 10, v[136:137]
	v_cndmask_b32_e64 v148, v148, v149, s[6:7]
	v_cndmask_b32_e32 v149, 0, v131, vcc
	v_sub_f32_e32 v169, v148, v149
	v_sub_f32_e32 v149, 1.0, v150
	v_cmp_gt_f32_e32 vcc, s14, v149
	v_mul_f32_e32 v148, 0x3f317217, v168
	v_fma_f32 v148, v168, s9, -v148
	v_cndmask_b32_e64 v170, 0, 32, vcc
	v_ldexp_f32 v149, v149, v170
	v_log_f32_e32 v149, v149
	v_fmac_f32_e32 v148, 0x3377d1cf, v168
	v_fmac_f32_e32 v148, 0x3f317217, v168
	v_cmp_lt_f32_e64 s[6:7], |v168|, s15
	v_lshl_add_u64 v[138:139], v[132:133], 0, v[136:137]
	v_lshl_add_u64 v[136:137], v[134:135], 0, v[136:137]
	v_cndmask_b32_e64 v148, v168, v148, s[6:7]
	v_cndmask_b32_e64 v168, 0, v131, s[4:5]
	v_sub_f32_e32 v168, v148, v168
	v_mul_f32_e32 v148, 0x3f317217, v149
	v_fma_f32 v148, v149, s9, -v148
	v_fmac_f32_e32 v148, 0x3377d1cf, v149
	v_fmac_f32_e32 v148, 0x3f317217, v149
	v_cmp_lt_f32_e64 s[4:5], |v149|, s15
	s_nop 1
	v_cndmask_b32_e64 v148, v149, v148, s[4:5]
	v_cndmask_b32_e32 v149, 0, v131, vcc
	v_sub_f32_e32 v170, v148, v149
	v_pk_add_f32 v[148:149], v[162:163], 1.0 op_sel_hi:[1,0]
	s_nop 0
	v_rcp_f32_e32 v163, v149
	s_and_b64 s[4:5], s[0:1], s[2:3]
	v_cndmask_b32_e64 v151, v151, 0, s[4:5]
	v_cndmask_b32_e64 v150, v150, 0, s[4:5]
	v_rcp_f32_e32 v174, v148
	v_mul_f32_e32 v162, v152, v163
	v_mul_f32_e32 v163, v159, v174
	v_sub_f32_e32 v148, 1.0, v163
	v_cmp_gt_f32_e64 s[0:1], s14, v148
	v_cndmask_b32_e64 v161, v161, 0, s[4:5]
	v_cndmask_b32_e64 v166, v166, 0, s[4:5]
	v_cndmask_b32_e64 v171, 0, 32, s[0:1]
	v_ldexp_f32 v148, v148, v171
	v_log_f32_e32 v171, v148
	v_cndmask_b32_e64 v163, v163, 0, s[4:5]
	v_bfe_u32 v176, v151, 16, 1
	v_add3_u32 v176, v151, v176, s16
	v_mul_f32_e32 v148, 0x3f317217, v171
	v_fma_f32 v172, v171, s9, -v148
	v_pk_add_f32 v[148:149], v[164:165], 1.0 op_sel_hi:[1,0]
	v_fmac_f32_e32 v172, 0x3377d1cf, v171
	v_rcp_f32_e32 v165, v149
	v_fmac_f32_e32 v172, 0x3f317217, v171
	v_cmp_lt_f32_e64 vcc, |v171|, s15
	v_bfe_u32 v151, v161, 16, 1
	v_add3_u32 v151, v161, v151, s16
	v_cndmask_b32_e32 v171, v171, v172, vcc
	v_rcp_f32_e32 v175, v148
	v_mul_f32_e32 v149, v153, v165
	v_mul_f32_e32 v148, v160, v175
	v_sub_f32_e32 v165, 1.0, v148
	v_cmp_gt_f32_e32 vcc, s14, v165
	v_cndmask_b32_e64 v148, v148, 0, s[4:5]
	v_bfe_u32 v175, v150, 16, 1
	v_cndmask_b32_e64 v172, 0, 32, vcc
	v_ldexp_f32 v165, v165, v172
	v_log_f32_e32 v165, v165
	v_cndmask_b32_e64 v172, 0, v131, s[0:1]
	v_sub_f32_e32 v171, v171, v172
	v_sub_f32_e32 v172, 1.0, v162
	v_cmp_gt_f32_e64 s[0:1], s14, v172
	v_mul_f32_e32 v164, 0x3f317217, v165
	v_fma_f32 v164, v165, s9, -v164
	v_cndmask_b32_e64 v173, 0, 32, s[0:1]
	v_ldexp_f32 v172, v172, v173
	v_fmac_f32_e32 v164, 0x3377d1cf, v165
	v_log_f32_e32 v172, v172
	v_fmac_f32_e32 v164, 0x3f317217, v165
	v_cmp_lt_f32_e64 s[2:3], |v165|, s15
	v_sub_f32_e32 v173, 1.0, v149
	v_cndmask_b32_e64 v149, v149, 0, s[4:5]
	v_cndmask_b32_e64 v164, v165, v164, s[2:3]
	v_cndmask_b32_e32 v165, 0, v131, vcc
	v_cmp_gt_f32_e32 vcc, s14, v173
	v_sub_f32_e32 v164, v164, v165
	v_mul_f32_e32 v165, 0x3f317217, v172
	v_cndmask_b32_e64 v174, 0, 32, vcc
	v_ldexp_f32 v173, v173, v174
	v_fma_f32 v165, v172, s9, -v165
	v_log_f32_e32 v173, v173
	v_fmac_f32_e32 v165, 0x3377d1cf, v172
	v_fmac_f32_e32 v165, 0x3f317217, v172
	v_cmp_lt_f32_e64 s[2:3], |v172|, s15
	v_cndmask_b32_e64 v162, v162, 0, s[4:5]
	s_nop 0
	v_cndmask_b32_e64 v165, v172, v165, s[2:3]
	v_cndmask_b32_e64 v172, 0, v131, s[0:1]
	v_sub_f32_e32 v165, v165, v172
	v_mul_f32_e32 v172, 0x3f317217, v173
	v_fma_f32 v172, v173, s9, -v172
	v_fmac_f32_e32 v172, 0x3377d1cf, v173
	v_fmac_f32_e32 v172, 0x3f317217, v173
	v_cmp_lt_f32_e64 s[0:1], |v173|, s15
	v_add3_u32 v175, v150, v175, s16
	v_cvt_pk_bf16_f32 v148, v163, v148
	v_cndmask_b32_e64 v172, v173, v172, s[0:1]
	v_cndmask_b32_e32 v173, 0, v131, vcc
	v_sub_f32_e32 v172, v172, v173
	v_cvt_pk_bf16_f32 v149, v162, v149
	v_bfe_u32 v150, v166, 16, 1
	v_add3_u32 v150, v166, v150, s16
	v_lshrrev_b32_e32 v161, 16, v150
	v_lshrrev_b32_e32 v166, 16, v151
	v_mov_b32_e32 v151, v149
	v_mov_b32_e32 v150, v148
	v_and_or_b32 v149, v175, s17, v166
	v_and_or_b32 v148, v176, s17, v161
	global_store_dwordx4 v[138:139], v[148:151], off
	s_nop 1
	v_cndmask_b32_e64 v148, v167, 0, s[4:5]
	v_bfe_u32 v149, v148, 16, 1
	v_add3_u32 v148, v148, v149, s16
	v_cndmask_b32_e64 v149, v169, 0, s[4:5]
	v_bfe_u32 v150, v149, 16, 1
	v_lshrrev_b32_e32 v148, 16, v148
	v_add3_u32 v149, v149, v150, s16
	v_and_or_b32 v148, v149, s17, v148
	v_cndmask_b32_e64 v149, v168, 0, s[4:5]
	v_bfe_u32 v150, v149, 16, 1
	v_add3_u32 v149, v149, v150, s16
	v_cndmask_b32_e64 v150, v170, 0, s[4:5]
	v_bfe_u32 v151, v150, 16, 1
	v_lshrrev_b32_e32 v149, 16, v149
	v_add3_u32 v150, v150, v151, s16
	v_and_or_b32 v149, v150, s17, v149
	v_cndmask_b32_e64 v150, v171, 0, s[4:5]
	v_bfe_u32 v151, v150, 16, 1
	v_add3_u32 v150, v150, v151, s16
	v_cndmask_b32_e64 v151, v164, 0, s[4:5]
	v_bfe_u32 v161, v151, 16, 1
	v_lshrrev_b32_e32 v150, 16, v150
	v_add3_u32 v151, v151, v161, s16
	v_and_or_b32 v150, v151, s17, v150
	v_cndmask_b32_e64 v151, v165, 0, s[4:5]
	v_bfe_u32 v161, v151, 16, 1
	v_add3_u32 v151, v151, v161, s16
	v_cndmask_b32_e64 v161, v172, 0, s[4:5]
	v_bfe_u32 v162, v161, 16, 1
	v_lshrrev_b32_e32 v151, 16, v151
	v_add3_u32 v161, v161, v162, s16
	v_and_or_b32 v151, v161, s17, v151
	global_store_dwordx4 v[136:137], v[148:151], off
	v_mul_f32_e32 v161, 0x3fb8aa3b, v50
	v_exp_f32_e32 v162, v161
	v_mul_f32_e32 v149, 0x3fb8aa3b, v55
	v_mul_f32_e32 v148, 0x3fb8aa3b, v54
	v_exp_f32_e32 v150, v149
	v_mul_f32_e32 v149, 0x3fb8aa3b, v56
	v_exp_f32_e32 v148, v148
	v_exp_f32_e32 v149, v149
	v_mul_f32_e32 v161, 0x3fb8aa3b, v51
	v_exp_f32_e32 v164, v161
	v_mul_f32_e32 v161, 0x3fb8aa3b, v52
	v_pk_add_f32 v[148:149], v[148:149], 1.0 op_sel_hi:[1,0]
	v_exp_f32_e32 v163, v161
	v_rcp_f32_e32 v166, v149
	v_mul_f32_e32 v151, 0x3fb8aa3b, v57
	v_exp_f32_e32 v151, v151
	v_rcp_f32_e32 v169, v148
	v_mul_f32_e32 v161, v144, v166
	v_mul_f32_e32 v166, v146, v169
	v_sub_f32_e32 v148, 1.0, v166
	v_cmp_gt_f32_e64 s[0:1], s14, v148
	v_cndmask_b32_e64 v166, v166, 0, s[4:5]
	s_nop 0
	v_cndmask_b32_e64 v165, 0, 32, s[0:1]
	v_ldexp_f32 v148, v148, v165
	v_log_f32_e32 v167, v148
	v_mul_f32_e32 v148, 0x3fb8aa3b, v53
	v_exp_f32_e32 v165, v148
	v_mul_f32_e32 v148, 0x3f317217, v167
	v_fma_f32 v168, v167, s9, -v148
	v_pk_add_f32 v[148:149], v[150:151], 1.0 op_sel_hi:[1,0]
	v_fmac_f32_e32 v168, 0x3377d1cf, v167
	v_rcp_f32_e32 v151, v149
	v_fmac_f32_e32 v168, 0x3f317217, v167
	v_cmp_lt_f32_e64 vcc, |v167|, s15
	s_nop 1
	v_cndmask_b32_e32 v167, v167, v168, vcc
	v_rcp_f32_e32 v171, v148
	v_mul_f32_e32 v150, v145, v151
	v_mul_f32_e32 v151, v147, v171
	v_sub_f32_e32 v148, 1.0, v151
	v_cmp_gt_f32_e32 vcc, s14, v148
	v_cndmask_b32_e64 v151, v151, 0, s[4:5]
	v_bfe_u32 v176, v151, 16, 1
	v_cndmask_b32_e64 v168, 0, 32, vcc
	v_ldexp_f32 v148, v148, v168
	v_log_f32_e32 v148, v148
	v_cndmask_b32_e64 v168, 0, v131, s[0:1]
	v_sub_f32_e32 v167, v167, v168
	v_sub_f32_e32 v168, 1.0, v161
	v_mul_f32_e32 v149, 0x3f317217, v148
	v_fma_f32 v149, v148, s9, -v149
	v_cmp_gt_f32_e64 s[0:1], s14, v168
	v_fmac_f32_e32 v149, 0x3377d1cf, v148
	v_fmac_f32_e32 v149, 0x3f317217, v148
	v_cndmask_b32_e64 v169, 0, 32, s[0:1]
	v_ldexp_f32 v168, v168, v169
	v_cmp_lt_f32_e64 s[2:3], |v148|, s15
	v_log_f32_e32 v168, v168
	v_cndmask_b32_e64 v161, v161, 0, s[4:5]
	v_cndmask_b32_e64 v148, v148, v149, s[2:3]
	v_cndmask_b32_e32 v149, 0, v131, vcc
	v_sub_f32_e32 v169, v148, v149
	v_sub_f32_e32 v149, 1.0, v150
	v_cmp_gt_f32_e32 vcc, s14, v149
	v_mul_f32_e32 v148, 0x3f317217, v168
	v_fma_f32 v148, v168, s9, -v148
	v_cndmask_b32_e64 v170, 0, 32, vcc
	v_ldexp_f32 v149, v149, v170
	v_log_f32_e32 v149, v149
	v_fmac_f32_e32 v148, 0x3377d1cf, v168
	v_fmac_f32_e32 v148, 0x3f317217, v168
	v_cmp_lt_f32_e64 s[2:3], |v168|, s15
	v_cndmask_b32_e32 v171, 0, v131, vcc
	v_cndmask_b32_e64 v150, v150, 0, s[4:5]
	v_cndmask_b32_e64 v148, v168, v148, s[2:3]
	v_cndmask_b32_e64 v168, 0, v131, s[0:1]
	v_sub_f32_e32 v168, v148, v168
	v_mul_f32_e32 v148, 0x3f317217, v149
	v_fma_f32 v148, v149, s9, -v148
	v_fmac_f32_e32 v148, 0x3377d1cf, v149
	v_fmac_f32_e32 v148, 0x3f317217, v149
	v_cmp_lt_f32_e64 s[0:1], |v149|, s15
	v_add3_u32 v176, v151, v176, s16
	v_bfe_u32 v151, v161, 16, 1
	v_cndmask_b32_e64 v170, v149, v148, s[0:1]
	v_pk_add_f32 v[148:149], v[162:163], 1.0 op_sel_hi:[1,0]
	v_sub_f32_e32 v170, v170, v171
	v_rcp_f32_e32 v163, v149
	v_add3_u32 v151, v161, v151, s16
	v_rcp_f32_e32 v174, v148
	v_mul_f32_e32 v162, v140, v163
	v_mul_f32_e32 v163, v142, v174
	v_sub_f32_e32 v148, 1.0, v163
	v_cmp_gt_f32_e64 s[0:1], s14, v148
	v_cndmask_b32_e64 v163, v163, 0, s[4:5]
	s_nop 0
	v_cndmask_b32_e64 v171, 0, 32, s[0:1]
	v_ldexp_f32 v148, v148, v171
	v_log_f32_e32 v171, v148
	s_nop 0
	v_mul_f32_e32 v148, 0x3f317217, v171
	v_fma_f32 v172, v171, s9, -v148
	v_pk_add_f32 v[148:149], v[164:165], 1.0 op_sel_hi:[1,0]
	v_fmac_f32_e32 v172, 0x3377d1cf, v171
	v_rcp_f32_e32 v165, v149
	v_fmac_f32_e32 v172, 0x3f317217, v171
	v_cmp_lt_f32_e64 vcc, |v171|, s15
	s_nop 1
	v_cndmask_b32_e32 v171, v171, v172, vcc
	v_rcp_f32_e32 v175, v148
	v_mul_f32_e32 v149, v141, v165
	v_mul_f32_e32 v148, v143, v175
	v_sub_f32_e32 v165, 1.0, v148
	v_cmp_gt_f32_e32 vcc, s14, v165
	v_cndmask_b32_e64 v148, v148, 0, s[4:5]
	v_bfe_u32 v175, v150, 16, 1
	v_cndmask_b32_e64 v172, 0, 32, vcc
	v_ldexp_f32 v165, v165, v172
	v_log_f32_e32 v165, v165
	v_cndmask_b32_e64 v172, 0, v131, s[0:1]
	v_sub_f32_e32 v171, v171, v172
	v_sub_f32_e32 v172, 1.0, v162
	v_cmp_gt_f32_e64 s[0:1], s14, v172
	v_mul_f32_e32 v164, 0x3f317217, v165
	v_fma_f32 v164, v165, s9, -v164
	v_cndmask_b32_e64 v173, 0, 32, s[0:1]
	v_ldexp_f32 v172, v172, v173
	v_fmac_f32_e32 v164, 0x3377d1cf, v165
	v_log_f32_e32 v172, v172
	v_fmac_f32_e32 v164, 0x3f317217, v165
	v_cmp_lt_f32_e64 s[2:3], |v165|, s15
	v_sub_f32_e32 v173, 1.0, v149
	v_cndmask_b32_e64 v149, v149, 0, s[4:5]
	v_cndmask_b32_e64 v164, v165, v164, s[2:3]
	v_cndmask_b32_e32 v165, 0, v131, vcc
	v_cmp_gt_f32_e32 vcc, s14, v173
	v_sub_f32_e32 v164, v164, v165
	v_mul_f32_e32 v165, 0x3f317217, v172
	v_cndmask_b32_e64 v174, 0, 32, vcc
	v_ldexp_f32 v173, v173, v174
	v_fma_f32 v165, v172, s9, -v165
	v_log_f32_e32 v173, v173
	v_fmac_f32_e32 v165, 0x3377d1cf, v172
	v_fmac_f32_e32 v165, 0x3f317217, v172
	v_cmp_lt_f32_e64 s[2:3], |v172|, s15
	v_cndmask_b32_e64 v162, v162, 0, s[4:5]
	s_nop 0
	v_cndmask_b32_e64 v165, v172, v165, s[2:3]
	v_cndmask_b32_e64 v172, 0, v131, s[0:1]
	v_sub_f32_e32 v165, v165, v172
	v_mul_f32_e32 v172, 0x3f317217, v173
	v_fma_f32 v172, v173, s9, -v172
	v_fmac_f32_e32 v172, 0x3377d1cf, v173
	v_fmac_f32_e32 v172, 0x3f317217, v173
	v_cmp_lt_f32_e64 s[0:1], |v173|, s15
	v_add3_u32 v175, v150, v175, s16
	v_cvt_pk_bf16_f32 v148, v163, v148
	v_cndmask_b32_e64 v172, v173, v172, s[0:1]
	v_cndmask_b32_e32 v173, 0, v131, vcc
	v_sub_f32_e32 v172, v172, v173
	v_cvt_pk_bf16_f32 v149, v162, v149
	v_bfe_u32 v150, v166, 16, 1
	v_add3_u32 v150, v166, v150, s16
	v_lshrrev_b32_e32 v161, 16, v150
	v_lshrrev_b32_e32 v166, 16, v151
	v_mov_b32_e32 v151, v149
	v_mov_b32_e32 v150, v148
	v_and_or_b32 v149, v175, s17, v166
	v_and_or_b32 v148, v176, s17, v161
	global_store_dwordx4 v[138:139], v[148:151], off offset:256
	v_cndmask_b32_e64 v138, v167, 0, s[4:5]
	v_bfe_u32 v139, v138, 16, 1
	v_add3_u32 v138, v138, v139, s16
	v_cndmask_b32_e64 v139, v169, 0, s[4:5]
	v_bfe_u32 v148, v139, 16, 1
	v_lshrrev_b32_e32 v138, 16, v138
	v_add3_u32 v139, v139, v148, s16
	v_and_or_b32 v148, v139, s17, v138
	v_cndmask_b32_e64 v138, v168, 0, s[4:5]
	v_bfe_u32 v139, v138, 16, 1
	v_add3_u32 v138, v138, v139, s16
	v_cndmask_b32_e64 v139, v170, 0, s[4:5]
	v_bfe_u32 v149, v139, 16, 1
	v_lshrrev_b32_e32 v138, 16, v138
	v_add3_u32 v139, v139, v149, s16
	v_and_or_b32 v149, v139, s17, v138
	v_cndmask_b32_e64 v138, v171, 0, s[4:5]
	v_bfe_u32 v139, v138, 16, 1
	v_add3_u32 v138, v138, v139, s16
	v_cndmask_b32_e64 v139, v164, 0, s[4:5]
	v_bfe_u32 v150, v139, 16, 1
	v_lshrrev_b32_e32 v138, 16, v138
	v_add3_u32 v139, v139, v150, s16
	v_and_or_b32 v150, v139, s17, v138
	v_cndmask_b32_e64 v138, v165, 0, s[4:5]
	v_bfe_u32 v139, v138, 16, 1
	v_add3_u32 v138, v138, v139, s16
	v_cndmask_b32_e64 v139, v172, 0, s[4:5]
	v_bfe_u32 v151, v139, 16, 1
	v_lshrrev_b32_e32 v138, 16, v138
	v_add3_u32 v139, v139, v151, s16
	v_and_or_b32 v151, v139, s17, v138
	global_store_dwordx4 v[136:137], v[148:151], off offset:256
	v_mul_f32_e32 v161, 0x3fb8aa3b, v42
	v_exp_f32_e32 v162, v161
	v_mul_f32_e32 v149, 0x3fb8aa3b, v47
	v_mul_f32_e32 v148, 0x3fb8aa3b, v46
	v_exp_f32_e32 v150, v149
	v_mul_f32_e32 v149, 0x3fb8aa3b, v48
	v_exp_f32_e32 v148, v148
	v_exp_f32_e32 v149, v149
	v_mul_f32_e32 v161, 0x3fb8aa3b, v43
	s_movk_i32 s2, 0x1ff0
	v_exp_f32_e32 v164, v161
	v_pk_add_f32 v[148:149], v[148:149], 1.0 op_sel_hi:[1,0]
	v_mul_f32_e32 v161, 0x3fb8aa3b, v44
	v_div_scale_f32 v165, s[4:5], v149, v149, v157
	v_rcp_f32_e32 v166, v165
	v_cmp_gt_i32_e32 vcc, s2, v130
	v_exp_f32_e32 v163, v161
	v_mul_f32_e32 v151, 0x3fb8aa3b, v49
	v_fma_f32 v161, -v165, v166, 1.0
	v_cndmask_b32_e64 v137, v154, 0, vcc
	v_fmac_f32_e32 v166, v161, v166
	v_div_scale_f32 v161, vcc, v157, v149, v157
	v_mul_f32_e32 v167, v161, v166
	v_fma_f32 v168, -v165, v167, v161
	v_fmac_f32_e32 v167, v168, v166
	v_rcp_f32_e32 v169, v148
	v_fma_f32 v161, -v165, v167, v161
	v_div_fmas_f32 v161, v161, v166, v167
	v_exp_f32_e32 v151, v151
	v_mul_f32_e32 v166, v156, v169
	v_sub_f32_e32 v148, 1.0, v166
	v_cmp_gt_f32_e64 s[4:5], s14, v148
	v_div_fixup_f32 v161, v161, v149, v157
	v_add_u32_e32 v136, 0x90, v130
	v_cndmask_b32_e64 v165, 0, 32, s[4:5]
	v_ldexp_f32 v148, v148, v165
	v_log_f32_e32 v167, v148
	v_mul_f32_e32 v148, 0x3fb8aa3b, v45
	v_exp_f32_e32 v165, v148
	s_movk_i32 s0, 0x4070
	v_mul_f32_e32 v148, 0x3f317217, v167
	v_fma_f32 v168, v167, s9, -v148
	v_pk_add_f32 v[148:149], v[150:151], 1.0 op_sel_hi:[1,0]
	v_fmac_f32_e32 v168, 0x3377d1cf, v167
	v_rcp_f32_e32 v151, v149
	v_fmac_f32_e32 v168, 0x3f317217, v167
	v_cmp_lt_f32_e64 vcc, |v167|, s15
	v_add_u32_e32 v137, v137, v136
	v_cmp_gt_i32_e64 s[0:1], s0, v130
	v_cndmask_b32_e32 v167, v167, v168, vcc
	v_rcp_f32_e32 v171, v148
	v_mul_f32_e32 v150, v158, v151
	v_mul_f32_e32 v151, v155, v171
	v_sub_f32_e32 v148, 1.0, v151
	v_cmp_gt_f32_e32 vcc, s14, v148
	v_cmp_gt_i32_e64 s[2:3], s18, v137
	v_ashrrev_i32_e32 v137, 31, v136
	v_cndmask_b32_e64 v168, 0, 32, vcc
	v_ldexp_f32 v148, v148, v168
	v_log_f32_e32 v148, v148
	v_cndmask_b32_e64 v168, 0, v131, s[4:5]
	v_sub_f32_e32 v167, v167, v168
	v_sub_f32_e32 v168, 1.0, v161
	v_mul_f32_e32 v149, 0x3f317217, v148
	v_fma_f32 v149, v148, s9, -v149
	v_cmp_gt_f32_e64 s[4:5], s14, v168
	v_fmac_f32_e32 v149, 0x3377d1cf, v148
	v_fmac_f32_e32 v149, 0x3f317217, v148
	v_cndmask_b32_e64 v169, 0, 32, s[4:5]
	v_ldexp_f32 v168, v168, v169
	v_cmp_lt_f32_e64 s[6:7], |v148|, s15
	v_log_f32_e32 v168, v168
	v_lshlrev_b64 v[136:137], 10, v[136:137]
	v_cndmask_b32_e64 v148, v148, v149, s[6:7]
	v_cndmask_b32_e32 v149, 0, v131, vcc
	v_sub_f32_e32 v169, v148, v149
	v_sub_f32_e32 v149, 1.0, v150
	v_cmp_gt_f32_e32 vcc, s14, v149
	v_mul_f32_e32 v148, 0x3f317217, v168
	v_fma_f32 v148, v168, s9, -v148
	v_cndmask_b32_e64 v170, 0, 32, vcc
	v_ldexp_f32 v149, v149, v170
	v_log_f32_e32 v149, v149
	v_fmac_f32_e32 v148, 0x3377d1cf, v168
	v_fmac_f32_e32 v148, 0x3f317217, v168
	v_cmp_lt_f32_e64 s[6:7], |v168|, s15
	v_lshl_add_u64 v[138:139], v[132:133], 0, v[136:137]
	v_lshl_add_u64 v[136:137], v[134:135], 0, v[136:137]
	v_cndmask_b32_e64 v148, v168, v148, s[6:7]
	v_cndmask_b32_e64 v168, 0, v131, s[4:5]
	v_sub_f32_e32 v168, v148, v168
	v_mul_f32_e32 v148, 0x3f317217, v149
	v_fma_f32 v148, v149, s9, -v148
	v_fmac_f32_e32 v148, 0x3377d1cf, v149
	v_fmac_f32_e32 v148, 0x3f317217, v149
	v_cmp_lt_f32_e64 s[4:5], |v149|, s15
	s_nop 1
	v_cndmask_b32_e64 v148, v149, v148, s[4:5]
	v_cndmask_b32_e32 v149, 0, v131, vcc
	v_sub_f32_e32 v170, v148, v149
	v_pk_add_f32 v[148:149], v[162:163], 1.0 op_sel_hi:[1,0]
	s_nop 0
	v_rcp_f32_e32 v163, v149
	s_and_b64 s[4:5], s[0:1], s[2:3]
	v_cndmask_b32_e64 v151, v151, 0, s[4:5]
	v_cndmask_b32_e64 v150, v150, 0, s[4:5]
	v_rcp_f32_e32 v174, v148
	v_mul_f32_e32 v162, v152, v163
	v_mul_f32_e32 v163, v159, v174
	v_sub_f32_e32 v148, 1.0, v163
	v_cmp_gt_f32_e64 s[0:1], s14, v148
	v_cndmask_b32_e64 v161, v161, 0, s[4:5]
	v_cndmask_b32_e64 v166, v166, 0, s[4:5]
	v_cndmask_b32_e64 v171, 0, 32, s[0:1]
	v_ldexp_f32 v148, v148, v171
	v_log_f32_e32 v171, v148
	v_cndmask_b32_e64 v163, v163, 0, s[4:5]
	v_bfe_u32 v176, v151, 16, 1
	v_add3_u32 v176, v151, v176, s16
	v_mul_f32_e32 v148, 0x3f317217, v171
	v_fma_f32 v172, v171, s9, -v148
	v_pk_add_f32 v[148:149], v[164:165], 1.0 op_sel_hi:[1,0]
	v_fmac_f32_e32 v172, 0x3377d1cf, v171
	v_rcp_f32_e32 v165, v149
	v_fmac_f32_e32 v172, 0x3f317217, v171
	v_cmp_lt_f32_e64 vcc, |v171|, s15
	v_bfe_u32 v151, v161, 16, 1
	v_add3_u32 v151, v161, v151, s16
	v_cndmask_b32_e32 v171, v171, v172, vcc
	v_rcp_f32_e32 v175, v148
	v_mul_f32_e32 v149, v153, v165
	v_mul_f32_e32 v148, v160, v175
	v_sub_f32_e32 v165, 1.0, v148
	v_cmp_gt_f32_e32 vcc, s14, v165
	v_cndmask_b32_e64 v148, v148, 0, s[4:5]
	v_bfe_u32 v175, v150, 16, 1
	v_cndmask_b32_e64 v172, 0, 32, vcc
	v_ldexp_f32 v165, v165, v172
	v_log_f32_e32 v165, v165
	v_cndmask_b32_e64 v172, 0, v131, s[0:1]
	v_sub_f32_e32 v171, v171, v172
	v_sub_f32_e32 v172, 1.0, v162
	v_cmp_gt_f32_e64 s[0:1], s14, v172
	v_mul_f32_e32 v164, 0x3f317217, v165
	v_fma_f32 v164, v165, s9, -v164
	v_cndmask_b32_e64 v173, 0, 32, s[0:1]
	v_ldexp_f32 v172, v172, v173
	v_fmac_f32_e32 v164, 0x3377d1cf, v165
	v_log_f32_e32 v172, v172
	v_fmac_f32_e32 v164, 0x3f317217, v165
	v_cmp_lt_f32_e64 s[2:3], |v165|, s15
	v_sub_f32_e32 v173, 1.0, v149
	v_cndmask_b32_e64 v149, v149, 0, s[4:5]
	v_cndmask_b32_e64 v164, v165, v164, s[2:3]
	v_cndmask_b32_e32 v165, 0, v131, vcc
	v_cmp_gt_f32_e32 vcc, s14, v173
	v_sub_f32_e32 v164, v164, v165
	v_mul_f32_e32 v165, 0x3f317217, v172
	v_cndmask_b32_e64 v174, 0, 32, vcc
	v_ldexp_f32 v173, v173, v174
	v_fma_f32 v165, v172, s9, -v165
	v_log_f32_e32 v173, v173
	v_fmac_f32_e32 v165, 0x3377d1cf, v172
	v_fmac_f32_e32 v165, 0x3f317217, v172
	v_cmp_lt_f32_e64 s[2:3], |v172|, s15
	v_cndmask_b32_e64 v162, v162, 0, s[4:5]
	s_nop 0
	v_cndmask_b32_e64 v165, v172, v165, s[2:3]
	v_cndmask_b32_e64 v172, 0, v131, s[0:1]
	v_sub_f32_e32 v165, v165, v172
	v_mul_f32_e32 v172, 0x3f317217, v173
	v_fma_f32 v172, v173, s9, -v172
	v_fmac_f32_e32 v172, 0x3377d1cf, v173
	v_fmac_f32_e32 v172, 0x3f317217, v173
	v_cmp_lt_f32_e64 s[0:1], |v173|, s15
	v_add3_u32 v175, v150, v175, s16
	v_cvt_pk_bf16_f32 v148, v163, v148
	v_cndmask_b32_e64 v172, v173, v172, s[0:1]
	v_cndmask_b32_e32 v173, 0, v131, vcc
	v_sub_f32_e32 v172, v172, v173
	v_cvt_pk_bf16_f32 v149, v162, v149
	v_bfe_u32 v150, v166, 16, 1
	v_add3_u32 v150, v166, v150, s16
	v_lshrrev_b32_e32 v161, 16, v150
	v_lshrrev_b32_e32 v166, 16, v151
	v_mov_b32_e32 v151, v149
	v_mov_b32_e32 v150, v148
	v_and_or_b32 v149, v175, s17, v166
	v_and_or_b32 v148, v176, s17, v161
	global_store_dwordx4 v[138:139], v[148:151], off
	s_nop 1
	v_cndmask_b32_e64 v148, v167, 0, s[4:5]
	v_bfe_u32 v149, v148, 16, 1
	v_add3_u32 v148, v148, v149, s16
	v_cndmask_b32_e64 v149, v169, 0, s[4:5]
	v_bfe_u32 v150, v149, 16, 1
	v_lshrrev_b32_e32 v148, 16, v148
	v_add3_u32 v149, v149, v150, s16
	v_and_or_b32 v148, v149, s17, v148
	v_cndmask_b32_e64 v149, v168, 0, s[4:5]
	v_bfe_u32 v150, v149, 16, 1
	v_add3_u32 v149, v149, v150, s16
	v_cndmask_b32_e64 v150, v170, 0, s[4:5]
	v_bfe_u32 v151, v150, 16, 1
	v_lshrrev_b32_e32 v149, 16, v149
	v_add3_u32 v150, v150, v151, s16
	v_and_or_b32 v149, v150, s17, v149
	v_cndmask_b32_e64 v150, v171, 0, s[4:5]
	v_bfe_u32 v151, v150, 16, 1
	v_add3_u32 v150, v150, v151, s16
	v_cndmask_b32_e64 v151, v164, 0, s[4:5]
	v_bfe_u32 v161, v151, 16, 1
	v_lshrrev_b32_e32 v150, 16, v150
	v_add3_u32 v151, v151, v161, s16
	v_and_or_b32 v150, v151, s17, v150
	v_cndmask_b32_e64 v151, v165, 0, s[4:5]
	v_bfe_u32 v161, v151, 16, 1
	v_add3_u32 v151, v151, v161, s16
	v_cndmask_b32_e64 v161, v172, 0, s[4:5]
	v_bfe_u32 v162, v161, 16, 1
	v_lshrrev_b32_e32 v151, 16, v151
	v_add3_u32 v161, v161, v162, s16
	v_and_or_b32 v151, v161, s17, v151
	global_store_dwordx4 v[136:137], v[148:151], off
	v_mul_f32_e32 v161, 0x3fb8aa3b, v34
	v_exp_f32_e32 v162, v161
	v_mul_f32_e32 v149, 0x3fb8aa3b, v39
	v_mul_f32_e32 v148, 0x3fb8aa3b, v38
	v_exp_f32_e32 v150, v149
	v_mul_f32_e32 v149, 0x3fb8aa3b, v40
	v_exp_f32_e32 v148, v148
	v_exp_f32_e32 v149, v149
	v_mul_f32_e32 v161, 0x3fb8aa3b, v35
	v_exp_f32_e32 v164, v161
	v_mul_f32_e32 v161, 0x3fb8aa3b, v36
	v_pk_add_f32 v[148:149], v[148:149], 1.0 op_sel_hi:[1,0]
	v_exp_f32_e32 v163, v161
	v_rcp_f32_e32 v166, v149
	v_mul_f32_e32 v151, 0x3fb8aa3b, v41
	v_exp_f32_e32 v151, v151
	v_rcp_f32_e32 v169, v148
	v_mul_f32_e32 v161, v144, v166
	v_mul_f32_e32 v166, v146, v169
	v_sub_f32_e32 v148, 1.0, v166
	v_cmp_gt_f32_e64 s[0:1], s14, v148
	v_cndmask_b32_e64 v166, v166, 0, s[4:5]
	s_nop 0
	v_cndmask_b32_e64 v165, 0, 32, s[0:1]
	v_ldexp_f32 v148, v148, v165
	v_log_f32_e32 v167, v148
	v_mul_f32_e32 v148, 0x3fb8aa3b, v37
	v_exp_f32_e32 v165, v148
	v_mul_f32_e32 v148, 0x3f317217, v167
	v_fma_f32 v168, v167, s9, -v148
	v_pk_add_f32 v[148:149], v[150:151], 1.0 op_sel_hi:[1,0]
	v_fmac_f32_e32 v168, 0x3377d1cf, v167
	v_rcp_f32_e32 v151, v149
	v_fmac_f32_e32 v168, 0x3f317217, v167
	v_cmp_lt_f32_e64 vcc, |v167|, s15
	s_nop 1
	v_cndmask_b32_e32 v167, v167, v168, vcc
	v_rcp_f32_e32 v171, v148
	v_mul_f32_e32 v150, v145, v151
	v_mul_f32_e32 v151, v147, v171
	v_sub_f32_e32 v148, 1.0, v151
	v_cmp_gt_f32_e32 vcc, s14, v148
	v_cndmask_b32_e64 v151, v151, 0, s[4:5]
	v_bfe_u32 v176, v151, 16, 1
	v_cndmask_b32_e64 v168, 0, 32, vcc
	v_ldexp_f32 v148, v148, v168
	v_log_f32_e32 v148, v148
	v_cndmask_b32_e64 v168, 0, v131, s[0:1]
	v_sub_f32_e32 v167, v167, v168
	v_sub_f32_e32 v168, 1.0, v161
	v_mul_f32_e32 v149, 0x3f317217, v148
	v_fma_f32 v149, v148, s9, -v149
	v_cmp_gt_f32_e64 s[0:1], s14, v168
	v_fmac_f32_e32 v149, 0x3377d1cf, v148
	v_fmac_f32_e32 v149, 0x3f317217, v148
	v_cndmask_b32_e64 v169, 0, 32, s[0:1]
	v_ldexp_f32 v168, v168, v169
	v_cmp_lt_f32_e64 s[2:3], |v148|, s15
	v_log_f32_e32 v168, v168
	v_cndmask_b32_e64 v161, v161, 0, s[4:5]
	v_cndmask_b32_e64 v148, v148, v149, s[2:3]
	v_cndmask_b32_e32 v149, 0, v131, vcc
	v_sub_f32_e32 v169, v148, v149
	v_sub_f32_e32 v149, 1.0, v150
	v_cmp_gt_f32_e32 vcc, s14, v149
	v_mul_f32_e32 v148, 0x3f317217, v168
	v_fma_f32 v148, v168, s9, -v148
	v_cndmask_b32_e64 v170, 0, 32, vcc
	v_ldexp_f32 v149, v149, v170
	v_log_f32_e32 v149, v149
	v_fmac_f32_e32 v148, 0x3377d1cf, v168
	v_fmac_f32_e32 v148, 0x3f317217, v168
	v_cmp_lt_f32_e64 s[2:3], |v168|, s15
	v_cndmask_b32_e32 v171, 0, v131, vcc
	v_cndmask_b32_e64 v150, v150, 0, s[4:5]
	v_cndmask_b32_e64 v148, v168, v148, s[2:3]
	v_cndmask_b32_e64 v168, 0, v131, s[0:1]
	v_sub_f32_e32 v168, v148, v168
	v_mul_f32_e32 v148, 0x3f317217, v149
	v_fma_f32 v148, v149, s9, -v148
	v_fmac_f32_e32 v148, 0x3377d1cf, v149
	v_fmac_f32_e32 v148, 0x3f317217, v149
	v_cmp_lt_f32_e64 s[0:1], |v149|, s15
	v_add3_u32 v176, v151, v176, s16
	v_bfe_u32 v151, v161, 16, 1
	v_cndmask_b32_e64 v170, v149, v148, s[0:1]
	v_pk_add_f32 v[148:149], v[162:163], 1.0 op_sel_hi:[1,0]
	v_sub_f32_e32 v170, v170, v171
	v_rcp_f32_e32 v163, v149
	v_add3_u32 v151, v161, v151, s16
	v_rcp_f32_e32 v174, v148
	v_mul_f32_e32 v162, v140, v163
	v_mul_f32_e32 v163, v142, v174
	v_sub_f32_e32 v148, 1.0, v163
	v_cmp_gt_f32_e64 s[0:1], s14, v148
	v_cndmask_b32_e64 v163, v163, 0, s[4:5]
	s_nop 0
	v_cndmask_b32_e64 v171, 0, 32, s[0:1]
	v_ldexp_f32 v148, v148, v171
	v_log_f32_e32 v171, v148
	s_nop 0
	v_mul_f32_e32 v148, 0x3f317217, v171
	v_fma_f32 v172, v171, s9, -v148
	v_pk_add_f32 v[148:149], v[164:165], 1.0 op_sel_hi:[1,0]
	v_fmac_f32_e32 v172, 0x3377d1cf, v171
	v_rcp_f32_e32 v165, v149
	v_fmac_f32_e32 v172, 0x3f317217, v171
	v_cmp_lt_f32_e64 vcc, |v171|, s15
	s_nop 1
	v_cndmask_b32_e32 v171, v171, v172, vcc
	v_rcp_f32_e32 v175, v148
	v_mul_f32_e32 v149, v141, v165
	v_mul_f32_e32 v148, v143, v175
	v_sub_f32_e32 v165, 1.0, v148
	v_cmp_gt_f32_e32 vcc, s14, v165
	v_cndmask_b32_e64 v148, v148, 0, s[4:5]
	v_bfe_u32 v175, v150, 16, 1
	v_cndmask_b32_e64 v172, 0, 32, vcc
	v_ldexp_f32 v165, v165, v172
	v_log_f32_e32 v165, v165
	v_cndmask_b32_e64 v172, 0, v131, s[0:1]
	v_sub_f32_e32 v171, v171, v172
	v_sub_f32_e32 v172, 1.0, v162
	v_cmp_gt_f32_e64 s[0:1], s14, v172
	v_mul_f32_e32 v164, 0x3f317217, v165
	v_fma_f32 v164, v165, s9, -v164
	v_cndmask_b32_e64 v173, 0, 32, s[0:1]
	v_ldexp_f32 v172, v172, v173
	v_fmac_f32_e32 v164, 0x3377d1cf, v165
	v_log_f32_e32 v172, v172
	v_fmac_f32_e32 v164, 0x3f317217, v165
	v_cmp_lt_f32_e64 s[2:3], |v165|, s15
	v_sub_f32_e32 v173, 1.0, v149
	v_cndmask_b32_e64 v149, v149, 0, s[4:5]
	v_cndmask_b32_e64 v164, v165, v164, s[2:3]
	v_cndmask_b32_e32 v165, 0, v131, vcc
	v_cmp_gt_f32_e32 vcc, s14, v173
	v_sub_f32_e32 v164, v164, v165
	v_mul_f32_e32 v165, 0x3f317217, v172
	v_cndmask_b32_e64 v174, 0, 32, vcc
	v_ldexp_f32 v173, v173, v174
	v_fma_f32 v165, v172, s9, -v165
	v_log_f32_e32 v173, v173
	v_fmac_f32_e32 v165, 0x3377d1cf, v172
	v_fmac_f32_e32 v165, 0x3f317217, v172
	v_cmp_lt_f32_e64 s[2:3], |v172|, s15
	v_cndmask_b32_e64 v162, v162, 0, s[4:5]
	s_nop 0
	v_cndmask_b32_e64 v165, v172, v165, s[2:3]
	v_cndmask_b32_e64 v172, 0, v131, s[0:1]
	v_sub_f32_e32 v165, v165, v172
	v_mul_f32_e32 v172, 0x3f317217, v173
	v_fma_f32 v172, v173, s9, -v172
	v_fmac_f32_e32 v172, 0x3377d1cf, v173
	v_fmac_f32_e32 v172, 0x3f317217, v173
	v_cmp_lt_f32_e64 s[0:1], |v173|, s15
	v_add3_u32 v175, v150, v175, s16
	v_cvt_pk_bf16_f32 v148, v163, v148
	v_cndmask_b32_e64 v172, v173, v172, s[0:1]
	v_cndmask_b32_e32 v173, 0, v131, vcc
	v_sub_f32_e32 v172, v172, v173
	v_cvt_pk_bf16_f32 v149, v162, v149
	v_bfe_u32 v150, v166, 16, 1
	v_add3_u32 v150, v166, v150, s16
	v_lshrrev_b32_e32 v161, 16, v150
	v_lshrrev_b32_e32 v166, 16, v151
	v_mov_b32_e32 v151, v149
	v_mov_b32_e32 v150, v148
	v_and_or_b32 v149, v175, s17, v166
	v_and_or_b32 v148, v176, s17, v161
	global_store_dwordx4 v[138:139], v[148:151], off offset:256
	v_cndmask_b32_e64 v138, v167, 0, s[4:5]
	v_bfe_u32 v139, v138, 16, 1
	v_add3_u32 v138, v138, v139, s16
	v_cndmask_b32_e64 v139, v169, 0, s[4:5]
	v_bfe_u32 v148, v139, 16, 1
	v_lshrrev_b32_e32 v138, 16, v138
	v_add3_u32 v139, v139, v148, s16
	v_and_or_b32 v148, v139, s17, v138
	v_cndmask_b32_e64 v138, v168, 0, s[4:5]
	v_bfe_u32 v139, v138, 16, 1
	v_add3_u32 v138, v138, v139, s16
	v_cndmask_b32_e64 v139, v170, 0, s[4:5]
	v_bfe_u32 v149, v139, 16, 1
	v_lshrrev_b32_e32 v138, 16, v138
	v_add3_u32 v139, v139, v149, s16
	v_and_or_b32 v149, v139, s17, v138
	v_cndmask_b32_e64 v138, v171, 0, s[4:5]
	v_bfe_u32 v139, v138, 16, 1
	v_add3_u32 v138, v138, v139, s16
	v_cndmask_b32_e64 v139, v164, 0, s[4:5]
	v_bfe_u32 v150, v139, 16, 1
	v_lshrrev_b32_e32 v138, 16, v138
	v_add3_u32 v139, v139, v150, s16
	v_and_or_b32 v150, v139, s17, v138
	v_cndmask_b32_e64 v138, v165, 0, s[4:5]
	v_bfe_u32 v139, v138, 16, 1
	v_add3_u32 v138, v138, v139, s16
	v_cndmask_b32_e64 v139, v172, 0, s[4:5]
	v_bfe_u32 v151, v139, 16, 1
	v_lshrrev_b32_e32 v138, 16, v138
	v_add3_u32 v139, v139, v151, s16
	v_and_or_b32 v151, v139, s17, v138
	global_store_dwordx4 v[136:137], v[148:151], off offset:256
	v_mul_f32_e32 v161, 0x3fb8aa3b, v26
	v_exp_f32_e32 v162, v161
	v_mul_f32_e32 v149, 0x3fb8aa3b, v31
	v_mul_f32_e32 v148, 0x3fb8aa3b, v30
	v_exp_f32_e32 v150, v149
	v_mul_f32_e32 v149, 0x3fb8aa3b, v32
	v_exp_f32_e32 v148, v148
	v_exp_f32_e32 v149, v149
	v_mul_f32_e32 v161, 0x3fb8aa3b, v27
	s_movk_i32 s2, 0x1fe0
	v_exp_f32_e32 v164, v161
	v_pk_add_f32 v[148:149], v[148:149], 1.0 op_sel_hi:[1,0]
	v_mul_f32_e32 v161, 0x3fb8aa3b, v28
	v_div_scale_f32 v165, s[4:5], v149, v149, v157
	v_rcp_f32_e32 v166, v165
	v_cmp_gt_i32_e32 vcc, s2, v130
	v_exp_f32_e32 v163, v161
	v_mul_f32_e32 v151, 0x3fb8aa3b, v33
	v_fma_f32 v161, -v165, v166, 1.0
	v_cndmask_b32_e64 v137, v154, 0, vcc
	v_fmac_f32_e32 v166, v161, v166
	v_div_scale_f32 v161, vcc, v157, v149, v157
	v_mul_f32_e32 v167, v161, v166
	v_fma_f32 v168, -v165, v167, v161
	v_fmac_f32_e32 v167, v168, v166
	v_rcp_f32_e32 v169, v148
	v_fma_f32 v161, -v165, v167, v161
	v_div_fmas_f32 v161, v161, v166, v167
	v_exp_f32_e32 v151, v151
	v_mul_f32_e32 v166, v156, v169
	v_sub_f32_e32 v148, 1.0, v166
	v_cmp_gt_f32_e64 s[4:5], s14, v148
	v_div_fixup_f32 v161, v161, v149, v157
	v_add_u32_e32 v136, 0xa0, v130
	v_cndmask_b32_e64 v165, 0, 32, s[4:5]
	v_ldexp_f32 v148, v148, v165
	v_log_f32_e32 v167, v148
	v_mul_f32_e32 v148, 0x3fb8aa3b, v29
	v_exp_f32_e32 v165, v148
	s_movk_i32 s0, 0x4060
	v_mul_f32_e32 v148, 0x3f317217, v167
	v_fma_f32 v168, v167, s9, -v148
	v_pk_add_f32 v[148:149], v[150:151], 1.0 op_sel_hi:[1,0]
	v_fmac_f32_e32 v168, 0x3377d1cf, v167
	v_rcp_f32_e32 v151, v149
	v_fmac_f32_e32 v168, 0x3f317217, v167
	v_cmp_lt_f32_e64 vcc, |v167|, s15
	v_add_u32_e32 v137, v137, v136
	v_cmp_gt_i32_e64 s[0:1], s0, v130
	v_cndmask_b32_e32 v167, v167, v168, vcc
	v_rcp_f32_e32 v171, v148
	v_mul_f32_e32 v150, v158, v151
	v_mul_f32_e32 v151, v155, v171
	v_sub_f32_e32 v148, 1.0, v151
	v_cmp_gt_f32_e32 vcc, s14, v148
	v_cmp_gt_i32_e64 s[2:3], s18, v137
	v_ashrrev_i32_e32 v137, 31, v136
	v_cndmask_b32_e64 v168, 0, 32, vcc
	v_ldexp_f32 v148, v148, v168
	v_log_f32_e32 v148, v148
	v_cndmask_b32_e64 v168, 0, v131, s[4:5]
	v_sub_f32_e32 v167, v167, v168
	v_sub_f32_e32 v168, 1.0, v161
	v_mul_f32_e32 v149, 0x3f317217, v148
	v_fma_f32 v149, v148, s9, -v149
	v_cmp_gt_f32_e64 s[4:5], s14, v168
	v_fmac_f32_e32 v149, 0x3377d1cf, v148
	v_fmac_f32_e32 v149, 0x3f317217, v148
	v_cndmask_b32_e64 v169, 0, 32, s[4:5]
	v_ldexp_f32 v168, v168, v169
	v_cmp_lt_f32_e64 s[6:7], |v148|, s15
	v_log_f32_e32 v168, v168
	v_lshlrev_b64 v[136:137], 10, v[136:137]
	v_cndmask_b32_e64 v148, v148, v149, s[6:7]
	v_cndmask_b32_e32 v149, 0, v131, vcc
	v_sub_f32_e32 v169, v148, v149
	v_sub_f32_e32 v149, 1.0, v150
	v_cmp_gt_f32_e32 vcc, s14, v149
	v_mul_f32_e32 v148, 0x3f317217, v168
	v_fma_f32 v148, v168, s9, -v148
	v_cndmask_b32_e64 v170, 0, 32, vcc
	v_ldexp_f32 v149, v149, v170
	v_log_f32_e32 v149, v149
	v_fmac_f32_e32 v148, 0x3377d1cf, v168
	v_fmac_f32_e32 v148, 0x3f317217, v168
	v_cmp_lt_f32_e64 s[6:7], |v168|, s15
	v_lshl_add_u64 v[138:139], v[132:133], 0, v[136:137]
	v_lshl_add_u64 v[136:137], v[134:135], 0, v[136:137]
	v_cndmask_b32_e64 v148, v168, v148, s[6:7]
	v_cndmask_b32_e64 v168, 0, v131, s[4:5]
	v_sub_f32_e32 v168, v148, v168
	v_mul_f32_e32 v148, 0x3f317217, v149
	v_fma_f32 v148, v149, s9, -v148
	v_fmac_f32_e32 v148, 0x3377d1cf, v149
	v_fmac_f32_e32 v148, 0x3f317217, v149
	v_cmp_lt_f32_e64 s[4:5], |v149|, s15
	s_nop 1
	v_cndmask_b32_e64 v148, v149, v148, s[4:5]
	v_cndmask_b32_e32 v149, 0, v131, vcc
	v_sub_f32_e32 v170, v148, v149
	v_pk_add_f32 v[148:149], v[162:163], 1.0 op_sel_hi:[1,0]
	s_nop 0
	v_rcp_f32_e32 v163, v149
	s_and_b64 s[4:5], s[0:1], s[2:3]
	v_cndmask_b32_e64 v151, v151, 0, s[4:5]
	v_cndmask_b32_e64 v150, v150, 0, s[4:5]
	v_rcp_f32_e32 v174, v148
	v_mul_f32_e32 v162, v152, v163
	v_mul_f32_e32 v163, v159, v174
	v_sub_f32_e32 v148, 1.0, v163
	v_cmp_gt_f32_e64 s[0:1], s14, v148
	v_cndmask_b32_e64 v161, v161, 0, s[4:5]
	v_cndmask_b32_e64 v166, v166, 0, s[4:5]
	v_cndmask_b32_e64 v171, 0, 32, s[0:1]
	v_ldexp_f32 v148, v148, v171
	v_log_f32_e32 v171, v148
	v_cndmask_b32_e64 v163, v163, 0, s[4:5]
	v_bfe_u32 v176, v151, 16, 1
	v_add3_u32 v176, v151, v176, s16
	v_mul_f32_e32 v148, 0x3f317217, v171
	v_fma_f32 v172, v171, s9, -v148
	v_pk_add_f32 v[148:149], v[164:165], 1.0 op_sel_hi:[1,0]
	v_fmac_f32_e32 v172, 0x3377d1cf, v171
	v_rcp_f32_e32 v165, v149
	v_fmac_f32_e32 v172, 0x3f317217, v171
	v_cmp_lt_f32_e64 vcc, |v171|, s15
	v_bfe_u32 v151, v161, 16, 1
	v_add3_u32 v151, v161, v151, s16
	v_cndmask_b32_e32 v171, v171, v172, vcc
	v_rcp_f32_e32 v175, v148
	v_mul_f32_e32 v149, v153, v165
	v_mul_f32_e32 v148, v160, v175
	v_sub_f32_e32 v165, 1.0, v148
	v_cmp_gt_f32_e32 vcc, s14, v165
	v_cndmask_b32_e64 v148, v148, 0, s[4:5]
	v_bfe_u32 v175, v150, 16, 1
	v_cndmask_b32_e64 v172, 0, 32, vcc
	v_ldexp_f32 v165, v165, v172
	v_log_f32_e32 v165, v165
	v_cndmask_b32_e64 v172, 0, v131, s[0:1]
	v_sub_f32_e32 v171, v171, v172
	v_sub_f32_e32 v172, 1.0, v162
	v_cmp_gt_f32_e64 s[0:1], s14, v172
	v_mul_f32_e32 v164, 0x3f317217, v165
	v_fma_f32 v164, v165, s9, -v164
	v_cndmask_b32_e64 v173, 0, 32, s[0:1]
	v_ldexp_f32 v172, v172, v173
	v_fmac_f32_e32 v164, 0x3377d1cf, v165
	v_log_f32_e32 v172, v172
	v_fmac_f32_e32 v164, 0x3f317217, v165
	v_cmp_lt_f32_e64 s[2:3], |v165|, s15
	v_sub_f32_e32 v173, 1.0, v149
	v_cndmask_b32_e64 v149, v149, 0, s[4:5]
	v_cndmask_b32_e64 v164, v165, v164, s[2:3]
	v_cndmask_b32_e32 v165, 0, v131, vcc
	v_cmp_gt_f32_e32 vcc, s14, v173
	v_sub_f32_e32 v164, v164, v165
	v_mul_f32_e32 v165, 0x3f317217, v172
	v_cndmask_b32_e64 v174, 0, 32, vcc
	v_ldexp_f32 v173, v173, v174
	v_fma_f32 v165, v172, s9, -v165
	v_log_f32_e32 v173, v173
	v_fmac_f32_e32 v165, 0x3377d1cf, v172
	v_fmac_f32_e32 v165, 0x3f317217, v172
	v_cmp_lt_f32_e64 s[2:3], |v172|, s15
	v_cndmask_b32_e64 v162, v162, 0, s[4:5]
	s_nop 0
	v_cndmask_b32_e64 v165, v172, v165, s[2:3]
	v_cndmask_b32_e64 v172, 0, v131, s[0:1]
	v_sub_f32_e32 v165, v165, v172
	v_mul_f32_e32 v172, 0x3f317217, v173
	v_fma_f32 v172, v173, s9, -v172
	v_fmac_f32_e32 v172, 0x3377d1cf, v173
	v_fmac_f32_e32 v172, 0x3f317217, v173
	v_cmp_lt_f32_e64 s[0:1], |v173|, s15
	v_add3_u32 v175, v150, v175, s16
	v_cvt_pk_bf16_f32 v148, v163, v148
	v_cndmask_b32_e64 v172, v173, v172, s[0:1]
	v_cndmask_b32_e32 v173, 0, v131, vcc
	v_sub_f32_e32 v172, v172, v173
	v_cvt_pk_bf16_f32 v149, v162, v149
	v_bfe_u32 v150, v166, 16, 1
	v_add3_u32 v150, v166, v150, s16
	v_lshrrev_b32_e32 v161, 16, v150
	v_lshrrev_b32_e32 v166, 16, v151
	v_mov_b32_e32 v151, v149
	v_mov_b32_e32 v150, v148
	v_and_or_b32 v149, v175, s17, v166
	v_and_or_b32 v148, v176, s17, v161
	global_store_dwordx4 v[138:139], v[148:151], off
	s_nop 1
	v_cndmask_b32_e64 v148, v167, 0, s[4:5]
	v_bfe_u32 v149, v148, 16, 1
	v_add3_u32 v148, v148, v149, s16
	v_cndmask_b32_e64 v149, v169, 0, s[4:5]
	v_bfe_u32 v150, v149, 16, 1
	v_lshrrev_b32_e32 v148, 16, v148
	v_add3_u32 v149, v149, v150, s16
	v_and_or_b32 v148, v149, s17, v148
	v_cndmask_b32_e64 v149, v168, 0, s[4:5]
	v_bfe_u32 v150, v149, 16, 1
	v_add3_u32 v149, v149, v150, s16
	v_cndmask_b32_e64 v150, v170, 0, s[4:5]
	v_bfe_u32 v151, v150, 16, 1
	v_lshrrev_b32_e32 v149, 16, v149
	v_add3_u32 v150, v150, v151, s16
	v_and_or_b32 v149, v150, s17, v149
	v_cndmask_b32_e64 v150, v171, 0, s[4:5]
	v_bfe_u32 v151, v150, 16, 1
	v_add3_u32 v150, v150, v151, s16
	v_cndmask_b32_e64 v151, v164, 0, s[4:5]
	v_bfe_u32 v161, v151, 16, 1
	v_lshrrev_b32_e32 v150, 16, v150
	v_add3_u32 v151, v151, v161, s16
	v_and_or_b32 v150, v151, s17, v150
	v_cndmask_b32_e64 v151, v165, 0, s[4:5]
	v_bfe_u32 v161, v151, 16, 1
	v_add3_u32 v151, v151, v161, s16
	v_cndmask_b32_e64 v161, v172, 0, s[4:5]
	v_bfe_u32 v162, v161, 16, 1
	v_lshrrev_b32_e32 v151, 16, v151
	v_add3_u32 v161, v161, v162, s16
	v_and_or_b32 v151, v161, s17, v151
	global_store_dwordx4 v[136:137], v[148:151], off
	v_mul_f32_e32 v161, 0x3fb8aa3b, v18
	v_exp_f32_e32 v162, v161
	v_mul_f32_e32 v149, 0x3fb8aa3b, v23
	v_mul_f32_e32 v148, 0x3fb8aa3b, v22
	v_exp_f32_e32 v150, v149
	v_mul_f32_e32 v149, 0x3fb8aa3b, v24
	v_exp_f32_e32 v148, v148
	v_exp_f32_e32 v149, v149
	v_mul_f32_e32 v161, 0x3fb8aa3b, v19
	v_exp_f32_e32 v164, v161
	v_mul_f32_e32 v161, 0x3fb8aa3b, v20
	v_pk_add_f32 v[148:149], v[148:149], 1.0 op_sel_hi:[1,0]
	v_exp_f32_e32 v163, v161
	v_rcp_f32_e32 v166, v149
	v_mul_f32_e32 v151, 0x3fb8aa3b, v25
	v_exp_f32_e32 v151, v151
	v_rcp_f32_e32 v169, v148
	v_mul_f32_e32 v161, v144, v166
	v_mul_f32_e32 v166, v146, v169
	v_sub_f32_e32 v148, 1.0, v166
	v_cmp_gt_f32_e64 s[0:1], s14, v148
	v_cndmask_b32_e64 v166, v166, 0, s[4:5]
	s_nop 0
	v_cndmask_b32_e64 v165, 0, 32, s[0:1]
	v_ldexp_f32 v148, v148, v165
	v_log_f32_e32 v167, v148
	v_mul_f32_e32 v148, 0x3fb8aa3b, v21
	v_exp_f32_e32 v165, v148
	v_mul_f32_e32 v148, 0x3f317217, v167
	v_fma_f32 v168, v167, s9, -v148
	v_pk_add_f32 v[148:149], v[150:151], 1.0 op_sel_hi:[1,0]
	v_fmac_f32_e32 v168, 0x3377d1cf, v167
	v_rcp_f32_e32 v151, v149
	v_fmac_f32_e32 v168, 0x3f317217, v167
	v_cmp_lt_f32_e64 vcc, |v167|, s15
	s_nop 1
	v_cndmask_b32_e32 v167, v167, v168, vcc
	v_rcp_f32_e32 v171, v148
	v_mul_f32_e32 v150, v145, v151
	v_mul_f32_e32 v151, v147, v171
	v_sub_f32_e32 v148, 1.0, v151
	v_cmp_gt_f32_e32 vcc, s14, v148
	v_cndmask_b32_e64 v151, v151, 0, s[4:5]
	v_bfe_u32 v176, v151, 16, 1
	v_cndmask_b32_e64 v168, 0, 32, vcc
	v_ldexp_f32 v148, v148, v168
	v_log_f32_e32 v148, v148
	v_cndmask_b32_e64 v168, 0, v131, s[0:1]
	v_sub_f32_e32 v167, v167, v168
	v_sub_f32_e32 v168, 1.0, v161
	v_mul_f32_e32 v149, 0x3f317217, v148
	v_fma_f32 v149, v148, s9, -v149
	v_cmp_gt_f32_e64 s[0:1], s14, v168
	v_fmac_f32_e32 v149, 0x3377d1cf, v148
	v_fmac_f32_e32 v149, 0x3f317217, v148
	v_cndmask_b32_e64 v169, 0, 32, s[0:1]
	v_ldexp_f32 v168, v168, v169
	v_cmp_lt_f32_e64 s[2:3], |v148|, s15
	v_log_f32_e32 v168, v168
	v_cndmask_b32_e64 v161, v161, 0, s[4:5]
	v_cndmask_b32_e64 v148, v148, v149, s[2:3]
	v_cndmask_b32_e32 v149, 0, v131, vcc
	v_sub_f32_e32 v169, v148, v149
	v_sub_f32_e32 v149, 1.0, v150
	v_cmp_gt_f32_e32 vcc, s14, v149
	v_mul_f32_e32 v148, 0x3f317217, v168
	v_fma_f32 v148, v168, s9, -v148
	v_cndmask_b32_e64 v170, 0, 32, vcc
	v_ldexp_f32 v149, v149, v170
	v_log_f32_e32 v149, v149
	v_fmac_f32_e32 v148, 0x3377d1cf, v168
	v_fmac_f32_e32 v148, 0x3f317217, v168
	v_cmp_lt_f32_e64 s[2:3], |v168|, s15
	v_cndmask_b32_e32 v171, 0, v131, vcc
	v_cndmask_b32_e64 v150, v150, 0, s[4:5]
	v_cndmask_b32_e64 v148, v168, v148, s[2:3]
	v_cndmask_b32_e64 v168, 0, v131, s[0:1]
	v_sub_f32_e32 v168, v148, v168
	v_mul_f32_e32 v148, 0x3f317217, v149
	v_fma_f32 v148, v149, s9, -v148
	v_fmac_f32_e32 v148, 0x3377d1cf, v149
	v_fmac_f32_e32 v148, 0x3f317217, v149
	v_cmp_lt_f32_e64 s[0:1], |v149|, s15
	v_add3_u32 v176, v151, v176, s16
	v_bfe_u32 v151, v161, 16, 1
	v_cndmask_b32_e64 v170, v149, v148, s[0:1]
	v_pk_add_f32 v[148:149], v[162:163], 1.0 op_sel_hi:[1,0]
	v_sub_f32_e32 v170, v170, v171
	v_rcp_f32_e32 v163, v149
	v_add3_u32 v151, v161, v151, s16
	v_rcp_f32_e32 v174, v148
	v_mul_f32_e32 v162, v140, v163
	v_mul_f32_e32 v163, v142, v174
	v_sub_f32_e32 v148, 1.0, v163
	v_cmp_gt_f32_e64 s[0:1], s14, v148
	v_cndmask_b32_e64 v163, v163, 0, s[4:5]
	s_nop 0
	v_cndmask_b32_e64 v171, 0, 32, s[0:1]
	v_ldexp_f32 v148, v148, v171
	v_log_f32_e32 v171, v148
	s_nop 0
	v_mul_f32_e32 v148, 0x3f317217, v171
	v_fma_f32 v172, v171, s9, -v148
	v_pk_add_f32 v[148:149], v[164:165], 1.0 op_sel_hi:[1,0]
	v_fmac_f32_e32 v172, 0x3377d1cf, v171
	v_rcp_f32_e32 v165, v149
	v_fmac_f32_e32 v172, 0x3f317217, v171
	v_cmp_lt_f32_e64 vcc, |v171|, s15
	s_nop 1
	v_cndmask_b32_e32 v171, v171, v172, vcc
	v_rcp_f32_e32 v175, v148
	v_mul_f32_e32 v149, v141, v165
	v_mul_f32_e32 v148, v143, v175
	v_sub_f32_e32 v165, 1.0, v148
	v_cmp_gt_f32_e32 vcc, s14, v165
	v_cndmask_b32_e64 v148, v148, 0, s[4:5]
	v_bfe_u32 v175, v150, 16, 1
	v_cndmask_b32_e64 v172, 0, 32, vcc
	v_ldexp_f32 v165, v165, v172
	v_log_f32_e32 v165, v165
	v_cndmask_b32_e64 v172, 0, v131, s[0:1]
	v_sub_f32_e32 v171, v171, v172
	v_sub_f32_e32 v172, 1.0, v162
	v_cmp_gt_f32_e64 s[0:1], s14, v172
	v_mul_f32_e32 v164, 0x3f317217, v165
	v_fma_f32 v164, v165, s9, -v164
	v_cndmask_b32_e64 v173, 0, 32, s[0:1]
	v_ldexp_f32 v172, v172, v173
	v_fmac_f32_e32 v164, 0x3377d1cf, v165
	v_log_f32_e32 v172, v172
	v_fmac_f32_e32 v164, 0x3f317217, v165
	v_cmp_lt_f32_e64 s[2:3], |v165|, s15
	v_sub_f32_e32 v173, 1.0, v149
	v_cndmask_b32_e64 v149, v149, 0, s[4:5]
	v_cndmask_b32_e64 v164, v165, v164, s[2:3]
	v_cndmask_b32_e32 v165, 0, v131, vcc
	v_cmp_gt_f32_e32 vcc, s14, v173
	v_sub_f32_e32 v164, v164, v165
	v_mul_f32_e32 v165, 0x3f317217, v172
	v_cndmask_b32_e64 v174, 0, 32, vcc
	v_ldexp_f32 v173, v173, v174
	v_fma_f32 v165, v172, s9, -v165
	v_log_f32_e32 v173, v173
	v_fmac_f32_e32 v165, 0x3377d1cf, v172
	v_fmac_f32_e32 v165, 0x3f317217, v172
	v_cmp_lt_f32_e64 s[2:3], |v172|, s15
	v_cndmask_b32_e64 v162, v162, 0, s[4:5]
	s_nop 0
	v_cndmask_b32_e64 v165, v172, v165, s[2:3]
	v_cndmask_b32_e64 v172, 0, v131, s[0:1]
	v_sub_f32_e32 v165, v165, v172
	v_mul_f32_e32 v172, 0x3f317217, v173
	v_fma_f32 v172, v173, s9, -v172
	v_fmac_f32_e32 v172, 0x3377d1cf, v173
	v_fmac_f32_e32 v172, 0x3f317217, v173
	v_cmp_lt_f32_e64 s[0:1], |v173|, s15
	v_add3_u32 v175, v150, v175, s16
	v_cvt_pk_bf16_f32 v148, v163, v148
	v_cndmask_b32_e64 v172, v173, v172, s[0:1]
	v_cndmask_b32_e32 v173, 0, v131, vcc
	v_sub_f32_e32 v172, v172, v173
	v_cvt_pk_bf16_f32 v149, v162, v149
	v_bfe_u32 v150, v166, 16, 1
	v_add3_u32 v150, v166, v150, s16
	v_lshrrev_b32_e32 v161, 16, v150
	v_lshrrev_b32_e32 v166, 16, v151
	v_mov_b32_e32 v151, v149
	v_mov_b32_e32 v150, v148
	v_and_or_b32 v149, v175, s17, v166
	v_and_or_b32 v148, v176, s17, v161
	global_store_dwordx4 v[138:139], v[148:151], off offset:256
	v_cndmask_b32_e64 v138, v167, 0, s[4:5]
	v_bfe_u32 v139, v138, 16, 1
	v_add3_u32 v138, v138, v139, s16
	v_cndmask_b32_e64 v139, v169, 0, s[4:5]
	v_bfe_u32 v148, v139, 16, 1
	v_lshrrev_b32_e32 v138, 16, v138
	v_add3_u32 v139, v139, v148, s16
	v_and_or_b32 v148, v139, s17, v138
	v_cndmask_b32_e64 v138, v168, 0, s[4:5]
	v_bfe_u32 v139, v138, 16, 1
	v_add3_u32 v138, v138, v139, s16
	v_cndmask_b32_e64 v139, v170, 0, s[4:5]
	v_bfe_u32 v149, v139, 16, 1
	v_lshrrev_b32_e32 v138, 16, v138
	v_add3_u32 v139, v139, v149, s16
	v_and_or_b32 v149, v139, s17, v138
	v_cndmask_b32_e64 v138, v171, 0, s[4:5]
	v_bfe_u32 v139, v138, 16, 1
	v_add3_u32 v138, v138, v139, s16
	v_cndmask_b32_e64 v139, v164, 0, s[4:5]
	v_bfe_u32 v150, v139, 16, 1
	v_lshrrev_b32_e32 v138, 16, v138
	v_add3_u32 v139, v139, v150, s16
	v_and_or_b32 v150, v139, s17, v138
	v_cndmask_b32_e64 v138, v165, 0, s[4:5]
	v_bfe_u32 v139, v138, 16, 1
	v_add3_u32 v138, v138, v139, s16
	v_cndmask_b32_e64 v139, v172, 0, s[4:5]
	v_bfe_u32 v151, v139, 16, 1
	v_lshrrev_b32_e32 v138, 16, v138
	v_add3_u32 v139, v139, v151, s16
	s_movk_i32 s2, 0x1fd0
	v_and_or_b32 v151, v139, s17, v138
	v_cmp_gt_i32_e32 vcc, s2, v130
	global_store_dwordx4 v[136:137], v[148:151], off offset:256
	v_add_u32_e32 v136, 0xb0, v130
	v_cndmask_b32_e64 v137, v154, 0, vcc
	v_add_u32_e32 v137, v137, v136
	v_cmp_gt_i32_e64 s[2:3], s18, v137
	v_ashrrev_i32_e32 v137, 31, v136
	v_lshlrev_b64 v[138:139], 10, v[136:137]
	v_lshl_add_u64 v[136:137], v[132:133], 0, v[138:139]
	v_lshl_add_u64 v[132:133], v[134:135], 0, v[138:139]
	v_mul_f32_e32 v135, 0x3fb8aa3b, v15
	v_mul_f32_e32 v134, 0x3fb8aa3b, v14
	v_exp_f32_e32 v138, v135
	v_mul_f32_e32 v135, 0x3fb8aa3b, v16
	v_exp_f32_e32 v134, v134
	v_exp_f32_e32 v135, v135
	v_mul_f32_e32 v139, 0x3fb8aa3b, v17
	v_exp_f32_e32 v139, v139
	v_mul_f32_e32 v149, 0x3fb8aa3b, v11
	v_pk_add_f32 v[134:135], v[134:135], 1.0 op_sel_hi:[1,0]
	v_mul_f32_e32 v148, 0x3fb8aa3b, v10
	v_rcp_f32_e32 v154, v135
	v_exp_f32_e32 v150, v149
	v_mul_f32_e32 v149, 0x3fb8aa3b, v12
	v_exp_f32_e32 v148, v148
	v_rcp_f32_e32 v164, v134
	v_mul_f32_e32 v154, v157, v154
	v_mul_f32_e32 v156, v156, v164
	v_sub_f32_e32 v134, 1.0, v156
	v_cmp_gt_f32_e64 s[4:5], s14, v134
	v_exp_f32_e32 v149, v149
	s_movk_i32 s0, 0x4050
	v_cndmask_b32_e64 v151, 0, 32, s[4:5]
	v_ldexp_f32 v134, v134, v151
	v_log_f32_e32 v161, v134
	v_mul_f32_e32 v134, 0x3fb8aa3b, v13
	v_exp_f32_e32 v151, v134
	v_cmp_gt_i32_e64 s[0:1], s0, v130
	v_mul_f32_e32 v134, 0x3f317217, v161
	v_fma_f32 v157, v161, s9, -v134
	v_pk_add_f32 v[134:135], v[138:139], 1.0 op_sel_hi:[1,0]
	v_fmac_f32_e32 v157, 0x3377d1cf, v161
	v_rcp_f32_e32 v139, v135
	v_fmac_f32_e32 v157, 0x3f317217, v161
	v_cmp_lt_f32_e64 vcc, |v161|, s15
	s_nop 1
	v_cndmask_b32_e32 v157, v161, v157, vcc
	v_rcp_f32_e32 v164, v134
	v_mul_f32_e32 v138, v158, v139
	v_mul_f32_e32 v139, v155, v164
	v_sub_f32_e32 v134, 1.0, v139
	v_cmp_gt_f32_e32 vcc, s14, v134
	s_nop 1
	v_cndmask_b32_e64 v155, 0, 32, vcc
	v_ldexp_f32 v134, v134, v155
	v_log_f32_e32 v134, v134
	v_cndmask_b32_e64 v155, 0, v131, s[4:5]
	v_sub_f32_e32 v155, v157, v155
	v_sub_f32_e32 v157, 1.0, v154
	v_mul_f32_e32 v135, 0x3f317217, v134
	v_fma_f32 v135, v134, s9, -v135
	v_cmp_gt_f32_e64 s[4:5], s14, v157
	v_fmac_f32_e32 v135, 0x3377d1cf, v134
	v_fmac_f32_e32 v135, 0x3f317217, v134
	v_cndmask_b32_e64 v158, 0, 32, s[4:5]
	v_ldexp_f32 v157, v157, v158
	v_cmp_lt_f32_e64 s[6:7], |v134|, s15
	v_log_f32_e32 v157, v157
	s_nop 0
	v_cndmask_b32_e64 v134, v134, v135, s[6:7]
	v_cndmask_b32_e32 v135, 0, v131, vcc
	v_sub_f32_e32 v158, v134, v135
	v_sub_f32_e32 v135, 1.0, v138
	v_cmp_gt_f32_e32 vcc, s14, v135
	v_mul_f32_e32 v134, 0x3f317217, v157
	v_fma_f32 v134, v157, s9, -v134
	v_cndmask_b32_e64 v161, 0, 32, vcc
	v_ldexp_f32 v135, v135, v161
	v_log_f32_e32 v135, v135
	v_fmac_f32_e32 v134, 0x3377d1cf, v157
	v_fmac_f32_e32 v134, 0x3f317217, v157
	v_cmp_lt_f32_e64 s[6:7], |v157|, s15
	s_nop 1
	v_cndmask_b32_e64 v134, v157, v134, s[6:7]
	v_cndmask_b32_e64 v157, 0, v131, s[4:5]
	v_sub_f32_e32 v157, v134, v157
	v_mul_f32_e32 v134, 0x3f317217, v135
	v_fma_f32 v134, v135, s9, -v134
	v_fmac_f32_e32 v134, 0x3377d1cf, v135
	v_fmac_f32_e32 v134, 0x3f317217, v135
	v_cmp_lt_f32_e64 s[4:5], |v135|, s15
	s_nop 1
	v_cndmask_b32_e64 v134, v135, v134, s[4:5]
	v_cndmask_b32_e32 v135, 0, v131, vcc
	v_sub_f32_e32 v161, v134, v135
	v_pk_add_f32 v[134:135], v[148:149], 1.0 op_sel_hi:[1,0]
	s_nop 0
	v_rcp_f32_e32 v149, v135
	s_and_b64 s[4:5], s[0:1], s[2:3]
	v_cndmask_b32_e64 v138, v138, 0, s[4:5]
	v_cndmask_b32_e64 v139, v139, 0, s[4:5]
	v_rcp_f32_e32 v165, v134
	v_mul_f32_e32 v148, v152, v149
	v_mul_f32_e32 v149, v159, v165
	v_sub_f32_e32 v134, 1.0, v149
	v_cmp_gt_f32_e64 s[0:1], s14, v134
	v_cndmask_b32_e64 v149, v149, 0, s[4:5]
	v_cndmask_b32_e64 v156, v156, 0, s[4:5]
	v_cndmask_b32_e64 v159, 0, 32, s[0:1]
	v_ldexp_f32 v134, v134, v159
	v_log_f32_e32 v159, v134
	v_cndmask_b32_e64 v154, v154, 0, s[4:5]
	v_mul_f32_e32 v134, 0x3f317217, v159
	v_fma_f32 v152, v159, s9, -v134
	v_pk_add_f32 v[134:135], v[150:151], 1.0 op_sel_hi:[1,0]
	v_fmac_f32_e32 v152, 0x3377d1cf, v159
	v_rcp_f32_e32 v151, v135
	v_fmac_f32_e32 v152, 0x3f317217, v159
	v_cmp_lt_f32_e64 vcc, |v159|, s15
	s_nop 1
	v_cndmask_b32_e32 v152, v159, v152, vcc
	v_rcp_f32_e32 v164, v134
	v_mul_f32_e32 v135, v153, v151
	v_mul_f32_e32 v134, v160, v164
	v_sub_f32_e32 v151, 1.0, v134
	v_cmp_gt_f32_e32 vcc, s14, v151
	v_sub_f32_e32 v153, 1.0, v148
	v_bfe_u32 v162, v138, 16, 1
	v_cndmask_b32_e64 v159, 0, 32, vcc
	v_ldexp_f32 v151, v151, v159
	v_log_f32_e32 v151, v151
	v_cndmask_b32_e64 v159, 0, v131, s[0:1]
	v_cmp_gt_f32_e64 s[0:1], s14, v153
	v_sub_f32_e32 v152, v152, v159
	v_mul_f32_e32 v150, 0x3f317217, v151
	v_fma_f32 v150, v151, s9, -v150
	v_fmac_f32_e32 v150, 0x3377d1cf, v151
	v_cndmask_b32_e64 v159, 0, 32, s[0:1]
	v_fmac_f32_e32 v150, 0x3f317217, v151
	v_ldexp_f32 v153, v153, v159
	v_cmp_lt_f32_e64 s[2:3], |v151|, s15
	v_log_f32_e32 v153, v153
	v_cndmask_b32_e64 v148, v148, 0, s[4:5]
	v_cndmask_b32_e64 v150, v151, v150, s[2:3]
	v_cndmask_b32_e32 v151, 0, v131, vcc
	v_sub_f32_e32 v159, v150, v151
	v_sub_f32_e32 v151, 1.0, v135
	v_cmp_gt_f32_e32 vcc, s14, v151
	v_mul_f32_e32 v150, 0x3f317217, v153
	v_fma_f32 v150, v153, s9, -v150
	v_cndmask_b32_e64 v160, 0, 32, vcc
	v_ldexp_f32 v151, v151, v160
	v_log_f32_e32 v151, v151
	v_fmac_f32_e32 v150, 0x3377d1cf, v153
	v_fmac_f32_e32 v150, 0x3f317217, v153
	v_cmp_lt_f32_e64 s[2:3], |v153|, s15
	v_cndmask_b32_e64 v135, v135, 0, s[4:5]
	v_cndmask_b32_e64 v134, v134, 0, s[4:5]
	v_cndmask_b32_e64 v150, v153, v150, s[2:3]
	v_cndmask_b32_e64 v153, 0, v131, s[0:1]
	v_sub_f32_e32 v153, v150, v153
	v_mul_f32_e32 v150, 0x3f317217, v151
	v_fma_f32 v150, v151, s9, -v150
	v_fmac_f32_e32 v150, 0x3377d1cf, v151
	v_fmac_f32_e32 v150, 0x3f317217, v151
	v_cmp_lt_f32_e64 s[0:1], |v151|, s15
	v_bfe_u32 v163, v139, 16, 1
	v_add3_u32 v138, v138, v162, s16
	v_cndmask_b32_e64 v150, v151, v150, s[0:1]
	v_cndmask_b32_e32 v151, 0, v131, vcc
	v_sub_f32_e32 v160, v150, v151
	v_add3_u32 v139, v139, v163, s16
	v_cvt_pk_bf16_f32 v135, v148, v135
	v_bfe_u32 v150, v156, 16, 1
	v_cvt_pk_bf16_f32 v134, v149, v134
	v_bfe_u32 v151, v154, 16, 1
	v_add3_u32 v150, v156, v150, s16
	v_add3_u32 v151, v154, v151, s16
	v_lshrrev_b32_e32 v154, 16, v150
	v_mov_b32_e32 v150, v134
	v_cndmask_b32_e64 v134, v155, 0, s[4:5]
	v_lshrrev_b32_e32 v156, 16, v151
	v_mov_b32_e32 v151, v135
	v_bfe_u32 v135, v134, 16, 1
	v_add3_u32 v134, v134, v135, s16
	v_cndmask_b32_e64 v135, v158, 0, s[4:5]
	v_and_or_b32 v149, v138, s17, v156
	v_bfe_u32 v138, v135, 16, 1
	v_and_or_b32 v148, v139, s17, v154
	v_lshrrev_b32_e32 v134, 16, v134
	v_add3_u32 v135, v135, v138, s16
	global_store_dwordx4 v[136:137], v[148:151], off
	v_mul_f32_e32 v139, 0x3fb8aa3b, v9
	v_exp_f32_e32 v139, v139
	v_and_or_b32 v148, v135, s17, v134
	v_cndmask_b32_e64 v134, v157, 0, s[4:5]
	v_bfe_u32 v135, v134, 16, 1
	v_add3_u32 v134, v134, v135, s16
	v_cndmask_b32_e64 v135, v161, 0, s[4:5]
	v_bfe_u32 v138, v135, 16, 1
	v_lshrrev_b32_e32 v134, 16, v134
	v_add3_u32 v135, v135, v138, s16
	v_and_or_b32 v149, v135, s17, v134
	v_cndmask_b32_e64 v134, v152, 0, s[4:5]
	v_bfe_u32 v135, v134, 16, 1
	v_add3_u32 v134, v134, v135, s16
	v_cndmask_b32_e64 v135, v159, 0, s[4:5]
	v_bfe_u32 v138, v135, 16, 1
	v_lshrrev_b32_e32 v134, 16, v134
	v_add3_u32 v135, v135, v138, s16
	v_and_or_b32 v150, v135, s17, v134
	v_cndmask_b32_e64 v134, v153, 0, s[4:5]
	v_bfe_u32 v135, v134, 16, 1
	v_add3_u32 v134, v134, v135, s16
	v_cndmask_b32_e64 v135, v160, 0, s[4:5]
	v_bfe_u32 v138, v135, 16, 1
	v_lshrrev_b32_e32 v134, 16, v134
	v_add3_u32 v135, v135, v138, s16
	v_and_or_b32 v151, v135, s17, v134
	v_mul_f32_e32 v135, 0x3fb8aa3b, v7
	v_mul_f32_e32 v134, 0x3fb8aa3b, v6
	v_exp_f32_e32 v138, v135
	v_mul_f32_e32 v135, 0x3fb8aa3b, v8
	v_exp_f32_e32 v134, v134
	v_exp_f32_e32 v135, v135
	global_store_dwordx4 v[132:133], v[148:151], off
	v_pk_add_f32 v[134:135], v[134:135], 1.0 op_sel_hi:[1,0]
	s_nop 0
	v_rcp_f32_e32 v152, v135
	v_mul_f32_e32 v149, 0x3fb8aa3b, v3
	v_mul_f32_e32 v148, 0x3fb8aa3b, v2
	v_exp_f32_e32 v150, v149
	v_rcp_f32_e32 v156, v134
	v_mul_f32_e32 v144, v144, v152
	v_mul_f32_e32 v146, v146, v156
	v_sub_f32_e32 v134, 1.0, v146
	v_cmp_gt_f32_e64 s[0:1], s14, v134
	v_mul_f32_e32 v149, 0x3fb8aa3b, v4
	v_exp_f32_e32 v148, v148
	v_cndmask_b32_e64 v151, 0, 32, s[0:1]
	v_ldexp_f32 v134, v134, v151
	v_log_f32_e32 v153, v134
	v_mul_f32_e32 v134, 0x3fb8aa3b, v5
	v_exp_f32_e32 v151, v134
	v_exp_f32_e32 v149, v149
	v_mul_f32_e32 v134, 0x3f317217, v153
	v_fma_f32 v152, v153, s9, -v134
	v_pk_add_f32 v[134:135], v[138:139], 1.0 op_sel_hi:[1,0]
	v_fmac_f32_e32 v152, 0x3377d1cf, v153
	v_rcp_f32_e32 v139, v135
	v_fmac_f32_e32 v152, 0x3f317217, v153
	v_cmp_lt_f32_e64 vcc, |v153|, s15
	v_cndmask_b32_e64 v146, v146, 0, s[4:5]
	s_nop 0
	v_cndmask_b32_e32 v152, v153, v152, vcc
	v_rcp_f32_e32 v156, v134
	v_mul_f32_e32 v138, v145, v139
	v_mul_f32_e32 v139, v147, v156
	v_sub_f32_e32 v134, 1.0, v139
	v_cmp_gt_f32_e32 vcc, s14, v134
	v_sub_f32_e32 v145, 1.0, v144
	v_cndmask_b32_e64 v139, v139, 0, s[4:5]
	v_cndmask_b32_e64 v147, 0, 32, vcc
	v_ldexp_f32 v134, v134, v147
	v_log_f32_e32 v134, v134
	v_cndmask_b32_e64 v147, 0, v131, s[0:1]
	v_cmp_gt_f32_e64 s[0:1], s14, v145
	v_sub_f32_e32 v147, v152, v147
	v_mul_f32_e32 v135, 0x3f317217, v134
	v_fma_f32 v135, v134, s9, -v135
	v_fmac_f32_e32 v135, 0x3377d1cf, v134
	v_cndmask_b32_e64 v152, 0, 32, s[0:1]
	v_fmac_f32_e32 v135, 0x3f317217, v134
	v_ldexp_f32 v145, v145, v152
	v_cmp_lt_f32_e64 s[2:3], |v134|, s15
	v_log_f32_e32 v145, v145
	v_cndmask_b32_e64 v144, v144, 0, s[4:5]
	v_cndmask_b32_e64 v134, v134, v135, s[2:3]
	v_cndmask_b32_e32 v135, 0, v131, vcc
	v_sub_f32_e32 v152, v134, v135
	v_sub_f32_e32 v135, 1.0, v138
	v_cmp_gt_f32_e32 vcc, s14, v135
	v_mul_f32_e32 v134, 0x3f317217, v145
	v_fma_f32 v134, v145, s9, -v134
	v_cndmask_b32_e64 v153, 0, 32, vcc
	v_ldexp_f32 v135, v135, v153
	v_log_f32_e32 v135, v135
	v_fmac_f32_e32 v134, 0x3377d1cf, v145
	v_fmac_f32_e32 v134, 0x3f317217, v145
	v_cmp_lt_f32_e64 s[2:3], |v145|, s15
	v_cndmask_b32_e32 v154, 0, v131, vcc
	v_cndmask_b32_e64 v138, v138, 0, s[4:5]
	v_cndmask_b32_e64 v134, v145, v134, s[2:3]
	v_cndmask_b32_e64 v145, 0, v131, s[0:1]
	v_sub_f32_e32 v145, v134, v145
	v_mul_f32_e32 v134, 0x3f317217, v135
	v_fma_f32 v134, v135, s9, -v134
	v_fmac_f32_e32 v134, 0x3377d1cf, v135
	v_fmac_f32_e32 v134, 0x3f317217, v135
	v_cmp_lt_f32_e64 s[0:1], |v135|, s15
	s_nop 1
	v_cndmask_b32_e64 v153, v135, v134, s[0:1]
	v_pk_add_f32 v[134:135], v[148:149], 1.0 op_sel_hi:[1,0]
	v_sub_f32_e32 v153, v153, v154
	v_rcp_f32_e32 v149, v135
	s_nop 0
	v_rcp_f32_e32 v157, v134
	v_mul_f32_e32 v140, v140, v149
	v_mul_f32_e32 v142, v142, v157
	v_sub_f32_e32 v134, 1.0, v142
	v_cmp_gt_f32_e64 s[0:1], s14, v134
	s_nop 1
	v_cndmask_b32_e64 v149, 0, 32, s[0:1]
	v_ldexp_f32 v134, v134, v149
	v_log_f32_e32 v149, v134
	s_nop 0
	v_mul_f32_e32 v134, 0x3f317217, v149
	v_fma_f32 v148, v149, s9, -v134
	v_pk_add_f32 v[134:135], v[150:151], 1.0 op_sel_hi:[1,0]
	v_fmac_f32_e32 v148, 0x3377d1cf, v149
	v_rcp_f32_e32 v151, v135
	v_fmac_f32_e32 v148, 0x3f317217, v149
	v_cmp_lt_f32_e64 vcc, |v149|, s15
	s_nop 1
	v_cndmask_b32_e32 v148, v149, v148, vcc
	v_rcp_f32_e32 v156, v134
	v_mul_f32_e32 v135, v141, v151
	v_mul_f32_e32 v134, v143, v156
	v_sub_f32_e32 v143, 1.0, v134
	v_cmp_gt_f32_e32 vcc, s14, v143
	v_sub_f32_e32 v149, 1.0, v140
	v_cndmask_b32_e64 v134, v134, 0, s[4:5]
	v_cndmask_b32_e64 v150, 0, 32, vcc
	v_ldexp_f32 v143, v143, v150
	v_log_f32_e32 v143, v143
	v_cndmask_b32_e64 v150, 0, v131, s[0:1]
	v_cmp_gt_f32_e64 s[0:1], s14, v149
	v_sub_f32_e32 v148, v148, v150
	v_mul_f32_e32 v141, 0x3f317217, v143
	v_cndmask_b32_e64 v150, 0, 32, s[0:1]
	v_fma_f32 v141, v143, s9, -v141
	v_ldexp_f32 v149, v149, v150
	v_fmac_f32_e32 v141, 0x3377d1cf, v143
	v_log_f32_e32 v149, v149
	v_fmac_f32_e32 v141, 0x3f317217, v143
	v_cmp_lt_f32_e64 s[2:3], |v143|, s15
	v_sub_f32_e32 v150, 1.0, v135
	v_cndmask_b32_e64 v135, v135, 0, s[4:5]
	v_cndmask_b32_e64 v141, v143, v141, s[2:3]
	v_cndmask_b32_e32 v143, 0, v131, vcc
	v_cmp_gt_f32_e32 vcc, s14, v150
	v_sub_f32_e32 v143, v141, v143
	v_mul_f32_e32 v141, 0x3f317217, v149
	v_cndmask_b32_e64 v151, 0, 32, vcc
	v_ldexp_f32 v150, v150, v151
	v_fma_f32 v141, v149, s9, -v141
	v_log_f32_e32 v150, v150
	v_fmac_f32_e32 v141, 0x3377d1cf, v149
	v_fmac_f32_e32 v141, 0x3f317217, v149
	v_cmp_lt_f32_e64 s[2:3], |v149|, s15
	v_cndmask_b32_e64 v140, v140, 0, s[4:5]
	v_bfe_u32 v151, v138, 16, 1
	v_cndmask_b32_e64 v141, v149, v141, s[2:3]
	v_cndmask_b32_e64 v149, 0, v131, s[0:1]
	v_sub_f32_e32 v149, v141, v149
	v_mul_f32_e32 v141, 0x3f317217, v150
	v_fma_f32 v141, v150, s9, -v141
	v_fmac_f32_e32 v141, 0x3377d1cf, v150
	v_fmac_f32_e32 v141, 0x3f317217, v150
	v_cmp_lt_f32_e64 s[0:1], |v150|, s15
	v_cndmask_b32_e32 v131, 0, v131, vcc
	v_bfe_u32 v154, v139, 16, 1
	v_cndmask_b32_e64 v141, v150, v141, s[0:1]
	v_sub_f32_e32 v131, v141, v131
	v_cndmask_b32_e64 v141, v142, 0, s[4:5]
	v_bfe_u32 v150, v134, 16, 1
	v_add3_u32 v154, v139, v154, s16
	v_add3_u32 v138, v138, v151, s16
	v_add3_u32 v134, v134, v150, s16
	v_cvt_pk_bf16_f32 v135, v140, v135
	v_bfe_u32 v139, v146, 16, 1
	v_bfe_u32 v142, v144, 16, 1
	v_bfe_u32 v150, v141, 16, 1
	v_add3_u32 v141, v141, v150, s16
	v_add3_u32 v142, v144, v142, s16
	v_add3_u32 v139, v146, v139, s16
	v_lshrrev_b32_e32 v144, 16, v139
	v_lshrrev_b32_e32 v139, 16, v142
	v_lshrrev_b32_e32 v142, 16, v141
	v_mov_b32_e32 v141, v135
	v_and_or_b32 v140, v134, s17, v142
	v_cndmask_b32_e64 v134, v147, 0, s[4:5]
	v_bfe_u32 v135, v134, 16, 1
	v_and_or_b32 v139, v138, s17, v139
	v_and_or_b32 v138, v154, s17, v144
	v_add3_u32 v134, v134, v135, s16
	v_cndmask_b32_e64 v135, v152, 0, s[4:5]
	global_store_dwordx4 v[136:137], v[138:141], off offset:256
	v_bfe_u32 v136, v135, 16, 1
	v_lshrrev_b32_e32 v134, 16, v134
	v_add3_u32 v135, v135, v136, s16
	v_and_or_b32 v134, v135, s17, v134
	v_cndmask_b32_e64 v135, v145, 0, s[4:5]
	v_bfe_u32 v136, v135, 16, 1
	v_add3_u32 v135, v135, v136, s16
	v_cndmask_b32_e64 v136, v153, 0, s[4:5]
	v_bfe_u32 v137, v136, 16, 1
	v_lshrrev_b32_e32 v135, 16, v135
	v_add3_u32 v136, v136, v137, s16
	v_and_or_b32 v135, v136, s17, v135
	v_cndmask_b32_e64 v136, v148, 0, s[4:5]
	v_bfe_u32 v137, v136, 16, 1
	v_add3_u32 v136, v136, v137, s16
	v_cndmask_b32_e64 v137, v143, 0, s[4:5]
	v_bfe_u32 v138, v137, 16, 1
	v_lshrrev_b32_e32 v136, 16, v136
	v_add3_u32 v137, v137, v138, s16
	v_and_or_b32 v136, v137, s17, v136
	v_cndmask_b32_e64 v137, v149, 0, s[4:5]
	v_cndmask_b32_e64 v131, v131, 0, s[4:5]
	v_cvt_pk_bf16_f32 v131, v137, v131
	v_mov_b32_e32 v137, v131
	global_store_dwordx4 v[132:133], v[134:137], off offset:256

.LBB0_1001:
	s_or_b64 exec, exec, s[4:5]
	s_waitcnt lgkmcnt(0)
	v_mov_b32_e32 v133, 0
	v_lshlrev_b32_e32 v132, 1, v1
	v_lshl_add_u64 v[134:135], s[10:11], 0, v[132:133]
	v_ashrrev_i32_e32 v131, 31, v130
	v_lshlrev_b32_e32 v132, 2, v1
	s_movk_i32 s6, 0x7fff
	v_lshlrev_b64 v[138:139], 10, v[130:131]
	v_cvt_pk_bf16_f32 v131, v126, v127
	s_mov_b32 s7, 0xffff0000
	v_mov_b32_e32 v140, v131
	v_cvt_pk_bf16_f32 v141, v128, v129
	v_cvt_pk_bf16_f32 v142, v122, v123
	v_lshl_add_u64 v[138:139], v[134:135], 0, v[138:139]
	v_cmp_ne_u64_e32 vcc, 0, v[136:137]
	v_lshl_add_u64 v[136:137], v[136:137], 0, v[132:133]
	v_cvt_pk_bf16_f32 v143, v124, v125
	global_store_dwordx4 v[138:139], v[140:143], off
	s_and_saveexec_b64 s[4:5], vcc
	s_cbranch_execz .LBB0_1003
	global_store_dwordx4 v[136:137], v[126:129], off
	global_store_dwordx4 v[136:137], v[122:125], off offset:16
.LBB0_1003:
	s_or_b64 exec, exec, s[4:5]
	v_cvt_pk_bf16_f32 v122, v118, v119
	v_cvt_pk_bf16_f32 v123, v120, v121
	v_cvt_pk_bf16_f32 v124, v114, v115
	v_cvt_pk_bf16_f32 v125, v116, v117
	global_store_dwordx4 v[138:139], v[122:125], off offset:256
	s_and_saveexec_b64 s[4:5], vcc
	s_cbranch_execz .LBB0_1005
	global_store_dwordx4 v[136:137], v[118:121], off offset:512
	global_store_dwordx4 v[136:137], v[114:117], off offset:528

.LBB0_1007:
	s_andn2_saveexec_b64 s[4:5], s[4:5]
	v_add_u32_e32 v116, 0xffffbf10, v130
	v_mov_b32_e32 v117, 0
	v_lshlrev_b64 v[116:117], 11, v[116:117]
	v_lshl_add_u64 v[118:119], s[0:1], 0, v[116:117]
	s_or_b64 exec, exec, s[4:5]
	v_ashrrev_i32_e32 v115, 31, v114
	v_lshlrev_b64 v[114:115], 10, v[114:115]
	v_mov_b32_e32 v133, 0
	s_movk_i32 s6, 0x7fff
	v_lshl_add_u64 v[116:117], v[134:135], 0, v[114:115]
	v_cmp_ne_u64_e32 vcc, 0, v[118:119]
	v_lshl_add_u64 v[114:115], v[118:119], 0, v[132:133]
	v_cvt_pk_bf16_f32 v118, v110, v111
	v_cvt_pk_bf16_f32 v119, v112, v113
	v_cvt_pk_bf16_f32 v120, v106, v107
	v_cvt_pk_bf16_f32 v121, v108, v109
	global_store_dwordx4 v[116:117], v[118:121], off
	s_and_saveexec_b64 s[4:5], vcc
	s_cbranch_execz .LBB0_1011
	global_store_dwordx4 v[114:115], v[110:113], off
	global_store_dwordx4 v[114:115], v[106:109], off offset:16
.LBB0_1011:
	s_or_b64 exec, exec, s[4:5]
	v_cvt_pk_bf16_f32 v106, v102, v103
	v_cvt_pk_bf16_f32 v107, v104, v105
	v_cvt_pk_bf16_f32 v108, v98, v99
	v_cvt_pk_bf16_f32 v109, v100, v101
	global_store_dwordx4 v[116:117], v[106:109], off offset:256
	s_and_saveexec_b64 s[4:5], vcc
	s_cbranch_execz .LBB0_1013
	global_store_dwordx4 v[114:115], v[102:105], off offset:512
	global_store_dwordx4 v[114:115], v[98:101], off offset:528

.LBB0_1015:
	s_andn2_saveexec_b64 s[4:5], s[4:5]
	v_add_u32_e32 v100, 0xffffbf20, v130
	v_mov_b32_e32 v101, 0
	v_lshlrev_b64 v[100:101], 11, v[100:101]
	v_lshl_add_u64 v[102:103], s[0:1], 0, v[100:101]
	s_or_b64 exec, exec, s[4:5]
	v_ashrrev_i32_e32 v99, 31, v98
	v_lshlrev_b64 v[98:99], 10, v[98:99]
	v_mov_b32_e32 v133, 0
	s_movk_i32 s6, 0x7fff
	v_lshl_add_u64 v[100:101], v[134:135], 0, v[98:99]
	v_cmp_ne_u64_e32 vcc, 0, v[102:103]
	v_lshl_add_u64 v[98:99], v[102:103], 0, v[132:133]
	v_cvt_pk_bf16_f32 v102, v94, v95
	v_cvt_pk_bf16_f32 v103, v96, v97
	v_cvt_pk_bf16_f32 v104, v90, v91
	v_cvt_pk_bf16_f32 v105, v92, v93
	global_store_dwordx4 v[100:101], v[102:105], off
	s_and_saveexec_b64 s[4:5], vcc
	s_cbranch_execz .LBB0_1019
	global_store_dwordx4 v[98:99], v[94:97], off
	global_store_dwordx4 v[98:99], v[90:93], off offset:16
.LBB0_1019:
	s_or_b64 exec, exec, s[4:5]
	v_cvt_pk_bf16_f32 v90, v86, v87
	v_cvt_pk_bf16_f32 v91, v88, v89
	v_cvt_pk_bf16_f32 v92, v82, v83
	v_cvt_pk_bf16_f32 v93, v84, v85
	global_store_dwordx4 v[100:101], v[90:93], off offset:256
	s_and_saveexec_b64 s[4:5], vcc
	s_cbranch_execz .LBB0_1021
	global_store_dwordx4 v[98:99], v[86:89], off offset:512
	global_store_dwordx4 v[98:99], v[82:85], off offset:528

.LBB0_1023:
	s_andn2_saveexec_b64 s[4:5], s[4:5]
	v_add_u32_e32 v84, 0xffffbf30, v130
	v_mov_b32_e32 v85, 0
	v_lshlrev_b64 v[84:85], 11, v[84:85]
	v_lshl_add_u64 v[86:87], s[0:1], 0, v[84:85]
	s_or_b64 exec, exec, s[4:5]
	v_ashrrev_i32_e32 v83, 31, v82
	v_lshlrev_b64 v[82:83], 10, v[82:83]
	v_mov_b32_e32 v133, 0
	s_movk_i32 s6, 0x7fff
	v_lshl_add_u64 v[84:85], v[134:135], 0, v[82:83]
	v_cmp_ne_u64_e32 vcc, 0, v[86:87]
	v_lshl_add_u64 v[82:83], v[86:87], 0, v[132:133]
	v_cvt_pk_bf16_f32 v86, v78, v79
	v_cvt_pk_bf16_f32 v87, v80, v81
	v_cvt_pk_bf16_f32 v88, v74, v75
	v_cvt_pk_bf16_f32 v89, v76, v77
	global_store_dwordx4 v[84:85], v[86:89], off
	s_and_saveexec_b64 s[4:5], vcc
	s_cbranch_execz .LBB0_1027
	global_store_dwordx4 v[82:83], v[78:81], off
	global_store_dwordx4 v[82:83], v[74:77], off offset:16
.LBB0_1027:
	s_or_b64 exec, exec, s[4:5]
	v_cvt_pk_bf16_f32 v74, v70, v71
	v_cvt_pk_bf16_f32 v75, v72, v73
	v_cvt_pk_bf16_f32 v76, v66, v67
	v_cvt_pk_bf16_f32 v77, v68, v69
	global_store_dwordx4 v[84:85], v[74:77], off offset:256
	s_and_saveexec_b64 s[4:5], vcc
	s_cbranch_execz .LBB0_1029
	global_store_dwordx4 v[82:83], v[70:73], off offset:512
	global_store_dwordx4 v[82:83], v[66:69], off offset:528

.LBB0_1031:
	s_andn2_saveexec_b64 s[4:5], s[4:5]
	v_add_u32_e32 v68, 0xffffbf80, v130
	v_mov_b32_e32 v69, 0
	v_lshlrev_b64 v[68:69], 11, v[68:69]
	v_lshl_add_u64 v[70:71], s[0:1], 0, v[68:69]
	s_or_b64 exec, exec, s[4:5]
	v_ashrrev_i32_e32 v67, 31, v66
	v_lshlrev_b64 v[66:67], 10, v[66:67]
	v_mov_b32_e32 v133, 0
	s_movk_i32 s6, 0x7fff
	v_lshl_add_u64 v[68:69], v[134:135], 0, v[66:67]
	v_cmp_ne_u64_e32 vcc, 0, v[70:71]
	v_lshl_add_u64 v[66:67], v[70:71], 0, v[132:133]
	v_cvt_pk_bf16_f32 v70, v62, v63
	v_cvt_pk_bf16_f32 v71, v64, v65
	v_cvt_pk_bf16_f32 v72, v58, v59
	v_cvt_pk_bf16_f32 v73, v60, v61
	global_store_dwordx4 v[68:69], v[70:73], off
	s_and_saveexec_b64 s[4:5], vcc
	s_cbranch_execz .LBB0_1035
	global_store_dwordx4 v[66:67], v[62:65], off
	global_store_dwordx4 v[66:67], v[58:61], off offset:16
.LBB0_1035:
	s_or_b64 exec, exec, s[4:5]
	v_cvt_pk_bf16_f32 v58, v54, v55
	v_cvt_pk_bf16_f32 v59, v56, v57
	v_cvt_pk_bf16_f32 v60, v50, v51
	v_cvt_pk_bf16_f32 v61, v52, v53
	global_store_dwordx4 v[68:69], v[58:61], off offset:256
	s_and_saveexec_b64 s[4:5], vcc
	s_cbranch_execz .LBB0_1037
	global_store_dwordx4 v[66:67], v[54:57], off offset:512
	global_store_dwordx4 v[66:67], v[50:53], off offset:528

.LBB0_1039:
	s_andn2_saveexec_b64 s[4:5], s[4:5]
	v_add_u32_e32 v52, 0xffffbf90, v130
	v_mov_b32_e32 v53, 0
	v_lshlrev_b64 v[52:53], 11, v[52:53]
	v_lshl_add_u64 v[54:55], s[0:1], 0, v[52:53]
	s_or_b64 exec, exec, s[4:5]
	v_ashrrev_i32_e32 v51, 31, v50
	v_lshlrev_b64 v[50:51], 10, v[50:51]
	v_mov_b32_e32 v133, 0
	s_movk_i32 s6, 0x7fff
	v_lshl_add_u64 v[52:53], v[134:135], 0, v[50:51]
	v_cmp_ne_u64_e32 vcc, 0, v[54:55]
	v_lshl_add_u64 v[50:51], v[54:55], 0, v[132:133]
	v_cvt_pk_bf16_f32 v54, v46, v47
	v_cvt_pk_bf16_f32 v55, v48, v49
	v_cvt_pk_bf16_f32 v56, v42, v43
	v_cvt_pk_bf16_f32 v57, v44, v45
	global_store_dwordx4 v[52:53], v[54:57], off
	s_and_saveexec_b64 s[4:5], vcc
	s_cbranch_execz .LBB0_1043
	global_store_dwordx4 v[50:51], v[46:49], off
	global_store_dwordx4 v[50:51], v[42:45], off offset:16
.LBB0_1043:
	s_or_b64 exec, exec, s[4:5]
	v_cvt_pk_bf16_f32 v42, v38, v39
	v_cvt_pk_bf16_f32 v43, v40, v41
	v_cvt_pk_bf16_f32 v44, v34, v35
	v_cvt_pk_bf16_f32 v45, v36, v37
	global_store_dwordx4 v[52:53], v[42:45], off offset:256
	s_and_saveexec_b64 s[4:5], vcc
	s_cbranch_execz .LBB0_1045
	global_store_dwordx4 v[50:51], v[38:41], off offset:512
	global_store_dwordx4 v[50:51], v[34:37], off offset:528

.LBB0_1047:
	s_andn2_saveexec_b64 s[4:5], s[4:5]
	v_add_u32_e32 v36, 0xffffbfa0, v130
	v_mov_b32_e32 v37, 0
	v_lshlrev_b64 v[36:37], 11, v[36:37]
	v_lshl_add_u64 v[38:39], s[0:1], 0, v[36:37]
	s_or_b64 exec, exec, s[4:5]
	v_ashrrev_i32_e32 v35, 31, v34
	v_lshlrev_b64 v[34:35], 10, v[34:35]
	v_mov_b32_e32 v133, 0
	s_movk_i32 s6, 0x7fff
	v_lshl_add_u64 v[36:37], v[134:135], 0, v[34:35]
	v_cmp_ne_u64_e32 vcc, 0, v[38:39]
	v_lshl_add_u64 v[34:35], v[38:39], 0, v[132:133]
	v_cvt_pk_bf16_f32 v38, v30, v31
	v_cvt_pk_bf16_f32 v39, v32, v33
	v_cvt_pk_bf16_f32 v40, v26, v27
	v_cvt_pk_bf16_f32 v41, v28, v29
	global_store_dwordx4 v[36:37], v[38:41], off
	s_and_saveexec_b64 s[4:5], vcc
	s_cbranch_execz .LBB0_1051
	global_store_dwordx4 v[34:35], v[30:33], off
	global_store_dwordx4 v[34:35], v[26:29], off offset:16
.LBB0_1051:
	s_or_b64 exec, exec, s[4:5]
	v_cvt_pk_bf16_f32 v26, v22, v23
	v_cvt_pk_bf16_f32 v27, v24, v25
	v_cvt_pk_bf16_f32 v28, v18, v19
	v_cvt_pk_bf16_f32 v29, v20, v21
	global_store_dwordx4 v[36:37], v[26:29], off offset:256
	s_and_saveexec_b64 s[4:5], vcc
	s_cbranch_execz .LBB0_1053
	global_store_dwordx4 v[34:35], v[22:25], off offset:512
	global_store_dwordx4 v[34:35], v[18:21], off offset:528

.LBB0_1055:
	s_andn2_saveexec_b64 s[2:3], s[4:5]
	v_add_u32_e32 v20, 0xffffbfb0, v130
	v_mov_b32_e32 v21, 0
	v_lshlrev_b64 v[20:21], 11, v[20:21]
	v_lshl_add_u64 v[22:23], s[0:1], 0, v[20:21]
	s_or_b64 exec, exec, s[2:3]
	v_ashrrev_i32_e32 v19, 31, v18
	v_lshlrev_b64 v[18:19], 10, v[18:19]
	v_mov_b32_e32 v133, 0
	s_movk_i32 s2, 0x7fff
	v_lshl_add_u64 v[20:21], v[134:135], 0, v[18:19]
	v_cmp_ne_u64_e32 vcc, 0, v[22:23]
	v_lshl_add_u64 v[18:19], v[22:23], 0, v[132:133]
	v_cvt_pk_bf16_f32 v22, v14, v15
	s_mov_b32 s3, 0xffff0000
	v_cvt_pk_bf16_f32 v23, v16, v17
	v_cvt_pk_bf16_f32 v24, v10, v11
	v_cvt_pk_bf16_f32 v25, v12, v13
	global_store_dwordx4 v[20:21], v[22:25], off
	s_and_saveexec_b64 s[0:1], vcc
	s_cbranch_execz .LBB0_1059
	global_store_dwordx4 v[18:19], v[14:17], off
	global_store_dwordx4 v[18:19], v[10:13], off offset:16
.LBB0_1059:
	s_or_b64 exec, exec, s[0:1]
	v_cvt_pk_bf16_f32 v10, v6, v7
	v_cvt_pk_bf16_f32 v11, v8, v9
	v_cvt_pk_bf16_f32 v12, v2, v3
	v_cvt_pk_bf16_f32 v13, v4, v5
	global_store_dwordx4 v[20:21], v[10:13], off offset:256
	s_and_saveexec_b64 s[0:1], vcc
	s_cbranch_execz .LBB0_1061
	global_store_dwordx4 v[18:19], v[6:9], off offset:512
	global_store_dwordx4 v[18:19], v[2:5], off offset:528

.LBB0_1066:
	s_or_b64 exec, exec, s[0:1]
	s_and_saveexec_b64 s[0:1], s[96:97]
	s_cbranch_execz .LBB0_1081
	v_mov_b32_e32 v1, 0xf000
	global_load_dword v1, v1, s[72:73] sc1
	s_add_u32 s4, s72, 0xf000
	s_addc_u32 s5, s73, 0
	s_waitcnt vmcnt(0)
	v_cmp_lt_u32_e32 vcc, 31, v1
	s_cbranch_vccnz .LBB0_1080
	s_add_u32 s2, s72, 0x4200
	s_addc_u32 s3, s73, 0
	s_mov_b32 s9, 1
	v_mov_b32_e32 v1, 0
	s_branch .LBB0_1070
	s_nop 0
	s_nop 0
	s_nop 0
	s_nop 0
	s_nop 0
	s_nop 0
	s_nop 0
	s_nop 0
	s_nop 0
	s_nop 0
	s_nop 0
	s_nop 0
	s_nop 0
	s_nop 0
	s_nop 0
	s_nop 0
	s_nop 0
	s_nop 0
	s_nop 0
	s_nop 0
	s_nop 0
	s_nop 0
	s_nop 0
	s_nop 0
	s_nop 0
	s_nop 0
	s_nop 0
	s_nop 0
	s_nop 0
	s_nop 0
	s_nop 0
	s_nop 0
	s_nop 0
	s_nop 0
	s_nop 0
	s_nop 0
	s_nop 0
	s_nop 0
	s_nop 0
	s_nop 0
	s_nop 0
	s_nop 0
	s_nop 0
	s_nop 0
	s_nop 0
	s_nop 0
	s_nop 0
	s_nop 0
	s_nop 0
	s_nop 0
	s_nop 0
	s_nop 0
	s_nop 0
	s_nop 0
	s_nop 0
	s_nop 0
	s_nop 0
	s_nop 0
	s_nop 0
	s_nop 0
	s_nop 0
	s_nop 0
	s_nop 0
	s_nop 0
	s_nop 0
	s_nop 0
	s_nop 0
	s_nop 0
	s_nop 0
	s_nop 0
	s_nop 0
	s_nop 0
	s_nop 0
	s_nop 0
	s_nop 0

.LBB0_1105:
	s_lshl_b32 s4, s12, 14
	s_add_i32 s4, s4, 0
	v_lshlrev_b32_e32 v140, 2, v139
	v_lshlrev_b32_e32 v141, 2, v138
	v_add3_u32 v241, s4, v140, v141
	s_add_i32 s4, 0, 0x10000
	v_add3_u32 v242, s4, v140, v141
	v_and_b32_e32 v140, 1, v135
	v_and_b32_e32 v135, 2, v135
	v_cmp_eq_u32_e64 s[6:7], 0, v135
	v_or_b32_e32 v135, v139, v138
	v_mov_b32_e32 v226, 0
	v_lshlrev_b32_e32 v138, 2, v135
	v_mov_b32_e32 v139, v226
	v_lshl_add_u64 v[138:139], s[72:73], 0, v[138:139]
	s_mov_b64 s[12:13], 0xde00000
	v_lshl_add_u64 v[228:229], v[138:139], 0, s[12:13]
	s_mov_b64 s[12:13], 0xdd00000
	v_lshl_add_u64 v[230:231], v[138:139], 0, s[12:13]
	s_add_u32 s12, s72, 0xf100
	s_addc_u32 s13, s73, 0
	v_lshl_add_u64 v[232:233], v[132:133], 1, s[14:15]
	s_add_u32 s14, s72, 0x4200
	s_addc_u32 s15, s73, 0
	v_lshl_add_u64 v[234:235], v[130:131], 2, s[16:17]
	s_add_u32 s16, s72, 0x4400
	s_addc_u32 s17, s73, 0
	s_add_u32 s18, s72, 0x4500
	s_addc_u32 s19, s73, 0
	s_add_u32 s20, s72, 0x4600
	s_addc_u32 s21, s73, 0
	s_add_u32 s22, s72, 0x4700
	s_addc_u32 s23, s73, 0
	s_add_u32 s24, s72, 0x4800
	s_addc_u32 s25, s73, 0
	s_add_u32 s26, s72, 0x4900
	s_addc_u32 s27, s73, 0
	s_add_u32 s28, s72, 0x4a00
	s_addc_u32 s29, s73, 0
	s_add_u32 s30, s72, 0x4b00
	s_addc_u32 s31, s73, 0
	s_add_u32 s34, s72, 0x4c00
	s_addc_u32 s35, s73, 0
	s_add_u32 s36, s72, 0x4d00
	s_addc_u32 s37, s73, 0
	s_add_u32 s40, s72, 0x4e00
	s_addc_u32 s41, s73, 0
	s_add_u32 s42, s72, 0x4f00
	s_addc_u32 s43, s73, 0
	s_add_u32 s44, s72, 0x5000
	s_addc_u32 s45, s73, 0
	s_add_u32 s46, s72, 0x5100
	s_addc_u32 s47, s73, 0
	s_add_u32 s48, s72, 0x5200
	s_addc_u32 s49, s73, 0
	s_add_u32 s52, s72, 0x5300
	s_addc_u32 s53, s73, 0
	s_add_u32 s66, s72, 0x7400
	v_lshlrev_b32_e32 v131, 2, v134
	s_addc_u32 s67, s73, 0
	v_lshl_or_b32 v130, v130, 10, v131
	v_mov_b32_e32 v131, v226
	s_add_u32 s70, s72, 0x7500
	v_lshl_add_u64 v[130:131], s[72:73], 0, v[130:131]
	s_mov_b64 s[38:39], 0xdf00000
	s_mov_b32 s50, 0
	s_mov_b32 s33, 4
	v_cmp_eq_u32_e64 s[4:5], 0, v140
	v_cmp_gt_u32_e64 s[8:9], 4, v137
	s_addc_u32 s71, s73, 0
	v_or_b32_e32 v243, 0x1000, v136
	v_lshl_add_u64 v[236:237], v[130:131], 0, s[38:39]
	v_mov_b32_e32 v248, 0xf149f2ca
	s_add_i32 s92, 0, 0x23fc0
	s_add_i32 s93, 0, 0x23fc4
	v_mov_b32_e32 v244, 0x2000
	v_mov_b32_e32 v245, 0x800
	s_branch .LBB0_1108
	s_nop 0
	s_nop 0
	s_nop 0
	s_nop 0
	s_nop 0
	s_nop 0
	s_nop 0
	s_nop 0
	s_nop 0
	s_nop 0
	s_nop 0
	s_nop 0
